# layer-0 mixer queue: context-attention items taken right after the dense items instead of forming the tail
# speedup vs baseline: 1.0090x; 1.0060x over previous
; #define LAS __attribute__((address_space(3)))
; DI int otid() { int t = threadIdx.x; asm volatile("" : "+v"(t)); return t; }
; DI float ret_lg2(const Params& p, int l, int dir, int h) { return log1pf(-exp2f(p.in[12][(l * 2 + dir) * 5 + h])) * 1.4426950408889634f; }
; DI void ret_out_item(const Params& p, int l, int b, int h, int c, LAS unsigned char* lds) {
;     const int tid = otid(), lane = tid & 63, wid = tid >> 6, r16 = lane & 15, q4 = lane >> 4;
;     unsigned char* ws = p.ws;
;     const bf16_t* P = (const bf16_t*)(ws + WS_P);
;     const float lgf = ret_lg2(p, l, 0, h), lgb = ret_lg2(p, l, 1, h);
;     const size_t rowb = (size_t)b * RB; const int tok0 = c * 128, tl = wid * 16 + r16;
;     const size_t row = rowb + tok0 + tl;
;     constexpr int RS = 272, MB = 128 * RS;
; DI void phase_mixers(const Params& p, int l, LAS unsigned char* lds) {
;     ...
;     const int nc = (l == 0) ? 18 : 16, n_ro = 20 * nc, n_na = 384, n_ctx = (l == 0) ? 44 : 0;
;     const int e0 = 160, e1 = e0 + n_ro, e2 = e1 + n_na, e3 = e2 + n_ctx;
;     int it = next_item(ctr, slot);
;     while (it < e0) { dense192_item(ws, lds, it / 40, (it >> 3) % 5, CL + (it & 7) * 256, RB); it = next_item(ctr, slot); }
;     while (it < e1) { const int i2 = it - e0, c = (i2 % nc) + (18 - nc), bh = i2 / nc; ret_out_item(p, l, bh / 5, bh % 5, c, lds); it = next_item(ctr, slot); }
.LBB0_1176:
	s_cmpk_gt_u32 s28, 0x233
	s_movk_i32 s2, 0x233
	s_cbranch_scc1 .LBB0_1183
	s_add_u32 s6, s50, 0x113a0000
	v_mbcnt_hi_u32_b32 v87, -1, v203
	s_addc_u32 s7, s51, 0
	v_and_b32_e32 v0, 64, v87
	v_mov_b32_e32 v69, 0
	s_mov_b32 s3, 0xc2fc0000
	v_mov_b32_e32 v82, 0x42800000
	s_mov_b32 s4, 0x3f2aaaab
	v_mov_b32_e32 v83, 0x3ecc95a3
	s_mov_b32 s5, 0x3f317218
	v_mov_b32_e32 v84, 0x7fc00000
	v_mov_b32_e32 v85, 0xff800000
	s_mov_b32 s20, 0x33800000
	s_movk_i32 s21, 0x3000
	s_movk_i32 s22, 0x1200
	s_mov_b64 s[8:9], 0x1f80
	s_add_i32 s23, 0, 0x11000
	s_add_i32 s27, 0, 0x19800
	s_movk_i32 s30, 0x110
	v_not_b32_e32 v86, 63
	v_mov_b64_e32 v[70:71], s[6:7]
	s_mov_b64 s[10:11], 0x1a80
	s_movk_i32 s31, 0x1000
	v_xor_b32_e32 v88, 16, v87
	v_add_u32_e32 v89, 64, v0
	v_xor_b32_e32 v90, 32, v87
	v_mov_b32_e32 v91, 0x3727c5ac
	s_mov_b32 s34, 0x800000
	s_mov_b64 s[12:13], 0x2980
	s_mov_b64 s[14:15], 0x1d9a0b00
	s_movk_i32 s35, 0x2000
	s_mov_b32 s36, 0x1d9a0000
	s_add_i32 s37, 0, 0x22040
	v_mov_b32_e32 v72, 0x3f317218
	s_branch .LBB0_1180

; #define LAS __attribute__((address_space(3)))
; DI int otid() { int t = threadIdx.x; asm volatile("" : "+v"(t)); return t; }
; DI float ret_lg2(const Params& p, int l, int dir, int h) { return log1pf(-exp2f(p.in[12][(l * 2 + dir) * 5 + h])) * 1.4426950408889634f; }
; DI void ret_out_item(const Params& p, int l, int b, int h, int c, LAS unsigned char* lds) {
;     const int tid = otid(), lane = tid & 63, wid = tid >> 6, r16 = lane & 15, q4 = lane >> 4;
;     unsigned char* ws = p.ws;
;     const bf16_t* P = (const bf16_t*)(ws + WS_P);
;     const float lgf = ret_lg2(p, l, 0, h), lgb = ret_lg2(p, l, 1, h);
;     const size_t rowb = (size_t)b * RB; const int tok0 = c * 128, tl = wid * 16 + r16;
;     const size_t row = rowb + tok0 + tl;
;     constexpr int RS = 272, MB = 128 * RS;
; DI void phase_mixers(const Params& p, int l, LAS unsigned char* lds) {
;     ...
;     const int nc = (l == 0) ? 18 : 16, n_ro = 20 * nc, n_na = 384, n_ctx = (l == 0) ? 44 : 0;
;     const int e0 = 160, e1 = e0 + n_ro, e2 = e1 + n_na, e3 = e2 + n_ctx;
;     int it = next_item(ctr, slot);
;     while (it < e0) { dense192_item(ws, lds, it / 40, (it >> 3) % 5, CL + (it & 7) * 256, RB); it = next_item(ctr, slot); }
;     while (it < e1) { const int i2 = it - e0, c = (i2 % nc) + (18 - nc), bh = i2 / nc; ret_out_item(p, l, bh / 5, bh % 5, c, lds); it = next_item(ctr, slot); }
.LBB0_1180:
	s_add_i32 s0, s28, 0xffffff34
	s_mul_hi_i32 s1, s0, 0x38e38e39
	s_lshr_b32 s16, s1, 31
	s_ashr_i32 s1, s1, 2
	s_add_i32 s1, s1, s16
	s_mul_i32 s16, s1, 18
	s_sub_i32 s19, s0, s16
	s_mul_hi_i32 s16, s0, 0xb60b60b7
	s_add_i32 s16, s16, s0
	s_lshr_b32 s0, s16, 31
	s_ashr_i32 s18, s16, 6
	s_add_i32 s18, s18, s0
	s_mul_hi_i32 s0, s1, 0x66666667
	s_lshr_b32 s16, s0, 31
	s_ashr_i32 s0, s0, 1
	s_add_i32 s0, s0, s16
	s_mul_i32 s0, s0, 5
	s_sub_i32 s16, s1, s0
	s_ashr_i32 s17, s16, 31
	s_lshl_b64 s[0:1], s[16:17], 2
	s_add_u32 s0, s60, s0
	v_mov_b32_e32 v16, v202
	s_addc_u32 s1, s61, s1
	global_load_dword v0, v69, s[0:1]
	global_load_dword v1, v69, s[0:1] offset:20
	v_bfe_u32 v92, v16, 4, 2
	s_waitcnt vmcnt(1)
	v_cmp_gt_f32_e32 vcc, s3, v0
	s_nop 1
	v_cndmask_b32_e32 v2, 0, v82, vcc
	s_waitcnt vmcnt(0)
	v_cmp_gt_f32_e64 s[0:1], s3, v1
	v_add_f32_e32 v0, v0, v2
	v_exp_f32_e32 v0, v0
	v_cndmask_b32_e64 v3, 0, v82, s[0:1]
	v_add_f32_e32 v1, v1, v3
	s_and_b64 s[28:29], vcc, exec
	v_exp_f32_e32 v1, v1
	s_cselect_b32 s17, 0xffffffc0, 0
	s_and_b64 s[0:1], s[0:1], exec
	v_ldexp_f32 v15, v0, s17
	s_cselect_b32 s0, 0xffffffc0, 0
	v_sub_f32_e32 v4, 1.0, v15
	v_ldexp_f32 v14, v1, s0
	v_frexp_mant_f32_e32 v7, v4
	v_cvt_f64_f32_e32 v[0:1], v4
	v_sub_f32_e32 v5, 1.0, v14
	v_add_f32_e32 v6, -1.0, v4
	v_frexp_exp_i32_f64_e32 v0, v[0:1]
	v_cmp_gt_f32_e32 vcc, s4, v7
	v_add_f32_e32 v8, -1.0, v5
	v_frexp_mant_f32_e32 v9, v5
	v_cvt_f64_f32_e32 v[2:3], v5
	v_sub_f32_e32 v10, v6, v4
	v_subbrev_co_u32_e32 v0, vcc, 0, v0, vcc
	v_sub_f32_e64 v6, -v15, v6
	v_sub_f32_e32 v1, v8, v5
	v_frexp_exp_i32_f64_e32 v2, v[2:3]
	v_add_f32_e32 v3, 1.0, v10
	v_cmp_gt_f32_e32 vcc, s4, v9
	v_sub_f32_e64 v8, -v14, v8
	v_add_f32_e32 v1, 1.0, v1
	v_subbrev_co_u32_e32 v17, vcc, 0, v2, vcc
	v_add_f32_e32 v2, v6, v3
	v_sub_u32_e32 v3, 0, v0
	v_add_f32_e32 v1, v8, v1
	v_sub_u32_e32 v6, 0, v17
	v_ldexp_f32 v4, v4, v3
	v_ldexp_f32 v20, v5, v6
	v_ldexp_f32 v21, v1, v6
	v_add_f32_e32 v1, -1.0, v4
	v_add_f32_e32 v5, 1.0, v4
	v_ldexp_f32 v2, v2, v3
	v_add_f32_e32 v3, 1.0, v1
	v_add_f32_e32 v6, -1.0, v5
	v_sub_f32_e32 v3, v4, v3
	v_sub_f32_e32 v4, v4, v6
	v_add_f32_e32 v6, v2, v3
	v_add_f32_e32 v2, v2, v4
	v_add_f32_e32 v8, v5, v2
	v_rcp_f32_e32 v9, v8
	v_add_f32_e32 v3, v1, v6
	v_sub_f32_e32 v4, v8, v5
	v_sub_f32_e32 v1, v3, v1
	v_mul_f32_e32 v11, v3, v9
	v_sub_f32_e32 v10, v2, v4
	v_mul_f32_e32 v4, v8, v11
	v_sub_f32_e32 v1, v6, v1
	v_fma_f32 v6, v11, v8, -v4
	v_fmac_f32_e32 v6, v11, v10
	v_add_f32_e32 v2, v4, v6
	v_sub_f32_e32 v5, v3, v2
	v_mov_b32_e32 v7, v2
	v_pk_add_f32 v[2:3], v[2:3], v[4:5] neg_lo:[0,1] neg_hi:[0,1]
	v_cvt_f32_i32_e32 v0, v0
	v_pk_add_f32 v[2:3], v[2:3], v[6:7] neg_lo:[0,1] neg_hi:[0,1]
	v_cmp_nlt_f32_e32 vcc, 1.0, v15
	v_add_f32_e32 v1, v1, v3
	v_add_f32_e32 v1, v2, v1
	v_add_f32_e32 v3, v5, v1
	v_mul_f32_e32 v2, v9, v3
	v_mul_f32_e32 v4, v8, v2
	v_sub_f32_e32 v5, v5, v3
	v_add_f32_e32 v12, v11, v2
	v_fma_f32 v6, v2, v8, -v4
	v_add_f32_e32 v1, v1, v5
	v_sub_f32_e32 v5, v12, v11
	v_fmac_f32_e32 v6, v2, v10
	v_sub_f32_e32 v8, v2, v5
	v_add_f32_e32 v2, v4, v6
	v_sub_f32_e32 v5, v3, v2
	v_mov_b32_e32 v7, v2
	v_pk_add_f32 v[2:3], v[2:3], v[4:5] neg_lo:[0,1] neg_hi:[0,1]
	v_cmp_lt_f32_e64 s[0:1], |v15|, s20
	v_pk_add_f32 v[2:3], v[2:3], v[6:7] neg_lo:[0,1] neg_hi:[0,1]
	s_lshl_b32 s28, s19, 7
	v_add_f32_e32 v1, v1, v3
	v_add_f32_e32 v1, v2, v1
	v_add_f32_e32 v1, v5, v1
	v_mul_f32_e32 v1, v9, v1
	v_add_f32_e32 v1, v8, v1
	v_add_f32_e32 v2, v12, v1
	v_mul_f32_e32 v4, v2, v2
	v_sub_f32_e32 v5, v2, v12
	v_fmamk_f32 v6, v4, 0x3e9b6dac, v83
	v_sub_f32_e32 v5, v1, v5
	v_mul_f32_e32 v1, v2, v4
	v_fmaak_f32 v73, v4, v6, 0x3f2aaada
	v_ldexp_f32 v7, v5, 1
	v_pk_mul_f32 v[4:5], v[0:1], v[72:73]
	v_ldexp_f32 v3, v2, 1
	v_fma_f32 v2, v0, s5, -v4
	v_fmac_f32_e32 v2, 0xb102e308, v0
	v_pk_add_f32 v[0:1], v[4:5], v[2:3]
	v_mov_b32_e32 v6, v4
	v_sub_f32_e32 v10, v1, v3
	v_pk_add_f32 v[8:9], v[0:1], v[4:5] neg_lo:[0,1] neg_hi:[0,1]
	v_sub_f32_e32 v5, v5, v10
	v_add_f32_e32 v7, v7, v5
	v_pk_add_f32 v[12:13], v[0:1], v[6:7]
	v_mov_b32_e32 v3, v0
	v_mov_b32_e32 v9, v13
	v_pk_add_f32 v[18:19], v[2:3], v[8:9] neg_lo:[0,1] neg_hi:[0,1]
	v_pk_add_f32 v[2:3], v[2:3], v[8:9]
	v_mov_b32_e32 v4, v1
	v_mov_b32_e32 v11, v0
	v_pk_add_f32 v[0:1], v[2:3], v[0:1] op_sel:[1,0] op_sel_hi:[0,1] neg_lo:[0,1] neg_hi:[0,1]
	v_mov_b32_e32 v10, v7
	v_mov_b32_e32 v6, v13
	v_mov_b32_e32 v7, v3
	v_mov_b32_e32 v5, v0
	v_pk_add_f32 v[8:9], v[12:13], v[0:1] op_sel_hi:[1,0] neg_lo:[0,1] neg_hi:[0,1]
	v_pk_add_f32 v[0:1], v[6:7], v[4:5] neg_lo:[0,1] neg_hi:[0,1]
	v_mov_b32_e32 v8, v18
	v_pk_add_f32 v[0:1], v[10:11], v[0:1] neg_lo:[0,1] neg_hi:[0,1]
	v_mov_b32_e32 v19, v3
	v_pk_add_f32 v[4:5], v[8:9], v[0:1]
	s_ashr_i32 s29, s28, 31
	v_pk_add_f32 v[6:7], v[4:5], v[4:5] op_sel:[0,1] op_sel_hi:[1,0]
	s_mul_i32 s17, s18, 5
	v_pk_add_f32 v[2:3], v[2:3], v[6:7] op_sel:[1,0] op_sel_hi:[0,1]
	v_mov_b32_e32 v5, v2
	v_mov_b32_e32 v1, v6
	v_pk_add_f32 v[6:7], v[4:5], v[18:19] neg_lo:[0,1] neg_hi:[0,1]
	s_nop 0
	v_sub_f32_e32 v3, v4, v6
	v_pk_add_f32 v[0:1], v[0:1], v[6:7] neg_lo:[0,1] neg_hi:[0,1]
	v_sub_f32_e32 v3, v18, v3
	v_add_f32_e32 v0, v0, v3
	v_add_f32_e32 v0, v0, v1
	v_add_f32_e32 v0, v2, v0
	v_cndmask_b32_e32 v0, v84, v0, vcc
	v_cmp_neq_f32_e32 vcc, 1.0, v15
	s_nop 1
	v_cndmask_b32_e32 v0, v85, v0, vcc
	v_cndmask_b32_e64 v15, v0, -v15, s[0:1]
	v_add_f32_e32 v0, -1.0, v20
	v_add_f32_e32 v1, 1.0, v0
	v_sub_f32_e32 v1, v20, v1
	v_add_f32_e32 v2, v21, v1
	v_add_f32_e32 v1, 1.0, v20
	v_add_f32_e32 v3, -1.0, v1
	v_sub_f32_e32 v3, v20, v3
	v_add_f32_e32 v3, v21, v3
	v_add_f32_e32 v8, v1, v3
	v_rcp_f32_e32 v10, v8
	v_sub_f32_e32 v1, v8, v1
; DI void ret_out_item(const Params& p, int l, int b, int h, int c, LAS unsigned char* lds) {
;     ...
;     constexpr int RS = 272, MB = 128 * RS;
;     {
;         const bf16_t* Sf = (const bf16_t*)(ws + WS_S) + ((size_t)((b * 5 + h) * 2 + 0) * 18 + c) * 16384;
;         const bf16_t* Sb = (const bf16_t*)(ws + WS_S) + ((size_t)((b * 5 + h) * 2 + 1) * 18 + c) * 16384;
;         const bf16_t* Kc = P + (rowb + tok0) * INP + C_RK + h * 128;
;         const bf16_t* Vc = (const bf16_t*)(ws + WS_VTR) + ((size_t)b * 640 + h * 128) * RB + tok0;
;         u32x4 t0[4], t1[4], t2[4], t3[4];
; #pragma unroll
;         for (int i = 0; i < 4; ++i) {
;             const int cid = tid + i * 512, rr = cid >> 4, cc = cid & 15;
;             t0[i] = *(const u32x4*)(Sf + rr * 128 + cc * 8); t1[i] = *(const u32x4*)(Sb + rr * 128 + cc * 8);
;             t2[i] = *(const u32x4*)(Kc + (size_t)rr * INP + cc * 8); t3[i] = *(const u32x4*)(Vc + (size_t)rr * RB + cc * 8);
;         }
	v_sub_f32_e32 v9, v3, v1
	v_add_f32_e32 v1, v0, v2
	v_sub_f32_e32 v0, v1, v0
	v_mul_f32_e32 v12, v1, v10
	v_sub_f32_e32 v11, v2, v0
	v_mul_f32_e32 v2, v8, v12
	v_fma_f32 v4, v12, v8, -v2
	v_fmac_f32_e32 v4, v12, v9
	v_add_f32_e32 v0, v2, v4
	v_sub_f32_e32 v3, v1, v0
	v_pk_add_f32 v[6:7], v[0:1], v[2:3] neg_lo:[0,1] neg_hi:[0,1]
	v_mov_b32_e32 v5, v0
	v_pk_add_f32 v[0:1], v[6:7], v[4:5] neg_lo:[0,1] neg_hi:[0,1]
	s_mul_i32 s0, s18, 0x900
	v_add_f32_e32 v1, v11, v1
	v_add_f32_e32 v0, v0, v1
	v_add_f32_e32 v1, v3, v0
	v_mul_f32_e32 v11, v10, v1
	v_mul_f32_e32 v2, v8, v11
	v_fma_f32 v4, v11, v8, -v2
	v_fmac_f32_e32 v4, v11, v9
	v_sub_f32_e32 v3, v3, v1
	v_add_f32_e32 v8, v0, v3
	v_add_f32_e32 v0, v2, v4
	v_sub_f32_e32 v3, v1, v0
	v_pk_add_f32 v[6:7], v[0:1], v[2:3] neg_lo:[0,1] neg_hi:[0,1]
	v_mov_b32_e32 v5, v0
	v_pk_add_f32 v[0:1], v[6:7], v[4:5] neg_lo:[0,1] neg_hi:[0,1]
	s_mul_hi_i32 s1, s18, 0x900
	v_add_f32_e32 v1, v8, v1
	v_add_f32_e32 v0, v0, v1
	v_add_f32_e32 v1, v12, v11
	s_add_u32 s0, s0, s28
	v_add_f32_e32 v0, v3, v0
	v_sub_f32_e32 v2, v1, v12
	s_addc_u32 s1, s1, s29
	s_add_i32 s17, s17, s16
	v_mul_f32_e32 v0, v10, v0
	v_sub_f32_e32 v2, v11, v2
	s_lshl_b32 s56, s17, 1
	s_mul_i32 s17, s17, 36
	s_ashr_i32 s57, s19, 31
	v_add_f32_e32 v2, v2, v0
	s_mul_hi_i32 s55, s56, 18
	s_add_u32 s54, s17, s19
	v_add_f32_e32 v4, v1, v2
	s_addc_u32 s55, s55, s57
	v_mul_f32_e32 v5, v4, v4
	s_lshl_b64 s[54:55], s[54:55], 15
	v_fmamk_f32 v0, v5, 0x3e9b6dac, v83
	s_add_u32 s54, s92, s54
	v_fmaak_f32 v73, v5, v0, 0x3f2aaada
	v_cvt_f32_i32_e32 v0, v17
	s_addc_u32 s55, s93, s55
	s_or_b32 s17, s56, 1
	v_sub_f32_e32 v1, v4, v1
	s_mul_hi_i32 s62, s17, 18
	s_mul_i32 s17, s17, 18
	v_sub_f32_e32 v1, v2, v1
	s_add_u32 s56, s17, s19
	v_ldexp_f32 v8, v1, 1
	v_mul_f32_e32 v1, v4, v5
	s_addc_u32 s57, s62, s57
	v_pk_mul_f32 v[6:7], v[0:1], v[72:73]
	s_lshl_b64 s[56:57], s[56:57], 15
	v_fma_f32 v2, v0, s5, -v6
	s_add_u32 s56, s92, s56
	s_mul_i32 s17, s1, 0x3000
	s_mul_hi_u32 s19, s0, 0x3000
	v_ldexp_f32 v3, v4, 1
	v_fmac_f32_e32 v2, 0xb102e308, v0
	s_addc_u32 s57, s93, s57
	s_add_i32 s19, s19, s17
	s_mul_i32 s17, s0, 0x3000
	v_pk_add_f32 v[4:5], v[6:7], v[2:3]
	s_add_u32 s68, s6, s17
	v_sub_f32_e32 v0, v5, v3
	s_addc_u32 s19, s7, s19
	s_lshl_b32 s62, s16, 7
	v_sub_f32_e32 v0, v7, v0
	s_ashr_i32 s63, s62, 31
	v_add_f32_e32 v9, v8, v0
	v_mov_b32_e32 v8, v6
	s_lshl_b64 s[16:17], s[62:63], 1
	v_pk_add_f32 v[0:1], v[4:5], v[6:7] neg_lo:[0,1] neg_hi:[0,1]
	v_pk_add_f32 v[66:67], v[4:5], v[8:9]
	s_add_u32 s68, s68, s16
	v_mov_b32_e32 v1, v67
	v_mov_b32_e32 v3, v4
	s_addc_u32 s69, s19, s17
	s_mul_hi_i32 s19, s18, 0x280
	s_mulk_i32 s18, 0x280
	v_pk_add_f32 v[10:11], v[2:3], v[0:1]
	s_add_u32 s18, s18, s62
	v_pk_add_f32 v[6:7], v[2:3], v[0:1] neg_lo:[0,1] neg_hi:[0,1]
	v_pk_add_f32 v[0:1], v[10:11], v[4:5] op_sel:[1,0] op_sel_hi:[0,1] neg_lo:[0,1] neg_hi:[0,1]
	s_addc_u32 s19, s19, s63
	v_pk_add_f32 v[12:13], v[66:67], v[0:1] op_sel_hi:[1,0] neg_lo:[0,1] neg_hi:[0,1]
	s_mulk_i32 s19, 0x1200
	s_mul_hi_u32 s62, s18, 0x1200
	v_lshlrev_b32_e32 v1, 4, v16
	s_add_i32 s62, s62, s19
	s_mulk_i32 s18, 0x1200
	v_and_b32_e32 v68, 0xf0, v1
	s_add_u32 s63, s87, s18
	v_lshl_add_u64 v[18:19], s[68:69], 0, v[68:69]
	v_ashrrev_i32_e32 v17, 4, v16
	s_addc_u32 s62, s91, s62
	s_lshl_b64 s[18:19], s[28:29], 1
	v_lshl_add_u64 v[76:77], v[18:19], 0, s[8:9]
	v_lshlrev_b32_e32 v18, 7, v17
	s_add_u32 s18, s63, s18
	v_ashrrev_i32_e32 v19, 31, v18
	v_add_u32_e32 v1, 0x200, v16
	s_addc_u32 s19, s62, s19
	v_lshl_add_u64 v[2:3], s[54:55], 0, v[68:69]
	v_lshl_add_u64 v[74:75], s[56:57], 0, v[68:69]
	v_lshlrev_b64 v[18:19], 1, v[18:19]
	v_ashrrev_i32_e32 v73, 4, v1
	v_lshl_add_u64 v[78:79], s[18:19], 0, v[68:69]
	v_lshl_add_u64 v[20:21], v[2:3], 0, v[18:19]
	v_lshl_add_u64 v[22:23], v[74:75], 0, v[18:19]
	v_lshlrev_b32_e32 v34, 7, v73
	global_load_dwordx4 v[18:21], v[20:21], off
	s_nop 0
	global_load_dwordx4 v[22:25], v[22:23], off
	v_mad_i64_i32 v[26:27], s[18:19], v17, s21, v[76:77]
	v_mad_i64_i32 v[30:31], s[18:19], v17, s22, v[78:79]
	v_ashrrev_i32_e32 v35, 31, v34
	v_add_u32_e32 v1, 0x400, v16
	global_load_dwordx4 v[26:29], v[26:27], off
	s_nop 0
	global_load_dwordx4 v[30:33], v[30:31], off
	v_lshlrev_b64 v[34:35], 1, v[34:35]
	v_ashrrev_i32_e32 v93, 4, v1
	v_lshl_add_u64 v[36:37], v[2:3], 0, v[34:35]
	v_lshl_add_u64 v[38:39], v[74:75], 0, v[34:35]
	v_lshlrev_b32_e32 v50, 7, v93
	global_load_dwordx4 v[34:37], v[36:37], off
	s_nop 0
	global_load_dwordx4 v[38:41], v[38:39], off
	v_mad_i64_i32 v[42:43], s[18:19], v73, s21, v[76:77]
	v_mad_i64_i32 v[46:47], s[18:19], v73, s22, v[78:79]
	v_ashrrev_i32_e32 v51, 31, v50
	v_add_u32_e32 v1, 0x600, v16
	global_load_dwordx4 v[42:45], v[42:43], off
	s_nop 0
	global_load_dwordx4 v[46:49], v[46:47], off
	v_lshlrev_b64 v[50:51], 1, v[50:51]
	v_ashrrev_i32_e32 v114, 4, v1
	v_lshl_add_u64 v[52:53], v[2:3], 0, v[50:51]
	v_lshl_add_u64 v[54:55], v[74:75], 0, v[50:51]
	v_lshlrev_b32_e32 v80, 7, v114
	global_load_dwordx4 v[50:53], v[52:53], off
	s_nop 0
	global_load_dwordx4 v[54:57], v[54:55], off
	v_mad_i64_i32 v[58:59], s[18:19], v93, s21, v[76:77]
	v_mad_i64_i32 v[62:63], s[18:19], v93, s22, v[78:79]
	v_ashrrev_i32_e32 v81, 31, v80
	global_load_dwordx4 v[58:61], v[58:59], off
	s_nop 0
	global_load_dwordx4 v[62:65], v[62:63], off
	v_lshlrev_b64 v[80:81], 1, v[80:81]
	v_lshl_add_u64 v[2:3], v[2:3], 0, v[80:81]
	v_lshl_add_u64 v[74:75], v[74:75], 0, v[80:81]
	global_load_dwordx4 v[94:97], v[2:3], off
	global_load_dwordx4 v[98:101], v[74:75], off
	v_mad_i64_i32 v[2:3], s[18:19], v114, s21, v[76:77]
	global_load_dwordx4 v[102:105], v[2:3], off
	v_mad_i64_i32 v[2:3], s[18:19], v114, s22, v[78:79]
; #define LAS __attribute__((address_space(3)))
; DI void ret_out_item(const Params& p, int l, int b, int h, int c, LAS unsigned char* lds) {
;     ...
; #pragma unroll
;         for (int i = 0; i < 4; ++i) {
;             const int cid = tid + i * 512, rr = cid >> 4, cc = cid & 15;
;             *(LAS u32x4*)(lds + 0 * MB + rr * RS + cc * 16) = t0[i]; *(LAS u32x4*)(lds + 1 * MB + rr * RS + cc * 16) = t1[i];
;             *(LAS u32x4*)(lds + 2 * MB + rr * RS + cc * 16) = t2[i]; *(LAS u32x4*)(lds + 3 * MB + rr * RS + cc * 16) = t3[i];
;         }
;     }
;     bf16x8 qf[4], qff[4], qfb[4];
;     const float qdf = exp2f(lgf * (float)(tl + 1)), qdb = exp2f(lgb * (float)(128 - tl));
; #pragma unroll
;     for (int ks = 0; ks < 4; ++ks) { qf[ks] = *(const bf16x8*)(P + row * INP + C_RQ + h * 128 + ks * 32 + q4 * 8); qff[ks] = scale1_bf16x8(qf[ks], qdf); qfb[ks] = scale1_bf16x8(qf[ks], qdb); }
	v_mov_b32_e32 v111, v0
	v_ashrrev_i32_e32 v0, 2, v16
	global_load_dwordx4 v[106:109], v[2:3], off
	v_bfi_b32 v78, -16, v0, v16
	v_ashrrev_i32_e32 v79, 31, v78
	v_lshl_add_u64 v[74:75], s[0:1], 0, v[78:79]
	v_mad_u64_u32 v[0:1], s[0:1], v74, s21, v[70:71]
	v_mad_i32_i24 v1, v75, s21, v1
	v_lshlrev_b32_e32 v80, 4, v92
	v_mov_b32_e32 v81, v69
	v_lshl_add_u64 v[76:77], v[0:1], 0, s[16:17]
	v_lshl_add_u64 v[112:113], v[76:77], 0, v[80:81]
	v_add_co_u32_e32 v0, vcc, s31, v112
	v_mov_b32_e32 v66, v67
	s_nop 0
	v_addc_co_u32_e32 v1, vcc, 0, v113, vcc
	global_load_dwordx4 v[120:123], v[0:1], off offset:2752
	global_load_dwordx4 v[124:127], v[0:1], off offset:2816
	global_load_dwordx4 v[128:131], v[0:1], off offset:2880
	global_load_dwordx4 v[0:3], v[0:1], off offset:2688
	v_mov_b32_e32 v67, v11
	v_mov_b32_e32 v110, v5
	v_pk_add_f32 v[66:67], v[66:67], v[110:111] neg_lo:[0,1] neg_hi:[0,1]
	v_mov_b32_e32 v8, v9
	v_mov_b32_e32 v9, v4
	v_pk_add_f32 v[4:5], v[8:9], v[66:67] neg_lo:[0,1] neg_hi:[0,1]
	v_mov_b32_e32 v12, v6
	v_pk_add_f32 v[8:9], v[12:13], v[4:5]
	v_mov_b32_e32 v7, v11
	v_pk_add_f32 v[12:13], v[8:9], v[8:9] op_sel:[0,1] op_sel_hi:[1,0]
	v_cmp_nlt_f32_e32 vcc, 1.0, v14
	v_pk_add_f32 v[10:11], v[10:11], v[12:13] op_sel:[1,0] op_sel_hi:[0,1]
	v_mov_b32_e32 v9, v10
	v_pk_add_f32 v[66:67], v[8:9], v[6:7] neg_lo:[0,1] neg_hi:[0,1]
	v_mov_b32_e32 v5, v12
	v_sub_f32_e32 v7, v8, v66
	v_pk_add_f32 v[4:5], v[4:5], v[66:67] neg_lo:[0,1] neg_hi:[0,1]
	v_sub_f32_e32 v6, v6, v7
	v_add_f32_e32 v4, v4, v6
	v_add_f32_e32 v4, v4, v5
	v_add_u32_e32 v5, 0, v68
	v_mul_lo_u32 v8, v17, s30
	v_add_u32_e32 v6, s23, v68
	v_add_u32_e32 v7, s27, v68
	v_add_u32_e32 v9, v5, v8
	s_waitcnt vmcnt(19)
	ds_write_b128 v9, v[18:21]
	s_waitcnt vmcnt(18)
	ds_write_b128 v9, v[22:25] offset:34816
	v_add_u32_e32 v9, v6, v8
	v_add_u32_e32 v8, v7, v8
	s_waitcnt vmcnt(16)
	ds_write_b128 v8, v[30:33]
	v_mul_lo_u32 v8, v73, s30
	ds_write_b128 v9, v[26:29]
	v_add_u32_e32 v9, v5, v8
	s_waitcnt vmcnt(15)
	ds_write_b128 v9, v[34:37]
	s_waitcnt vmcnt(14)
	ds_write_b128 v9, v[38:41] offset:34816
	v_add_u32_e32 v9, v6, v8
	v_add_u32_e32 v8, v7, v8
	v_add_f32_e32 v4, v10, v4
	v_cndmask_b32_e32 v4, v84, v4, vcc
	v_cmp_neq_f32_e32 vcc, 1.0, v14
	s_waitcnt vmcnt(13)
	ds_write_b128 v9, v[42:45]
	s_waitcnt vmcnt(12)
	ds_write_b128 v8, v[46:49]
	v_mul_lo_u32 v8, v93, s30
	v_add_u32_e32 v9, v5, v8
	s_waitcnt vmcnt(11)
	ds_write_b128 v9, v[50:53]
	s_waitcnt vmcnt(10)
	ds_write_b128 v9, v[54:57] offset:34816
	v_add_u32_e32 v9, v6, v8
	v_add_u32_e32 v8, v7, v8
	v_cndmask_b32_e32 v4, v85, v4, vcc
	v_cmp_lt_f32_e64 s[0:1], |v14|, s20
	s_waitcnt vmcnt(9)
	ds_write_b128 v9, v[58:61]
	s_waitcnt vmcnt(8)
	ds_write_b128 v8, v[62:65]
	v_mul_lo_u32 v8, v114, s30
	v_add_u32_e32 v5, v5, v8
	s_waitcnt vmcnt(7)
	ds_write_b128 v5, v[94:97]
	s_waitcnt vmcnt(6)
	ds_write_b128 v5, v[98:101] offset:34816
	v_add_u32_e32 v5, v6, v8
	v_add_u32_e32 v6, v7, v8
	s_waitcnt vmcnt(5)
	ds_write_b128 v5, v[102:105]
	v_add_u32_e32 v5, 1, v78
	v_cvt_f32_i32_e32 v5, v5
	v_sub_u32_e32 v7, 0x80, v78
	v_cvt_f32_i32_e32 v7, v7
	v_cndmask_b32_e64 v4, v4, -v14, s[0:1]
	v_mul_f32_e32 v79, 0x3fb8aa3b, v15
	s_waitcnt vmcnt(4)
	ds_write_b128 v6, v[106:109]
	v_mul_f32_e32 v6, v79, v5
	v_mul_f32_e32 v73, 0xbfb8aa3b, v4
	v_cmp_gt_f32_e32 vcc, s3, v6
	v_mul_f32_e64 v4, -v73, v7
	v_cmp_gt_f32_e64 s[0:1], s3, v4
	v_cndmask_b32_e32 v6, 0, v82, vcc
	v_fmac_f32_e32 v6, v79, v5
	v_cndmask_b32_e64 v4, 0, v82, s[0:1]
	v_exp_f32_e32 v5, v6
	v_fma_f32 v4, -v73, v7, v4
	v_exp_f32_e32 v4, v4
	v_cndmask_b32_e32 v6, 0, v86, vcc
	v_ldexp_f32 v17, v5, v6
	v_cndmask_b32_e64 v5, 0, v86, s[0:1]
	v_ldexp_f32 v19, v4, v5
	s_waitcnt vmcnt(0)
	v_lshlrev_b32_e32 v4, 16, v0
	v_mul_f32_e32 v5, v17, v4
	v_and_b32_e32 v6, 0xffff0000, v0
	v_mul_f32_e32 v7, v17, v6
	v_cvt_pk_bf16_f32 v48, v5, v7
	v_lshlrev_b32_e32 v5, 16, v1
	v_mul_f32_e32 v7, v17, v5
	v_and_b32_e32 v8, 0xffff0000, v1
	v_mul_f32_e32 v9, v17, v8
	v_cvt_pk_bf16_f32 v49, v7, v9
	v_lshlrev_b32_e32 v7, 16, v2
	v_mul_f32_e32 v9, v17, v7
	v_and_b32_e32 v10, 0xffff0000, v2
	v_mul_f32_e32 v11, v17, v10
	v_cvt_pk_bf16_f32 v50, v9, v11
	v_lshlrev_b32_e32 v9, 16, v3
	v_and_b32_e32 v14, 0xffff0000, v3
	v_mul_f32_e32 v4, v19, v4
	v_mul_f32_e32 v11, v17, v9
	v_mul_f32_e32 v15, v17, v14
	v_cvt_pk_bf16_f32 v51, v11, v15
	v_mul_f32_e32 v6, v19, v6
	v_cvt_pk_bf16_f32 v52, v4, v6
	v_mul_f32_e32 v4, v19, v5
	v_mul_f32_e32 v5, v19, v8
	v_cvt_pk_bf16_f32 v53, v4, v5
	v_mul_f32_e32 v4, v19, v7
	v_mul_f32_e32 v5, v19, v10
	v_lshl_add_u64 v[12:13], v[112:113], 0, s[10:11]
	v_cvt_pk_bf16_f32 v54, v4, v5
	v_mul_f32_e32 v4, v19, v9
	v_mul_f32_e32 v5, v19, v14
	v_cvt_pk_bf16_f32 v55, v4, v5
	s_waitcnt vmcnt(0)
	v_mov_b32_e32 v4, v120
	v_mov_b32_e32 v5, v121
	v_mov_b32_e32 v6, v122
	v_mov_b32_e32 v7, v123
	v_lshlrev_b32_e32 v8, 16, v4
	v_mul_f32_e32 v9, v17, v8
	v_and_b32_e32 v10, 0xffff0000, v4
	v_mul_f32_e32 v11, v17, v10
	v_cvt_pk_bf16_f32 v56, v9, v11
	v_lshlrev_b32_e32 v9, 16, v5
	v_mul_f32_e32 v11, v17, v9
	v_and_b32_e32 v14, 0xffff0000, v5
	v_mul_f32_e32 v15, v17, v14
	v_cvt_pk_bf16_f32 v57, v11, v15
	v_lshlrev_b32_e32 v11, 16, v6
	v_mul_f32_e32 v15, v17, v11
	v_and_b32_e32 v18, 0xffff0000, v6
	v_mul_f32_e32 v20, v17, v18
	v_cvt_pk_bf16_f32 v58, v15, v20
	v_lshlrev_b32_e32 v15, 16, v7
	v_and_b32_e32 v21, 0xffff0000, v7
	v_mul_f32_e32 v8, v19, v8
	v_mul_f32_e32 v20, v17, v15
	v_mul_f32_e32 v22, v17, v21
	v_cvt_pk_bf16_f32 v59, v20, v22
	v_mul_f32_e32 v10, v19, v10
	v_cvt_pk_bf16_f32 v60, v8, v10
	v_mul_f32_e32 v8, v19, v9
	v_mul_f32_e32 v9, v19, v14
	v_cvt_pk_bf16_f32 v61, v8, v9
	v_mul_f32_e32 v8, v19, v11
	v_mul_f32_e32 v9, v19, v18
	v_cvt_pk_bf16_f32 v62, v8, v9
	v_mul_f32_e32 v8, v19, v15
	v_mul_f32_e32 v9, v19, v21
	v_cvt_pk_bf16_f32 v63, v8, v9
	s_waitcnt vmcnt(0)
; #define LAS __attribute__((address_space(3)))
; #define MFMA16(a, b, c) __builtin_amdgcn_mfma_f32_16x16x32_bf16((a), (b), (c), 0, 0, 0)
; DI void ret_out_item(const Params& p, int l, int b, int h, int c, LAS unsigned char* lds) {
;     ...
;     for (int ks = 0; ks < 4; ++ks) { qf[ks] = *(const bf16x8*)(P + row * INP + C_RQ + h * 128 + ks * 32 + q4 * 8); qff[ks] = scale1_bf16x8(qf[ks], qdf); qfb[ks] = scale1_bf16x8(qf[ks], qdb); }
;     f32x4 oacc[8];
; #pragma unroll
;     for (int d = 0; d < 8; ++d) oacc[d] = (f32x4){0.f, 0.f, 0.f, 0.f};
;     __syncthreads();
;     const LAS unsigned char* sfp = lds + 0 * MB + r16 * RS + q4 * 16;
;     const LAS unsigned char* sbp = lds + 1 * MB + r16 * RS + q4 * 16;
;     const LAS unsigned char* kcp = lds + 2 * MB + r16 * RS + q4 * 16;
;     const LAS unsigned char* vtp = lds + 3 * MB + r16 * RS + q4 * 8;
; #pragma unroll
;     for (int d = 0; d < 8; ++d)
; #pragma unroll
;         for (int ks = 0; ks < 4; ++ks) {
;             oacc[d] = MFMA16(*(const LAS bf16x8*)(sfp + d * 16 * RS + ks * 64), qff[ks], oacc[d]);
;             oacc[d] = MFMA16(*(const LAS bf16x8*)(sbp + d * 16 * RS + ks * 64), qfb[ks], oacc[d]);
;         }
	v_mov_b32_e32 v8, v124
	v_mov_b32_e32 v9, v125
	v_mov_b32_e32 v10, v126
	v_mov_b32_e32 v11, v127
	v_lshlrev_b32_e32 v14, 16, v8
	v_mul_f32_e32 v15, v17, v14
	v_and_b32_e32 v18, 0xffff0000, v8
	v_mul_f32_e32 v20, v17, v18
	v_cvt_pk_bf16_f32 v64, v15, v20
	v_lshlrev_b32_e32 v15, 16, v9
	v_mul_f32_e32 v20, v17, v15
	v_and_b32_e32 v21, 0xffff0000, v9
	v_mul_f32_e32 v22, v17, v21
	v_cvt_pk_bf16_f32 v65, v20, v22
	v_lshlrev_b32_e32 v20, 16, v10
	v_mul_f32_e32 v22, v17, v20
	v_and_b32_e32 v23, 0xffff0000, v10
	v_mul_f32_e32 v24, v17, v23
	v_cvt_pk_bf16_f32 v66, v22, v24
	v_lshlrev_b32_e32 v22, 16, v11
	v_and_b32_e32 v25, 0xffff0000, v11
	v_mul_f32_e32 v14, v19, v14
	v_mul_f32_e32 v24, v17, v22
	v_mul_f32_e32 v26, v17, v25
	v_cvt_pk_bf16_f32 v67, v24, v26
	v_mul_f32_e32 v18, v19, v18
	v_cvt_pk_bf16_f32 v94, v14, v18
	v_mul_f32_e32 v14, v19, v15
	v_mul_f32_e32 v15, v19, v21
	v_cvt_pk_bf16_f32 v95, v14, v15
	v_mul_f32_e32 v14, v19, v20
	v_mul_f32_e32 v15, v19, v23
	v_cvt_pk_bf16_f32 v96, v14, v15
	v_mul_f32_e32 v14, v19, v22
	v_mul_f32_e32 v15, v19, v25
	v_cvt_pk_bf16_f32 v97, v14, v15
	s_waitcnt vmcnt(0)
	v_mov_b32_e32 v12, v128
	v_mov_b32_e32 v13, v129
	v_mov_b32_e32 v14, v130
	v_mov_b32_e32 v15, v131
	v_and_b32_e32 v20, 15, v16
	v_mul_u32_u24_e32 v81, 0x110, v20
	v_add3_u32 v68, 0, v81, v80
	s_waitcnt vmcnt(0)
	v_lshlrev_b32_e32 v16, 16, v12
	v_mul_f32_e32 v18, v17, v16
	v_and_b32_e32 v21, 0xffff0000, v12
	v_mul_f32_e32 v22, v17, v21
	v_cvt_pk_bf16_f32 v98, v18, v22
	v_lshlrev_b32_e32 v18, 16, v13
	v_mul_f32_e32 v22, v17, v18
	v_and_b32_e32 v23, 0xffff0000, v13
	v_mul_f32_e32 v24, v17, v23
	v_cvt_pk_bf16_f32 v99, v22, v24
	v_lshlrev_b32_e32 v22, 16, v14
	v_mul_f32_e32 v24, v17, v22
	v_and_b32_e32 v25, 0xffff0000, v14
	v_mul_f32_e32 v26, v17, v25
	v_cvt_pk_bf16_f32 v100, v24, v26
	v_lshlrev_b32_e32 v24, 16, v15
	v_and_b32_e32 v27, 0xffff0000, v15
	v_mul_f32_e32 v26, v17, v24
	v_mul_f32_e32 v17, v17, v27
	v_cvt_pk_bf16_f32 v101, v26, v17
	v_mul_f32_e32 v16, v19, v16
	v_mul_f32_e32 v17, v19, v21
	v_cvt_pk_bf16_f32 v16, v16, v17
	v_mul_f32_e32 v17, v19, v18
	v_mul_f32_e32 v18, v19, v23
	v_cvt_pk_bf16_f32 v17, v17, v18
	v_mul_f32_e32 v18, v19, v22
	v_mul_f32_e32 v21, v19, v25
	v_cvt_pk_bf16_f32 v18, v18, v21
	v_mul_f32_e32 v21, v19, v24
	v_mul_f32_e32 v19, v19, v27
	v_cvt_pk_bf16_f32 v19, v21, v19
	s_waitcnt lgkmcnt(0)
	s_barrier
	ds_read_b128 v[20:23], v68
	ds_read_b128 v[24:27], v68 offset:64
	s_waitcnt lgkmcnt(1)
	v_mfma_f32_16x16x32_bf16 v[20:23], v[20:23], v[48:51], 0
	ds_read_b128 v[28:31], v68 offset:34816
	ds_read_b128 v[32:35], v68 offset:34880
	s_waitcnt lgkmcnt(1)
	v_mfma_f32_16x16x32_bf16 v[20:23], v[28:31], v[52:55], v[20:23]
	v_mfma_f32_16x16x32_bf16 v[20:23], v[24:27], v[56:59], v[20:23]
	ds_read_b128 v[24:27], v68 offset:128
	ds_read_b128 v[28:31], v68 offset:192
	s_waitcnt lgkmcnt(2)
	v_mfma_f32_16x16x32_bf16 v[20:23], v[32:35], v[60:63], v[20:23]
	s_waitcnt lgkmcnt(1)
	v_mfma_f32_16x16x32_bf16 v[20:23], v[24:27], v[64:67], v[20:23]
	ds_read_b128 v[24:27], v68 offset:34944
	ds_read_b128 v[32:35], v68 offset:35008
	s_waitcnt lgkmcnt(1)
	v_mfma_f32_16x16x32_bf16 v[20:23], v[24:27], v[94:97], v[20:23]
	v_mfma_f32_16x16x32_bf16 v[20:23], v[28:31], v[98:101], v[20:23]
	ds_read_b128 v[24:27], v68 offset:4352
	ds_read_b128 v[28:31], v68 offset:4416
	s_waitcnt lgkmcnt(2)
	v_mfma_f32_16x16x32_bf16 v[20:23], v[32:35], v[16:19], v[20:23]
	ds_read_b128 v[32:35], v68 offset:39168
	ds_read_b128 v[36:39], v68 offset:39232
	s_waitcnt lgkmcnt(3)
	v_mfma_f32_16x16x32_bf16 v[24:27], v[24:27], v[48:51], 0
	s_waitcnt lgkmcnt(1)
	v_mfma_f32_16x16x32_bf16 v[24:27], v[32:35], v[52:55], v[24:27]
	v_mfma_f32_16x16x32_bf16 v[24:27], v[28:31], v[56:59], v[24:27]
	ds_read_b128 v[28:31], v68 offset:4480
	ds_read_b128 v[32:35], v68 offset:4544
	s_waitcnt lgkmcnt(2)
	v_mfma_f32_16x16x32_bf16 v[24:27], v[36:39], v[60:63], v[24:27]
	s_waitcnt lgkmcnt(1)
	v_mfma_f32_16x16x32_bf16 v[24:27], v[28:31], v[64:67], v[24:27]
	ds_read_b128 v[28:31], v68 offset:39296
	ds_read_b128 v[36:39], v68 offset:39360
	s_waitcnt lgkmcnt(1)
	v_mfma_f32_16x16x32_bf16 v[24:27], v[28:31], v[94:97], v[24:27]
	v_mfma_f32_16x16x32_bf16 v[24:27], v[32:35], v[98:101], v[24:27]
	ds_read_b128 v[28:31], v68 offset:8704
	ds_read_b128 v[32:35], v68 offset:8768
	s_waitcnt lgkmcnt(2)
	v_mfma_f32_16x16x32_bf16 v[24:27], v[36:39], v[16:19], v[24:27]
	ds_read_b128 v[36:39], v68 offset:43520
	ds_read_b128 v[40:43], v68 offset:43584
	s_waitcnt lgkmcnt(3)
	v_mfma_f32_16x16x32_bf16 v[28:31], v[28:31], v[48:51], 0
	s_waitcnt lgkmcnt(1)
	v_mfma_f32_16x16x32_bf16 v[28:31], v[36:39], v[52:55], v[28:31]
	v_mfma_f32_16x16x32_bf16 v[28:31], v[32:35], v[56:59], v[28:31]
	ds_read_b128 v[32:35], v68 offset:8832
	ds_read_b128 v[36:39], v68 offset:8896
	s_waitcnt lgkmcnt(2)
	v_mfma_f32_16x16x32_bf16 v[28:31], v[40:43], v[60:63], v[28:31]
	s_waitcnt lgkmcnt(1)
	v_mfma_f32_16x16x32_bf16 v[28:31], v[32:35], v[64:67], v[28:31]
	ds_read_b128 v[32:35], v68 offset:43648
	ds_read_b128 v[40:43], v68 offset:43712
	s_waitcnt lgkmcnt(1)
	v_mfma_f32_16x16x32_bf16 v[28:31], v[32:35], v[94:97], v[28:31]
	v_mfma_f32_16x16x32_bf16 v[28:31], v[36:39], v[98:101], v[28:31]
	ds_read_b128 v[32:35], v68 offset:13056
	ds_read_b128 v[36:39], v68 offset:13120
	s_waitcnt lgkmcnt(2)
	v_mfma_f32_16x16x32_bf16 v[28:31], v[40:43], v[16:19], v[28:31]
	ds_read_b128 v[40:43], v68 offset:47872
	ds_read_b128 v[44:47], v68 offset:47936
	s_waitcnt lgkmcnt(3)
	v_mfma_f32_16x16x32_bf16 v[32:35], v[32:35], v[48:51], 0
	s_waitcnt lgkmcnt(1)
	v_mfma_f32_16x16x32_bf16 v[32:35], v[40:43], v[52:55], v[32:35]
	v_mfma_f32_16x16x32_bf16 v[32:35], v[36:39], v[56:59], v[32:35]
	ds_read_b128 v[36:39], v68 offset:13184
	ds_read_b128 v[40:43], v68 offset:13248
	s_waitcnt lgkmcnt(2)
; #define LAS __attribute__((address_space(3)))
; #define MFMA16(a, b, c) __builtin_amdgcn_mfma_f32_16x16x32_bf16((a), (b), (c), 0, 0, 0)
; DI void ret_out_item(const Params& p, int l, int b, int h, int c, LAS unsigned char* lds) {
;     ...
; #pragma unroll
;     for (int d = 0; d < 8; ++d)
; #pragma unroll
;         for (int ks = 0; ks < 4; ++ks) {
;             oacc[d] = MFMA16(*(const LAS bf16x8*)(sfp + d * 16 * RS + ks * 64), qff[ks], oacc[d]);
;             oacc[d] = MFMA16(*(const LAS bf16x8*)(sbp + d * 16 * RS + ks * 64), qfb[ks], oacc[d]);
;         }
; #pragma unroll
;     for (int kc = 0; kc < 4; ++kc) {
;         f32x4 s[2];
; #pragma unroll
;         for (int hf = 0; hf < 2; ++hf) {
;             s[hf] = (f32x4){0.f, 0.f, 0.f, 0.f};
; #pragma unroll
;             for (int ks = 0; ks < 4; ++ks) s[hf] = MFMA16(*(const LAS bf16x8*)(kcp + (2 * kc + hf) * 16 * RS + ks * 64), qf[ks], s[hf]);
; #pragma unroll
;             for (int j = 0; j < 4; ++j) {
;                 const int m = (2 * kc + hf) * 16 + q4 * 4 + j, d = tl - m;
;                 const float w = (d >= 0 ? exp2f(lgf * (float)d) : 0.f) + (d <= 0 ? exp2f(-lgb * (float)d) : 0.f);
;                 s[hf][j] *= w;
	v_mfma_f32_16x16x32_bf16 v[32:35], v[44:47], v[60:63], v[32:35]
	s_waitcnt lgkmcnt(1)
	v_mfma_f32_16x16x32_bf16 v[32:35], v[36:39], v[64:67], v[32:35]
	ds_read_b128 v[36:39], v68 offset:48000
	ds_read_b128 v[44:47], v68 offset:48064
	s_waitcnt lgkmcnt(1)
	v_mfma_f32_16x16x32_bf16 v[32:35], v[36:39], v[94:97], v[32:35]
	v_mfma_f32_16x16x32_bf16 v[32:35], v[40:43], v[98:101], v[32:35]
	ds_read_b128 v[36:39], v68 offset:17408
	ds_read_b128 v[40:43], v68 offset:17472
	s_waitcnt lgkmcnt(2)
	v_mfma_f32_16x16x32_bf16 v[32:35], v[44:47], v[16:19], v[32:35]
	ds_read_b128 v[44:47], v68 offset:52224
	ds_read_b128 v[102:105], v68 offset:52288
	s_waitcnt lgkmcnt(3)
	v_mfma_f32_16x16x32_bf16 v[36:39], v[36:39], v[48:51], 0
	s_waitcnt lgkmcnt(1)
	v_mfma_f32_16x16x32_bf16 v[36:39], v[44:47], v[52:55], v[36:39]
	v_mfma_f32_16x16x32_bf16 v[36:39], v[40:43], v[56:59], v[36:39]
	ds_read_b128 v[40:43], v68 offset:17536
	ds_read_b128 v[44:47], v68 offset:17600
	s_waitcnt lgkmcnt(2)
	v_mfma_f32_16x16x32_bf16 v[36:39], v[102:105], v[60:63], v[36:39]
	s_waitcnt lgkmcnt(1)
	v_mfma_f32_16x16x32_bf16 v[36:39], v[40:43], v[64:67], v[36:39]
	ds_read_b128 v[40:43], v68 offset:52352
	ds_read_b128 v[102:105], v68 offset:52416
	s_waitcnt lgkmcnt(1)
	v_mfma_f32_16x16x32_bf16 v[36:39], v[40:43], v[94:97], v[36:39]
	v_mfma_f32_16x16x32_bf16 v[36:39], v[44:47], v[98:101], v[36:39]
	ds_read_b128 v[40:43], v68 offset:21760
	ds_read_b128 v[44:47], v68 offset:21824
	s_waitcnt lgkmcnt(2)
	v_mfma_f32_16x16x32_bf16 v[36:39], v[102:105], v[16:19], v[36:39]
	ds_read_b128 v[102:105], v68 offset:56576
	ds_read_b128 v[106:109], v68 offset:56640
	s_waitcnt lgkmcnt(3)
	v_mfma_f32_16x16x32_bf16 v[40:43], v[40:43], v[48:51], 0
	s_waitcnt lgkmcnt(1)
	v_mfma_f32_16x16x32_bf16 v[40:43], v[102:105], v[52:55], v[40:43]
	v_mfma_f32_16x16x32_bf16 v[40:43], v[44:47], v[56:59], v[40:43]
	ds_read_b128 v[44:47], v68 offset:21888
	ds_read_b128 v[102:105], v68 offset:21952
	s_waitcnt lgkmcnt(2)
	v_mfma_f32_16x16x32_bf16 v[40:43], v[106:109], v[60:63], v[40:43]
	s_waitcnt lgkmcnt(1)
	v_mfma_f32_16x16x32_bf16 v[40:43], v[44:47], v[64:67], v[40:43]
	ds_read_b128 v[44:47], v68 offset:56704
	ds_read_b128 v[106:109], v68 offset:56768
	s_waitcnt lgkmcnt(1)
	v_mfma_f32_16x16x32_bf16 v[40:43], v[44:47], v[94:97], v[40:43]
	v_mfma_f32_16x16x32_bf16 v[40:43], v[102:105], v[98:101], v[40:43]
	ds_read_b128 v[44:47], v68 offset:26112
	ds_read_b128 v[102:105], v68 offset:26176
	s_waitcnt lgkmcnt(2)
	v_mfma_f32_16x16x32_bf16 v[40:43], v[106:109], v[16:19], v[40:43]
	ds_read_b128 v[106:109], v68 offset:60928
	ds_read_b128 v[110:113], v68 offset:60992
	s_waitcnt lgkmcnt(3)
	v_mfma_f32_16x16x32_bf16 v[44:47], v[44:47], v[48:51], 0
	s_waitcnt lgkmcnt(1)
	v_mfma_f32_16x16x32_bf16 v[44:47], v[106:109], v[52:55], v[44:47]
	v_mfma_f32_16x16x32_bf16 v[44:47], v[102:105], v[56:59], v[44:47]
	ds_read_b128 v[102:105], v68 offset:26240
	ds_read_b128 v[106:109], v68 offset:26304
	s_waitcnt lgkmcnt(2)
	v_mfma_f32_16x16x32_bf16 v[44:47], v[110:113], v[60:63], v[44:47]
	s_waitcnt lgkmcnt(1)
	v_mfma_f32_16x16x32_bf16 v[44:47], v[102:105], v[64:67], v[44:47]
	ds_read_b128 v[102:105], v68 offset:61056
	ds_read_b128 v[110:113], v68 offset:61120
	s_waitcnt lgkmcnt(1)
	v_mfma_f32_16x16x32_bf16 v[44:47], v[102:105], v[94:97], v[44:47]
	v_mfma_f32_16x16x32_bf16 v[44:47], v[106:109], v[98:101], v[44:47]
	ds_read_b128 v[102:105], v68 offset:30464
	ds_read_b128 v[106:109], v68 offset:30528
	s_waitcnt lgkmcnt(2)
	v_mfma_f32_16x16x32_bf16 v[44:47], v[110:113], v[16:19], v[44:47]
	s_waitcnt lgkmcnt(1)
	v_mfma_f32_16x16x32_bf16 v[48:51], v[102:105], v[48:51], 0
	ds_read_b128 v[102:105], v68 offset:65280
	ds_read_b128 v[110:113], v68 offset:65344
	s_waitcnt lgkmcnt(1)
	v_mfma_f32_16x16x32_bf16 v[48:51], v[102:105], v[52:55], v[48:51]
	v_mfma_f32_16x16x32_bf16 v[48:51], v[106:109], v[56:59], v[48:51]
	ds_read_b128 v[52:55], v68 offset:30592
	ds_read_b128 v[56:59], v68 offset:30656
	s_waitcnt lgkmcnt(2)
	v_mfma_f32_16x16x32_bf16 v[48:51], v[110:113], v[60:63], v[48:51]
	v_add3_u32 v62, s23, v81, v80
	v_lshlrev_b32_e32 v61, 2, v92
	v_sub_u32_e32 v63, v78, v61
	s_waitcnt lgkmcnt(1)
	v_mfma_f32_16x16x32_bf16 v[48:51], v[52:55], v[64:67], v[48:51]
	ds_read_b128 v[64:67], v68 offset:65408
	ds_read_b128 v[52:55], v68 offset:65472
	v_cvt_f32_u32_e32 v80, v63
	s_waitcnt lgkmcnt(1)
	v_mfma_f32_16x16x32_bf16 v[48:51], v[64:67], v[94:97], v[48:51]
	ds_read_b128 v[64:67], v62
	ds_read_b128 v[94:97], v62 offset:128
	v_lshlrev_b32_e32 v68, 3, v92
	v_mfma_f32_16x16x32_bf16 v[56:59], v[56:59], v[98:101], v[48:51]
	v_add3_u32 v60, s27, v81, v68
	v_mul_f32_e32 v81, v79, v80
	v_cmp_gt_f32_e32 vcc, s3, v81
	s_nop 0
	ds_read_b128 v[48:51], v62 offset:64
	s_waitcnt lgkmcnt(2)
	v_mfma_f32_16x16x32_bf16 v[64:67], v[64:67], v[0:3], 0
	v_cndmask_b32_e32 v81, 0, v82, vcc
	v_fmac_f32_e32 v81, v79, v80
	v_exp_f32_e32 v80, v81
	s_waitcnt lgkmcnt(0)
	v_mfma_f32_16x16x32_bf16 v[48:51], v[48:51], v[4:7], v[64:67]
	s_nop 2
	ds_read_b128 v[64:67], v62 offset:192
	v_cvt_f32_i32_e32 v81, v63
	v_cmp_lt_i32_e64 s[0:1], -1, v63
	v_mfma_f32_16x16x32_bf16 v[48:51], v[94:97], v[8:11], v[48:51]
	ds_read_b128 v[96:99], v62 offset:4480
	s_waitcnt lgkmcnt(1)
; #define LAS __attribute__((address_space(3)))
; DI unsigned cvt_pk_bf16(float lo, float hi) { unsigned r; asm volatile("v_cvt_pk_bf16_f32 %0, %1, %2" : "=v"(r) : "v"(lo), "v"(hi)); return r; }
; #define MFMA16(a, b, c) __builtin_amdgcn_mfma_f32_16x16x32_bf16((a), (b), (c), 0, 0, 0)
; DI void ret_out_item(const Params& p, int l, int b, int h, int c, LAS unsigned char* lds) {
;     ...
;     for (int kc = 0; kc < 4; ++kc) {
;         f32x4 s[2];
; #pragma unroll
;         for (int hf = 0; hf < 2; ++hf) {
;             s[hf] = (f32x4){0.f, 0.f, 0.f, 0.f};
; #pragma unroll
;             for (int ks = 0; ks < 4; ++ks) s[hf] = MFMA16(*(const LAS bf16x8*)(kcp + (2 * kc + hf) * 16 * RS + ks * 64), qf[ks], s[hf]);
; #pragma unroll
;             for (int j = 0; j < 4; ++j) {
;                 const int m = (2 * kc + hf) * 16 + q4 * 4 + j, d = tl - m;
;                 const float w = (d >= 0 ? exp2f(lgf * (float)d) : 0.f) + (d <= 0 ? exp2f(-lgb * (float)d) : 0.f);
;                 s[hf][j] *= w;
;             }
;         }
;         u32x4 w4; w4.x = cvt_pk_bf16(s[0][0], s[0][1]); w4.y = cvt_pk_bf16(s[0][2], s[0][3]); w4.z = cvt_pk_bf16(s[1][0], s[1][1]); w4.w = cvt_pk_bf16(s[1][2], s[1][3]);
;         const bf16x8 pb = __builtin_bit_cast(bf16x8, w4);
; #pragma unroll
;         for (int d = 0; d < 8; ++d) {
;             const u32x2 lo = *(const LAS u32x2*)(vtp + d * 16 * RS + kc * 64), hi = *(const LAS u32x2*)(vtp + d * 16 * RS + kc * 64 + 32);
;             u32x4 a4; a4.x = lo.x; a4.y = lo.y; a4.z = hi.x; a4.w = hi.y;
;             oacc[d] = MFMA16(__builtin_bit_cast(bf16x8, a4), pb, oacc[d]);
;         }
	v_mfma_f32_16x16x32_bf16 v[48:51], v[64:67], v[12:15], v[48:51]
	v_mul_f32_e32 v65, v81, v73
	v_cndmask_b32_e32 v64, 0, v86, vcc
	v_cmp_gt_f32_e32 vcc, s3, v65
	v_ldexp_f32 v64, v80, v64
	v_cndmask_b32_e64 v64, 0, v64, s[0:1]
	v_cndmask_b32_e32 v65, 0, v82, vcc
	v_fmac_f32_e32 v65, v81, v73
	v_exp_f32_e32 v65, v65
	v_cndmask_b32_e32 v66, 0, v86, vcc
	v_cmp_gt_i32_e32 vcc, 1, v63
	v_mfma_f32_16x16x32_bf16 v[52:55], v[52:55], v[16:19], v[56:59]
	v_ldexp_f32 v65, v65, v66
	v_xad_u32 v66, v61, -1, v78
	v_cvt_f32_u32_e32 v67, v66
	v_cndmask_b32_e32 v63, 0, v65, vcc
	v_add_f32_e32 v63, v64, v63
	v_cvt_f32_i32_e32 v65, v66
	v_mul_f32_e32 v64, v79, v67
	v_cmp_gt_f32_e32 vcc, s3, v64
	v_mul_f32_e32 v63, v63, v48
	v_cmp_lt_i32_e64 s[0:1], -1, v66
	v_cndmask_b32_e32 v64, 0, v82, vcc
	v_fmac_f32_e32 v64, v79, v67
	v_exp_f32_e32 v64, v64
	v_cndmask_b32_e32 v48, 0, v86, vcc
	v_ldexp_f32 v48, v64, v48
	v_mul_f32_e32 v64, v65, v73
	v_cmp_gt_f32_e32 vcc, s3, v64
	v_cndmask_b32_e64 v48, 0, v48, s[0:1]
	s_nop 0
	v_cndmask_b32_e32 v64, 0, v82, vcc
	v_fmac_f32_e32 v64, v65, v73
	v_exp_f32_e32 v64, v64
	v_cndmask_b32_e32 v65, 0, v86, vcc
	v_cmp_gt_i32_e32 vcc, 1, v66
	v_ldexp_f32 v64, v64, v65
	v_or_b32_e32 v65, 2, v61
	v_sub_u32_e32 v65, v78, v65
	v_cvt_f32_u32_e32 v67, v65
	v_cvt_f32_i32_e32 v66, v65
	v_cndmask_b32_e32 v64, 0, v64, vcc
	v_add_f32_e32 v48, v48, v64
	v_mul_f32_e32 v64, v79, v67
	v_cmp_gt_f32_e32 vcc, s3, v64
	v_mul_f32_e32 v80, v48, v49
	v_mul_f32_e32 v49, v66, v73
	v_cndmask_b32_e32 v64, 0, v82, vcc
	v_cndmask_b32_e32 v48, 0, v86, vcc
	v_cmp_gt_f32_e32 vcc, s3, v49
	v_fmac_f32_e32 v64, v79, v67
	v_exp_f32_e32 v64, v64
	v_cndmask_b32_e32 v49, 0, v82, vcc
	v_fmac_f32_e32 v49, v66, v73
	v_exp_f32_e32 v49, v49
	v_ldexp_f32 v48, v64, v48
	v_cndmask_b32_e32 v64, 0, v86, vcc
	v_cmp_lt_i32_e64 s[0:1], -1, v65
	v_ldexp_f32 v49, v49, v64
	v_or_b32_e32 v64, 3, v61
	v_sub_u32_e32 v81, v78, v64
	v_cvt_f32_u32_e32 v64, v81
	v_cmp_gt_i32_e32 vcc, 1, v65
	v_cndmask_b32_e64 v48, 0, v48, s[0:1]
	v_cvt_f32_i32_e32 v92, v81
	v_cndmask_b32_e32 v49, 0, v49, vcc
	v_add_f32_e32 v48, v48, v49
	v_mul_f32_e32 v49, v79, v64
	v_cmp_gt_f32_e32 vcc, s3, v49
	v_mul_f32_e32 v100, v48, v50
	v_cmp_lt_i32_e64 s[0:1], -1, v81
	v_cndmask_b32_e32 v49, 0, v82, vcc
	v_fmac_f32_e32 v49, v79, v64
	v_exp_f32_e32 v49, v49
	v_cndmask_b32_e32 v48, 0, v86, vcc
	ds_read_b128 v[64:67], v62 offset:4352
	v_ldexp_f32 v48, v49, v48
	v_mul_f32_e32 v49, v92, v73
	v_cmp_gt_f32_e32 vcc, s3, v49
	v_cndmask_b32_e64 v48, 0, v48, s[0:1]
	s_nop 0
	v_cndmask_b32_e32 v49, 0, v82, vcc
	v_fmac_f32_e32 v49, v92, v73
	ds_read_b128 v[92:95], v62 offset:4416
	v_exp_f32_e32 v49, v49
	v_cndmask_b32_e32 v50, 0, v86, vcc
	s_waitcnt lgkmcnt(1)
	v_mfma_f32_16x16x32_bf16 v[64:67], v[64:67], v[0:3], 0
	v_cmp_gt_i32_e32 vcc, 1, v81
	v_ldexp_f32 v49, v49, v50
	s_nop 0
	v_cndmask_b32_e32 v49, 0, v49, vcc
	v_add_f32_e32 v48, v48, v49
	v_or_b32_e32 v49, 16, v61
	v_sub_u32_e32 v81, v78, v49
	s_waitcnt lgkmcnt(0)
	v_mfma_f32_16x16x32_bf16 v[64:67], v[92:95], v[4:7], v[64:67]
	v_cvt_f32_u32_e32 v101, v81
	ds_read_b128 v[92:95], v62 offset:4544
	v_mul_f32_e32 v102, v48, v51
	v_mfma_f32_16x16x32_bf16 v[48:51], v[96:99], v[8:11], v[64:67]
	v_cmp_lt_i32_e64 s[0:1], -1, v81
	s_nop 2
	v_mul_f32_e32 v64, v79, v101
	v_cmp_gt_f32_e32 vcc, s3, v64
	v_cvt_f32_i32_e32 v65, v81
	s_waitcnt lgkmcnt(0)
	v_mfma_f32_16x16x32_bf16 v[48:51], v[92:95], v[12:15], v[48:51]
	v_cndmask_b32_e32 v64, 0, v82, vcc
	v_fmac_f32_e32 v64, v79, v101
	v_exp_f32_e32 v64, v64
	v_cndmask_b32_e32 v66, 0, v86, vcc
	v_ldexp_f32 v64, v64, v66
	v_mul_f32_e32 v66, v65, v73
	v_cmp_gt_f32_e32 vcc, s3, v66
	v_cndmask_b32_e64 v64, 0, v64, s[0:1]
	s_nop 0
	v_cndmask_b32_e32 v66, 0, v82, vcc
	v_fmac_f32_e32 v66, v65, v73
	v_exp_f32_e32 v65, v66
	v_cndmask_b32_e32 v66, 0, v86, vcc
	v_cmp_gt_i32_e32 vcc, 1, v81
	v_ldexp_f32 v65, v65, v66
	v_or_b32_e32 v66, 17, v61
	v_sub_u32_e32 v66, v78, v66
	v_cvt_f32_u32_e32 v67, v66
	v_cndmask_b32_e32 v65, 0, v65, vcc
	v_add_f32_e32 v64, v64, v65
	v_mul_f32_e32 v64, v64, v48
	v_mul_f32_e32 v65, v79, v67
	v_cmp_gt_f32_e32 vcc, s3, v65
	v_cmp_lt_i32_e64 s[0:1], -1, v66
	s_nop 0
	v_cndmask_b32_e32 v65, 0, v82, vcc
	v_fmac_f32_e32 v65, v79, v67
	v_exp_f32_e32 v65, v65
	v_cvt_f32_i32_e32 v67, v66
	v_cndmask_b32_e32 v48, 0, v86, vcc
	v_ldexp_f32 v48, v65, v48
	v_mul_f32_e32 v65, v67, v73
	v_cmp_gt_f32_e32 vcc, s3, v65
	v_cndmask_b32_e64 v48, 0, v48, s[0:1]
	s_nop 0
	v_cndmask_b32_e32 v65, 0, v82, vcc
	v_fmac_f32_e32 v65, v67, v73
	v_exp_f32_e32 v65, v65
	v_cndmask_b32_e32 v67, 0, v86, vcc
	v_cmp_gt_i32_e32 vcc, 1, v66
	v_ldexp_f32 v65, v65, v67
	v_or_b32_e32 v67, 18, v61
	v_sub_u32_e32 v67, v78, v67
	v_cvt_f32_u32_e32 v81, v67
	v_cndmask_b32_e32 v65, 0, v65, vcc
	v_cvt_f32_i32_e32 v66, v67
	v_add_f32_e32 v48, v48, v65
	v_mul_f32_e32 v65, v79, v81
	v_cmp_gt_f32_e32 vcc, s3, v65
	v_cmp_lt_i32_e64 s[0:1], -1, v67
	s_nop 0
	v_cndmask_b32_e32 v65, 0, v82, vcc
	v_fmac_f32_e32 v65, v79, v81
	v_mul_f32_e32 v81, v48, v49
	v_mul_f32_e32 v49, v66, v73
	v_cndmask_b32_e32 v48, 0, v86, vcc
	v_cmp_gt_f32_e32 vcc, s3, v49
	v_exp_f32_e32 v65, v65
	s_nop 0
	v_cndmask_b32_e32 v49, 0, v82, vcc
	v_fmac_f32_e32 v49, v66, v73
	v_exp_f32_e32 v49, v49
	v_ldexp_f32 v48, v65, v48
	v_cndmask_b32_e32 v65, 0, v86, vcc
	v_cmp_gt_i32_e32 vcc, 1, v67
	v_ldexp_f32 v49, v49, v65
	v_or_b32_e32 v65, 19, v61
	v_sub_u32_e32 v65, v78, v65
	v_cvt_f32_u32_e32 v66, v65
	v_cndmask_b32_e64 v48, 0, v48, s[0:1]
	v_cndmask_b32_e32 v49, 0, v49, vcc
	v_add_f32_e32 v48, v48, v49
	v_mul_f32_e32 v49, v79, v66
	v_cmp_gt_f32_e32 vcc, s3, v49
	v_mul_f32_e32 v67, v48, v50
	v_cmp_lt_i32_e64 s[0:1], -1, v65
	v_cndmask_b32_e32 v49, 0, v82, vcc
	v_fmac_f32_e32 v49, v79, v66
	v_exp_f32_e32 v49, v49
	v_cvt_f32_i32_e32 v66, v65
	v_cndmask_b32_e32 v48, 0, v86, vcc
	v_ldexp_f32 v48, v49, v48
	v_mul_f32_e32 v49, v66, v73
	v_cmp_gt_f32_e32 vcc, s3, v49
	v_cndmask_b32_e64 v48, 0, v48, s[0:1]
	s_nop 0
	v_cndmask_b32_e32 v49, 0, v82, vcc
	v_fmac_f32_e32 v49, v66, v73
	v_exp_f32_e32 v49, v49
	v_cndmask_b32_e32 v50, 0, v86, vcc
	v_cmp_gt_i32_e32 vcc, 1, v65
	v_ldexp_f32 v49, v49, v50
	s_nop 0
	v_cndmask_b32_e32 v49, 0, v49, vcc
	v_add_f32_e32 v48, v48, v49
	v_mul_f32_e32 v51, v48, v51
	v_cvt_pk_bf16_f32 v48, v63, v80
	v_cvt_pk_bf16_f32 v49, v100, v102
	v_cvt_pk_bf16_f32 v50, v64, v81
	v_cvt_pk_bf16_f32 v51, v67, v51
	ds_read2_b64 v[64:67], v60 offset1:4
	v_add_u32_e32 v63, 0x1000, v60
	ds_read2_b64 v[16:19], v63 offset0:32 offset1:36
	s_waitcnt lgkmcnt(1)
; #define LAS __attribute__((address_space(3)))
; DI unsigned cvt_pk_bf16(float lo, float hi) { unsigned r; asm volatile("v_cvt_pk_bf16_f32 %0, %1, %2" : "=v"(r) : "v"(lo), "v"(hi)); return r; }
; #define MFMA16(a, b, c) __builtin_amdgcn_mfma_f32_16x16x32_bf16((a), (b), (c), 0, 0, 0)
; DI void ret_out_item(const Params& p, int l, int b, int h, int c, LAS unsigned char* lds) {
;     ...
;     for (int kc = 0; kc < 4; ++kc) {
;         f32x4 s[2];
; #pragma unroll
;         for (int hf = 0; hf < 2; ++hf) {
;             s[hf] = (f32x4){0.f, 0.f, 0.f, 0.f};
; #pragma unroll
;             for (int ks = 0; ks < 4; ++ks) s[hf] = MFMA16(*(const LAS bf16x8*)(kcp + (2 * kc + hf) * 16 * RS + ks * 64), qf[ks], s[hf]);
; #pragma unroll
;             for (int j = 0; j < 4; ++j) {
;                 const int m = (2 * kc + hf) * 16 + q4 * 4 + j, d = tl - m;
;                 const float w = (d >= 0 ? exp2f(lgf * (float)d) : 0.f) + (d <= 0 ? exp2f(-lgb * (float)d) : 0.f);
;                 s[hf][j] *= w;
;             }
;         }
;         u32x4 w4; w4.x = cvt_pk_bf16(s[0][0], s[0][1]); w4.y = cvt_pk_bf16(s[0][2], s[0][3]); w4.z = cvt_pk_bf16(s[1][0], s[1][1]); w4.w = cvt_pk_bf16(s[1][2], s[1][3]);
;         const bf16x8 pb = __builtin_bit_cast(bf16x8, w4);
; #pragma unroll
;         for (int d = 0; d < 8; ++d) {
;             const u32x2 lo = *(const LAS u32x2*)(vtp + d * 16 * RS + kc * 64), hi = *(const LAS u32x2*)(vtp + d * 16 * RS + kc * 64 + 32);
;             u32x4 a4; a4.x = lo.x; a4.y = lo.y; a4.z = hi.x; a4.w = hi.y;
;             oacc[d] = MFMA16(__builtin_bit_cast(bf16x8, a4), pb, oacc[d]);
;         }
	v_mfma_f32_16x16x32_bf16 v[20:23], v[64:67], v[48:51], v[20:23]
	v_add_u32_e32 v64, 0x2000, v60
	ds_read2_b64 v[56:59], v64 offset0:64 offset1:68
	v_add_u32_e32 v65, 0x3000, v60
	s_waitcnt lgkmcnt(1)
	v_mfma_f32_16x16x32_bf16 v[24:27], v[16:19], v[48:51], v[24:27]
	ds_read2_b64 v[16:19], v65 offset0:96 offset1:100
	v_add_u32_e32 v66, 0x4000, v60
	v_add_u32_e32 v67, 0x5000, v60
	s_waitcnt lgkmcnt(1)
	v_mfma_f32_16x16x32_bf16 v[28:31], v[56:59], v[48:51], v[28:31]
	ds_read2_b64 v[56:59], v66 offset0:128 offset1:132
	v_add_u32_e32 v80, 0x6000, v60
	ds_read_b128 v[92:95], v62 offset:8832
	s_waitcnt lgkmcnt(2)
	v_mfma_f32_16x16x32_bf16 v[32:35], v[16:19], v[48:51], v[32:35]
	ds_read2_b64 v[16:19], v67 offset0:160 offset1:164
	v_add_u32_e32 v81, 0x7000, v60
	s_waitcnt lgkmcnt(2)
	v_mfma_f32_16x16x32_bf16 v[36:39], v[56:59], v[48:51], v[36:39]
	ds_read2_b64 v[56:59], v80 offset0:192 offset1:196
	s_waitcnt lgkmcnt(1)
	v_mfma_f32_16x16x32_bf16 v[40:43], v[16:19], v[48:51], v[40:43]
	ds_read_b128 v[16:19], v62 offset:8704
	s_waitcnt lgkmcnt(1)
	v_mfma_f32_16x16x32_bf16 v[44:47], v[56:59], v[48:51], v[44:47]
	ds_read_b128 v[56:59], v62 offset:8768
	s_waitcnt lgkmcnt(1)
	v_mfma_f32_16x16x32_bf16 v[16:19], v[16:19], v[0:3], 0
	s_waitcnt lgkmcnt(0)
	v_mfma_f32_16x16x32_bf16 v[16:19], v[56:59], v[4:7], v[16:19]
	v_or_b32_e32 v56, 32, v61
	v_sub_u32_e32 v100, v78, v56
	v_cvt_f32_u32_e32 v101, v100
	v_mfma_f32_16x16x32_bf16 v[16:19], v[92:95], v[8:11], v[16:19]
	v_cvt_f32_i32_e32 v93, v100
	v_cmp_lt_i32_e64 s[0:1], -1, v100
	v_mul_f32_e32 v92, v79, v101
	v_cmp_gt_f32_e32 vcc, s3, v92
	ds_read_b128 v[96:99], v62 offset:8896
	ds_read2_b64 v[56:59], v81 offset0:224 offset1:228
	v_cndmask_b32_e32 v92, 0, v82, vcc
	v_fmac_f32_e32 v92, v79, v101
	v_exp_f32_e32 v92, v92
	v_cndmask_b32_e32 v94, 0, v86, vcc
	s_waitcnt lgkmcnt(1)
	v_mfma_f32_16x16x32_bf16 v[16:19], v[96:99], v[12:15], v[16:19]
	v_ldexp_f32 v92, v92, v94
	v_mul_f32_e32 v94, v93, v73
	v_cmp_gt_f32_e32 vcc, s3, v94
	v_cndmask_b32_e64 v92, 0, v92, s[0:1]
	s_waitcnt lgkmcnt(0)
	v_mfma_f32_16x16x32_bf16 v[48:51], v[56:59], v[48:51], v[52:55]
	v_cndmask_b32_e32 v94, 0, v82, vcc
	v_fmac_f32_e32 v94, v93, v73
	v_exp_f32_e32 v93, v94
	v_cndmask_b32_e32 v94, 0, v86, vcc
	v_cmp_gt_i32_e32 vcc, 1, v100
	ds_read_b128 v[100:103], v62 offset:13184
	v_ldexp_f32 v93, v93, v94
	v_or_b32_e32 v94, 33, v61
	v_sub_u32_e32 v94, v78, v94
	v_cvt_f32_u32_e32 v95, v94
	v_cndmask_b32_e32 v93, 0, v93, vcc
	v_add_f32_e32 v92, v92, v93
	v_mul_f32_e32 v104, v92, v16
	v_mul_f32_e32 v93, v79, v95
	v_cmp_gt_f32_e32 vcc, s3, v93
	v_cmp_lt_i32_e64 s[0:1], -1, v94
	s_nop 0
	v_cndmask_b32_e32 v93, 0, v82, vcc
	v_fmac_f32_e32 v93, v79, v95
	v_cvt_f32_i32_e32 v95, v94
	v_cndmask_b32_e32 v16, 0, v86, vcc
	v_exp_f32_e32 v93, v93
	v_mul_f32_e32 v92, v95, v73
	v_cmp_gt_f32_e32 vcc, s3, v92
	v_ldexp_f32 v16, v93, v16
	v_cndmask_b32_e64 v16, 0, v16, s[0:1]
	v_cndmask_b32_e32 v92, 0, v82, vcc
	v_fmac_f32_e32 v92, v95, v73
	v_exp_f32_e32 v92, v92
	v_cndmask_b32_e32 v93, 0, v86, vcc
	v_cmp_gt_i32_e32 vcc, 1, v94
	v_ldexp_f32 v92, v92, v93
	v_or_b32_e32 v93, 34, v61
	v_sub_u32_e32 v93, v78, v93
	v_cvt_f32_u32_e32 v95, v93
	v_cvt_f32_i32_e32 v94, v93
	v_cndmask_b32_e32 v92, 0, v92, vcc
	v_add_f32_e32 v16, v16, v92
	v_mul_f32_e32 v92, v79, v95
	v_cmp_gt_f32_e32 vcc, s3, v92
	v_mul_f32_e32 v105, v16, v17
	v_mul_f32_e32 v17, v94, v73
	v_cndmask_b32_e32 v92, 0, v82, vcc
	v_cndmask_b32_e32 v16, 0, v86, vcc
	v_cmp_gt_f32_e32 vcc, s3, v17
	v_fmac_f32_e32 v92, v79, v95
	v_exp_f32_e32 v92, v92
	v_cndmask_b32_e32 v17, 0, v82, vcc
	v_fmac_f32_e32 v17, v94, v73
	v_exp_f32_e32 v17, v17
	v_ldexp_f32 v16, v92, v16
	v_cndmask_b32_e32 v92, 0, v86, vcc
	v_cmp_lt_i32_e64 s[0:1], -1, v93
	v_ldexp_f32 v17, v17, v92
	v_or_b32_e32 v92, 35, v61
	v_sub_u32_e32 v106, v78, v92
	v_cvt_f32_u32_e32 v92, v106
	v_cmp_gt_i32_e32 vcc, 1, v93
	v_cndmask_b32_e64 v16, 0, v16, s[0:1]
	v_cvt_f32_i32_e32 v96, v106
	v_cndmask_b32_e32 v17, 0, v17, vcc
	v_add_f32_e32 v16, v16, v17
	v_mul_f32_e32 v17, v79, v92
	v_cmp_gt_f32_e32 vcc, s3, v17
	v_mul_f32_e32 v107, v16, v18
	v_cmp_lt_i32_e64 s[0:1], -1, v106
	v_cndmask_b32_e32 v17, 0, v82, vcc
	v_fmac_f32_e32 v17, v79, v92
	v_exp_f32_e32 v17, v17
	v_cndmask_b32_e32 v16, 0, v86, vcc
	ds_read_b128 v[92:95], v62 offset:13056
	v_ldexp_f32 v16, v17, v16
	v_mul_f32_e32 v17, v96, v73
	v_cmp_gt_f32_e32 vcc, s3, v17
	v_cndmask_b32_e64 v16, 0, v16, s[0:1]
	s_nop 0
	v_cndmask_b32_e32 v17, 0, v82, vcc
	v_fmac_f32_e32 v17, v96, v73
	ds_read_b128 v[96:99], v62 offset:13120
	v_exp_f32_e32 v17, v17
	v_cndmask_b32_e32 v18, 0, v86, vcc
	s_waitcnt lgkmcnt(1)
	v_mfma_f32_16x16x32_bf16 v[92:95], v[92:95], v[0:3], 0
	v_cmp_gt_i32_e32 vcc, 1, v106
	v_ldexp_f32 v17, v17, v18
	s_nop 0
	v_cndmask_b32_e32 v17, 0, v17, vcc
	v_add_f32_e32 v16, v16, v17
	v_or_b32_e32 v17, 48, v61
	v_sub_u32_e32 v106, v78, v17
	s_waitcnt lgkmcnt(0)
	v_mfma_f32_16x16x32_bf16 v[92:95], v[96:99], v[4:7], v[92:95]
	v_cvt_f32_u32_e32 v108, v106
	ds_read_b128 v[96:99], v62 offset:13248
	v_mul_f32_e32 v109, v16, v19
	v_mfma_f32_16x16x32_bf16 v[16:19], v[100:103], v[8:11], v[92:95]
	v_cmp_lt_i32_e64 s[0:1], -1, v106
	s_nop 2
	v_mul_f32_e32 v92, v79, v108
	v_cmp_gt_f32_e32 vcc, s3, v92
	v_cvt_f32_i32_e32 v93, v106
	s_waitcnt lgkmcnt(0)
; #define LAS __attribute__((address_space(3)))
; DI unsigned cvt_pk_bf16(float lo, float hi) { unsigned r; asm volatile("v_cvt_pk_bf16_f32 %0, %1, %2" : "=v"(r) : "v"(lo), "v"(hi)); return r; }
; #define MFMA16(a, b, c) __builtin_amdgcn_mfma_f32_16x16x32_bf16((a), (b), (c), 0, 0, 0)
; DI void ret_out_item(const Params& p, int l, int b, int h, int c, LAS unsigned char* lds) {
;     ...
;     for (int kc = 0; kc < 4; ++kc) {
;         f32x4 s[2];
; #pragma unroll
;         for (int hf = 0; hf < 2; ++hf) {
;             s[hf] = (f32x4){0.f, 0.f, 0.f, 0.f};
; #pragma unroll
;             for (int ks = 0; ks < 4; ++ks) s[hf] = MFMA16(*(const LAS bf16x8*)(kcp + (2 * kc + hf) * 16 * RS + ks * 64), qf[ks], s[hf]);
; #pragma unroll
;             for (int j = 0; j < 4; ++j) {
;                 const int m = (2 * kc + hf) * 16 + q4 * 4 + j, d = tl - m;
;                 const float w = (d >= 0 ? exp2f(lgf * (float)d) : 0.f) + (d <= 0 ? exp2f(-lgb * (float)d) : 0.f);
;                 s[hf][j] *= w;
;             }
;         }
;         u32x4 w4; w4.x = cvt_pk_bf16(s[0][0], s[0][1]); w4.y = cvt_pk_bf16(s[0][2], s[0][3]); w4.z = cvt_pk_bf16(s[1][0], s[1][1]); w4.w = cvt_pk_bf16(s[1][2], s[1][3]);
;         const bf16x8 pb = __builtin_bit_cast(bf16x8, w4);
; #pragma unroll
;         for (int d = 0; d < 8; ++d) {
;             const u32x2 lo = *(const LAS u32x2*)(vtp + d * 16 * RS + kc * 64), hi = *(const LAS u32x2*)(vtp + d * 16 * RS + kc * 64 + 32);
;             u32x4 a4; a4.x = lo.x; a4.y = lo.y; a4.z = hi.x; a4.w = hi.y;
;             oacc[d] = MFMA16(__builtin_bit_cast(bf16x8, a4), pb, oacc[d]);
;         }
	v_mfma_f32_16x16x32_bf16 v[16:19], v[96:99], v[12:15], v[16:19]
	v_cndmask_b32_e32 v92, 0, v82, vcc
	v_fmac_f32_e32 v92, v79, v108
	v_exp_f32_e32 v92, v92
	v_cndmask_b32_e32 v94, 0, v86, vcc
	v_ldexp_f32 v92, v92, v94
	v_mul_f32_e32 v94, v93, v73
	v_cmp_gt_f32_e32 vcc, s3, v94
	v_cndmask_b32_e64 v92, 0, v92, s[0:1]
	s_nop 0
	v_cndmask_b32_e32 v94, 0, v82, vcc
	v_fmac_f32_e32 v94, v93, v73
	v_exp_f32_e32 v93, v94
	v_cndmask_b32_e32 v94, 0, v86, vcc
	v_cmp_gt_i32_e32 vcc, 1, v106
	v_ldexp_f32 v93, v93, v94
	v_or_b32_e32 v94, 49, v61
	v_sub_u32_e32 v94, v78, v94
	v_cvt_f32_u32_e32 v95, v94
	v_cndmask_b32_e32 v93, 0, v93, vcc
	v_add_f32_e32 v92, v92, v93
	v_mul_f32_e32 v92, v92, v16
	v_mul_f32_e32 v93, v79, v95
	v_cmp_gt_f32_e32 vcc, s3, v93
	v_cmp_lt_i32_e64 s[0:1], -1, v94
	s_nop 0
	v_cndmask_b32_e32 v93, 0, v82, vcc
	v_fmac_f32_e32 v93, v79, v95
	v_exp_f32_e32 v93, v93
	v_cvt_f32_i32_e32 v95, v94
	v_cndmask_b32_e32 v16, 0, v86, vcc
	v_ldexp_f32 v16, v93, v16
	v_mul_f32_e32 v93, v95, v73
	v_cmp_gt_f32_e32 vcc, s3, v93
	v_cndmask_b32_e64 v16, 0, v16, s[0:1]
	s_nop 0
	v_cndmask_b32_e32 v93, 0, v82, vcc
	v_fmac_f32_e32 v93, v95, v73
	v_exp_f32_e32 v93, v93
	v_cndmask_b32_e32 v95, 0, v86, vcc
	v_cmp_gt_i32_e32 vcc, 1, v94
	v_ldexp_f32 v93, v93, v95
	v_or_b32_e32 v95, 50, v61
	v_sub_u32_e32 v95, v78, v95
	v_cvt_f32_u32_e32 v96, v95
	v_cndmask_b32_e32 v93, 0, v93, vcc
	v_cvt_f32_i32_e32 v94, v95
	v_add_f32_e32 v16, v16, v93
	v_mul_f32_e32 v93, v79, v96
	v_cmp_gt_f32_e32 vcc, s3, v93
	v_cmp_lt_i32_e64 s[0:1], -1, v95
	s_nop 0
	v_cndmask_b32_e32 v93, 0, v82, vcc
	v_fmac_f32_e32 v93, v79, v96
	v_mul_f32_e32 v96, v16, v17
	v_mul_f32_e32 v17, v94, v73
	v_cndmask_b32_e32 v16, 0, v86, vcc
	v_cmp_gt_f32_e32 vcc, s3, v17
	v_exp_f32_e32 v93, v93
	s_nop 0
	v_cndmask_b32_e32 v17, 0, v82, vcc
	v_fmac_f32_e32 v17, v94, v73
	v_exp_f32_e32 v17, v17
	v_ldexp_f32 v16, v93, v16
	v_cndmask_b32_e32 v93, 0, v86, vcc
	v_cmp_gt_i32_e32 vcc, 1, v95
	v_ldexp_f32 v17, v17, v93
	v_or_b32_e32 v93, 51, v61
	v_sub_u32_e32 v93, v78, v93
	v_cvt_f32_u32_e32 v94, v93
	v_cndmask_b32_e64 v16, 0, v16, s[0:1]
	v_cndmask_b32_e32 v17, 0, v17, vcc
	v_add_f32_e32 v16, v16, v17
	v_mul_f32_e32 v17, v79, v94
	v_cmp_gt_f32_e32 vcc, s3, v17
	v_mul_f32_e32 v95, v16, v18
	v_cmp_lt_i32_e64 s[0:1], -1, v93
	v_cndmask_b32_e32 v17, 0, v82, vcc
	v_fmac_f32_e32 v17, v79, v94
	v_exp_f32_e32 v17, v17
	v_cvt_f32_i32_e32 v94, v93
	v_cndmask_b32_e32 v16, 0, v86, vcc
	v_ldexp_f32 v16, v17, v16
	v_mul_f32_e32 v17, v94, v73
	v_cmp_gt_f32_e32 vcc, s3, v17
	v_cndmask_b32_e64 v16, 0, v16, s[0:1]
	s_nop 0
	v_cndmask_b32_e32 v17, 0, v82, vcc
	v_fmac_f32_e32 v17, v94, v73
	v_exp_f32_e32 v17, v17
	v_cndmask_b32_e32 v18, 0, v86, vcc
	v_cmp_gt_i32_e32 vcc, 1, v93
	v_ldexp_f32 v17, v17, v18
	s_nop 0
	v_cndmask_b32_e32 v17, 0, v17, vcc
	v_add_f32_e32 v16, v16, v17
	v_mul_f32_e32 v19, v16, v19
	v_cvt_pk_bf16_f32 v16, v104, v105
	v_cvt_pk_bf16_f32 v17, v107, v109
	v_cvt_pk_bf16_f32 v18, v92, v96
	v_cvt_pk_bf16_f32 v19, v95, v19
	ds_read2_b64 v[52:55], v63 offset0:40 offset1:44
	ds_read2_b64 v[56:59], v64 offset0:72 offset1:76
	s_waitcnt lgkmcnt(1)
	v_mfma_f32_16x16x32_bf16 v[24:27], v[52:55], v[16:19], v[24:27]
	ds_read2_b64 v[52:55], v65 offset0:104 offset1:108
	ds_read2_b64 v[92:95], v60 offset0:8 offset1:12
	s_waitcnt lgkmcnt(2)
	v_mfma_f32_16x16x32_bf16 v[28:31], v[56:59], v[16:19], v[28:31]
	ds_read2_b64 v[56:59], v66 offset0:136 offset1:140
	s_waitcnt lgkmcnt(2)
	v_mfma_f32_16x16x32_bf16 v[32:35], v[52:55], v[16:19], v[32:35]
	ds_read2_b64 v[52:55], v67 offset0:168 offset1:172
	s_waitcnt lgkmcnt(1)
	v_mfma_f32_16x16x32_bf16 v[36:39], v[56:59], v[16:19], v[36:39]
	ds_read2_b64 v[56:59], v80 offset0:200 offset1:204
	s_waitcnt lgkmcnt(1)
	v_mfma_f32_16x16x32_bf16 v[40:43], v[52:55], v[16:19], v[40:43]
	ds_read_b128 v[52:55], v62 offset:17408
	s_waitcnt lgkmcnt(1)
	v_mfma_f32_16x16x32_bf16 v[44:47], v[56:59], v[16:19], v[44:47]
	ds_read_b128 v[56:59], v62 offset:17472
	s_waitcnt lgkmcnt(1)
	v_mfma_f32_16x16x32_bf16 v[52:55], v[52:55], v[0:3], 0
	v_mfma_f32_16x16x32_bf16 v[20:23], v[92:95], v[16:19], v[20:23]
	ds_read_b128 v[92:95], v62 offset:17536
	s_waitcnt lgkmcnt(1)
	v_mfma_f32_16x16x32_bf16 v[56:59], v[56:59], v[4:7], v[52:55]
	s_nop 3
	v_or_b32_e32 v52, 64, v61
	v_sub_u32_e32 v100, v78, v52
	v_cvt_f32_u32_e32 v101, v100
	s_waitcnt lgkmcnt(0)
	v_mfma_f32_16x16x32_bf16 v[56:59], v[92:95], v[8:11], v[56:59]
	v_cvt_f32_i32_e32 v93, v100
	v_cmp_lt_i32_e64 s[0:1], -1, v100
	v_mul_f32_e32 v92, v79, v101
	v_cmp_gt_f32_e32 vcc, s3, v92
	ds_read_b128 v[96:99], v62 offset:17600
	ds_read2_b64 v[52:55], v81 offset0:232 offset1:236
	v_cndmask_b32_e32 v92, 0, v82, vcc
	v_fmac_f32_e32 v92, v79, v101
	v_exp_f32_e32 v92, v92
	v_cndmask_b32_e32 v94, 0, v86, vcc
	s_waitcnt lgkmcnt(1)
	v_mfma_f32_16x16x32_bf16 v[56:59], v[96:99], v[12:15], v[56:59]
	v_ldexp_f32 v92, v92, v94
	v_mul_f32_e32 v94, v93, v73
	v_cmp_gt_f32_e32 vcc, s3, v94
	v_cndmask_b32_e64 v92, 0, v92, s[0:1]
	s_waitcnt lgkmcnt(0)
; #define LAS __attribute__((address_space(3)))
; DI unsigned cvt_pk_bf16(float lo, float hi) { unsigned r; asm volatile("v_cvt_pk_bf16_f32 %0, %1, %2" : "=v"(r) : "v"(lo), "v"(hi)); return r; }
; #define MFMA16(a, b, c) __builtin_amdgcn_mfma_f32_16x16x32_bf16((a), (b), (c), 0, 0, 0)
; DI void ret_out_item(const Params& p, int l, int b, int h, int c, LAS unsigned char* lds) {
;     ...
;     for (int kc = 0; kc < 4; ++kc) {
;         f32x4 s[2];
; #pragma unroll
;         for (int hf = 0; hf < 2; ++hf) {
;             s[hf] = (f32x4){0.f, 0.f, 0.f, 0.f};
; #pragma unroll
;             for (int ks = 0; ks < 4; ++ks) s[hf] = MFMA16(*(const LAS bf16x8*)(kcp + (2 * kc + hf) * 16 * RS + ks * 64), qf[ks], s[hf]);
; #pragma unroll
;             for (int j = 0; j < 4; ++j) {
;                 const int m = (2 * kc + hf) * 16 + q4 * 4 + j, d = tl - m;
;                 const float w = (d >= 0 ? exp2f(lgf * (float)d) : 0.f) + (d <= 0 ? exp2f(-lgb * (float)d) : 0.f);
;                 s[hf][j] *= w;
;             }
;         }
;         u32x4 w4; w4.x = cvt_pk_bf16(s[0][0], s[0][1]); w4.y = cvt_pk_bf16(s[0][2], s[0][3]); w4.z = cvt_pk_bf16(s[1][0], s[1][1]); w4.w = cvt_pk_bf16(s[1][2], s[1][3]);
;         const bf16x8 pb = __builtin_bit_cast(bf16x8, w4);
; #pragma unroll
;         for (int d = 0; d < 8; ++d) {
;             const u32x2 lo = *(const LAS u32x2*)(vtp + d * 16 * RS + kc * 64), hi = *(const LAS u32x2*)(vtp + d * 16 * RS + kc * 64 + 32);
;             u32x4 a4; a4.x = lo.x; a4.y = lo.y; a4.z = hi.x; a4.w = hi.y;
;             oacc[d] = MFMA16(__builtin_bit_cast(bf16x8, a4), pb, oacc[d]);
;         }
	v_mfma_f32_16x16x32_bf16 v[48:51], v[52:55], v[16:19], v[48:51]
	v_cndmask_b32_e32 v94, 0, v82, vcc
	v_fmac_f32_e32 v94, v93, v73
	v_exp_f32_e32 v93, v94
	v_cndmask_b32_e32 v94, 0, v86, vcc
	v_cmp_gt_i32_e32 vcc, 1, v100
	ds_read_b128 v[100:103], v62 offset:21888
	v_ldexp_f32 v93, v93, v94
	v_or_b32_e32 v94, 0x41, v61
	v_sub_u32_e32 v94, v78, v94
	v_cvt_f32_u32_e32 v95, v94
	v_cndmask_b32_e32 v93, 0, v93, vcc
	v_add_f32_e32 v92, v92, v93
	v_mul_f32_e32 v104, v92, v56
	v_mul_f32_e32 v93, v79, v95
	v_cmp_gt_f32_e32 vcc, s3, v93
	v_cmp_lt_i32_e64 s[0:1], -1, v94
	s_nop 0
	v_cndmask_b32_e32 v93, 0, v82, vcc
	v_fmac_f32_e32 v93, v79, v95
	v_cvt_f32_i32_e32 v95, v94
	v_cndmask_b32_e32 v56, 0, v86, vcc
	v_exp_f32_e32 v93, v93
	v_mul_f32_e32 v92, v95, v73
	v_cmp_gt_f32_e32 vcc, s3, v92
	v_ldexp_f32 v56, v93, v56
	v_cndmask_b32_e64 v56, 0, v56, s[0:1]
	v_cndmask_b32_e32 v92, 0, v82, vcc
	v_fmac_f32_e32 v92, v95, v73
	v_exp_f32_e32 v92, v92
	v_cndmask_b32_e32 v93, 0, v86, vcc
	v_cmp_gt_i32_e32 vcc, 1, v94
	v_ldexp_f32 v92, v92, v93
	v_or_b32_e32 v93, 0x42, v61
	v_sub_u32_e32 v93, v78, v93
	v_cvt_f32_u32_e32 v95, v93
	v_cvt_f32_i32_e32 v94, v93
	v_cndmask_b32_e32 v92, 0, v92, vcc
	v_add_f32_e32 v56, v56, v92
	v_mul_f32_e32 v92, v79, v95
	v_cmp_gt_f32_e32 vcc, s3, v92
	v_mul_f32_e32 v105, v56, v57
	v_mul_f32_e32 v57, v94, v73
	v_cndmask_b32_e32 v92, 0, v82, vcc
	v_cndmask_b32_e32 v56, 0, v86, vcc
	v_cmp_gt_f32_e32 vcc, s3, v57
	v_fmac_f32_e32 v92, v79, v95
	v_exp_f32_e32 v92, v92
	v_cndmask_b32_e32 v57, 0, v82, vcc
	v_fmac_f32_e32 v57, v94, v73
	v_exp_f32_e32 v57, v57
	v_ldexp_f32 v56, v92, v56
	v_cndmask_b32_e32 v92, 0, v86, vcc
	v_cmp_lt_i32_e64 s[0:1], -1, v93
	v_ldexp_f32 v57, v57, v92
	v_or_b32_e32 v92, 0x43, v61
	v_sub_u32_e32 v106, v78, v92
	v_cvt_f32_u32_e32 v92, v106
	v_cmp_gt_i32_e32 vcc, 1, v93
	v_cndmask_b32_e64 v56, 0, v56, s[0:1]
	v_cvt_f32_i32_e32 v96, v106
	v_cndmask_b32_e32 v57, 0, v57, vcc
	v_add_f32_e32 v56, v56, v57
	v_mul_f32_e32 v57, v79, v92
	v_cmp_gt_f32_e32 vcc, s3, v57
	v_mul_f32_e32 v107, v56, v58
	v_cmp_lt_i32_e64 s[0:1], -1, v106
	v_cndmask_b32_e32 v57, 0, v82, vcc
	v_fmac_f32_e32 v57, v79, v92
	v_exp_f32_e32 v57, v57
	v_cndmask_b32_e32 v56, 0, v86, vcc
	ds_read_b128 v[92:95], v62 offset:21760
	v_ldexp_f32 v56, v57, v56
	v_mul_f32_e32 v57, v96, v73
	v_cmp_gt_f32_e32 vcc, s3, v57
	v_cndmask_b32_e64 v56, 0, v56, s[0:1]
	s_nop 0
	v_cndmask_b32_e32 v57, 0, v82, vcc
	v_fmac_f32_e32 v57, v96, v73
	ds_read_b128 v[96:99], v62 offset:21824
	v_exp_f32_e32 v57, v57
	v_cndmask_b32_e32 v58, 0, v86, vcc
	s_waitcnt lgkmcnt(1)
	v_mfma_f32_16x16x32_bf16 v[92:95], v[92:95], v[0:3], 0
	v_cmp_gt_i32_e32 vcc, 1, v106
	v_ldexp_f32 v57, v57, v58
	s_nop 0
	v_cndmask_b32_e32 v57, 0, v57, vcc
	v_add_f32_e32 v56, v56, v57
	v_or_b32_e32 v57, 0x50, v61
	v_sub_u32_e32 v106, v78, v57
	s_waitcnt lgkmcnt(0)
	v_mfma_f32_16x16x32_bf16 v[92:95], v[96:99], v[4:7], v[92:95]
	v_cvt_f32_u32_e32 v108, v106
	ds_read_b128 v[96:99], v62 offset:21952
	v_mul_f32_e32 v109, v56, v59
	v_mfma_f32_16x16x32_bf16 v[56:59], v[100:103], v[8:11], v[92:95]
	v_cmp_lt_i32_e64 s[0:1], -1, v106
	s_nop 2
	v_mul_f32_e32 v92, v79, v108
	v_cmp_gt_f32_e32 vcc, s3, v92
	v_cvt_f32_i32_e32 v93, v106
	s_waitcnt lgkmcnt(0)
	v_mfma_f32_16x16x32_bf16 v[56:59], v[96:99], v[12:15], v[56:59]
	v_cndmask_b32_e32 v92, 0, v82, vcc
	v_fmac_f32_e32 v92, v79, v108
	v_exp_f32_e32 v92, v92
	v_cndmask_b32_e32 v94, 0, v86, vcc
	v_ldexp_f32 v92, v92, v94
	v_mul_f32_e32 v94, v93, v73
	v_cmp_gt_f32_e32 vcc, s3, v94
	v_cndmask_b32_e64 v92, 0, v92, s[0:1]
	s_nop 0
	v_cndmask_b32_e32 v94, 0, v82, vcc
	v_fmac_f32_e32 v94, v93, v73
	v_exp_f32_e32 v93, v94
	v_cndmask_b32_e32 v94, 0, v86, vcc
	v_cmp_gt_i32_e32 vcc, 1, v106
	v_ldexp_f32 v93, v93, v94
	v_or_b32_e32 v94, 0x51, v61
	v_sub_u32_e32 v94, v78, v94
	v_cvt_f32_u32_e32 v95, v94
	v_cndmask_b32_e32 v93, 0, v93, vcc
	v_add_f32_e32 v92, v92, v93
	v_mul_f32_e32 v92, v92, v56
	v_mul_f32_e32 v93, v79, v95
	v_cmp_gt_f32_e32 vcc, s3, v93
	v_cmp_lt_i32_e64 s[0:1], -1, v94
	s_nop 0
	v_cndmask_b32_e32 v93, 0, v82, vcc
	v_fmac_f32_e32 v93, v79, v95
	v_exp_f32_e32 v93, v93
	v_cvt_f32_i32_e32 v95, v94
	v_cndmask_b32_e32 v56, 0, v86, vcc
	v_ldexp_f32 v56, v93, v56
	v_mul_f32_e32 v93, v95, v73
	v_cmp_gt_f32_e32 vcc, s3, v93
	v_cndmask_b32_e64 v56, 0, v56, s[0:1]
	s_nop 0
	v_cndmask_b32_e32 v93, 0, v82, vcc
	v_fmac_f32_e32 v93, v95, v73
	v_exp_f32_e32 v93, v93
	v_cndmask_b32_e32 v95, 0, v86, vcc
	v_cmp_gt_i32_e32 vcc, 1, v94
	v_ldexp_f32 v93, v93, v95
	v_or_b32_e32 v95, 0x52, v61
	v_sub_u32_e32 v95, v78, v95
	v_cvt_f32_u32_e32 v96, v95
	v_cndmask_b32_e32 v93, 0, v93, vcc
	v_cvt_f32_i32_e32 v94, v95
	v_add_f32_e32 v56, v56, v93
	v_mul_f32_e32 v93, v79, v96
	v_cmp_gt_f32_e32 vcc, s3, v93
	v_cmp_lt_i32_e64 s[0:1], -1, v95
	s_nop 0
	v_cndmask_b32_e32 v93, 0, v82, vcc
	v_fmac_f32_e32 v93, v79, v96
	v_mul_f32_e32 v96, v56, v57
	v_mul_f32_e32 v57, v94, v73
	v_cndmask_b32_e32 v56, 0, v86, vcc
	v_cmp_gt_f32_e32 vcc, s3, v57
	v_exp_f32_e32 v93, v93
	s_nop 0
	v_cndmask_b32_e32 v57, 0, v82, vcc
	v_fmac_f32_e32 v57, v94, v73
	v_exp_f32_e32 v57, v57
	v_ldexp_f32 v56, v93, v56
	v_cndmask_b32_e32 v93, 0, v86, vcc
	v_cmp_gt_i32_e32 vcc, 1, v95
	v_ldexp_f32 v57, v57, v93
	v_or_b32_e32 v93, 0x53, v61
	v_sub_u32_e32 v93, v78, v93
	v_cvt_f32_u32_e32 v94, v93
	v_cndmask_b32_e64 v56, 0, v56, s[0:1]
	v_cndmask_b32_e32 v57, 0, v57, vcc
	v_add_f32_e32 v56, v56, v57
	v_mul_f32_e32 v57, v79, v94
	v_cmp_gt_f32_e32 vcc, s3, v57
	v_mul_f32_e32 v95, v56, v58
	v_cmp_lt_i32_e64 s[0:1], -1, v93
	v_cndmask_b32_e32 v57, 0, v82, vcc
	v_fmac_f32_e32 v57, v79, v94
	v_exp_f32_e32 v57, v57
	v_cvt_f32_i32_e32 v94, v93
	v_cndmask_b32_e32 v56, 0, v86, vcc
	v_ldexp_f32 v56, v57, v56
	v_mul_f32_e32 v57, v94, v73
	v_cmp_gt_f32_e32 vcc, s3, v57
	v_cndmask_b32_e64 v56, 0, v56, s[0:1]
	s_nop 0
	v_cndmask_b32_e32 v57, 0, v82, vcc
	v_fmac_f32_e32 v57, v94, v73
	v_exp_f32_e32 v57, v57
	v_cndmask_b32_e32 v58, 0, v86, vcc
	v_cmp_gt_i32_e32 vcc, 1, v93
	v_ldexp_f32 v57, v57, v58
	s_nop 0
	v_cndmask_b32_e32 v57, 0, v57, vcc
	v_add_f32_e32 v56, v56, v57
	v_mul_f32_e32 v59, v56, v59
	v_cvt_pk_bf16_f32 v56, v104, v105
	v_cvt_pk_bf16_f32 v57, v107, v109
	v_cvt_pk_bf16_f32 v58, v92, v96
	v_cvt_pk_bf16_f32 v59, v95, v59
	ds_read2_b64 v[92:95], v60 offset0:16 offset1:20
	ds_read2_b64 v[52:55], v63 offset0:48 offset1:52
	s_waitcnt lgkmcnt(1)
; #define LAS __attribute__((address_space(3)))
; DI unsigned cvt_pk_bf16(float lo, float hi) { unsigned r; asm volatile("v_cvt_pk_bf16_f32 %0, %1, %2" : "=v"(r) : "v"(lo), "v"(hi)); return r; }
; #define MFMA16(a, b, c) __builtin_amdgcn_mfma_f32_16x16x32_bf16((a), (b), (c), 0, 0, 0)
; DI void ret_out_item(const Params& p, int l, int b, int h, int c, LAS unsigned char* lds) {
;     ...
;     for (int kc = 0; kc < 4; ++kc) {
;         f32x4 s[2];
; #pragma unroll
;         for (int hf = 0; hf < 2; ++hf) {
;             s[hf] = (f32x4){0.f, 0.f, 0.f, 0.f};
; #pragma unroll
;             for (int ks = 0; ks < 4; ++ks) s[hf] = MFMA16(*(const LAS bf16x8*)(kcp + (2 * kc + hf) * 16 * RS + ks * 64), qf[ks], s[hf]);
; #pragma unroll
;             for (int j = 0; j < 4; ++j) {
;                 const int m = (2 * kc + hf) * 16 + q4 * 4 + j, d = tl - m;
;                 const float w = (d >= 0 ? exp2f(lgf * (float)d) : 0.f) + (d <= 0 ? exp2f(-lgb * (float)d) : 0.f);
;                 s[hf][j] *= w;
;             }
;         }
;         u32x4 w4; w4.x = cvt_pk_bf16(s[0][0], s[0][1]); w4.y = cvt_pk_bf16(s[0][2], s[0][3]); w4.z = cvt_pk_bf16(s[1][0], s[1][1]); w4.w = cvt_pk_bf16(s[1][2], s[1][3]);
;         const bf16x8 pb = __builtin_bit_cast(bf16x8, w4);
; #pragma unroll
;         for (int d = 0; d < 8; ++d) {
;             const u32x2 lo = *(const LAS u32x2*)(vtp + d * 16 * RS + kc * 64), hi = *(const LAS u32x2*)(vtp + d * 16 * RS + kc * 64 + 32);
;             u32x4 a4; a4.x = lo.x; a4.y = lo.y; a4.z = hi.x; a4.w = hi.y;
;             oacc[d] = MFMA16(__builtin_bit_cast(bf16x8, a4), pb, oacc[d]);
;         }
	v_mfma_f32_16x16x32_bf16 v[16:19], v[92:95], v[56:59], v[20:23]
	ds_read2_b64 v[92:95], v64 offset0:80 offset1:84
	s_waitcnt lgkmcnt(1)
	v_mfma_f32_16x16x32_bf16 v[20:23], v[52:55], v[56:59], v[24:27]
	ds_read2_b64 v[52:55], v66 offset0:144 offset1:148
	s_nop 1
	ds_read2_b64 v[24:27], v65 offset0:112 offset1:116
	s_waitcnt lgkmcnt(0)
	v_mfma_f32_16x16x32_bf16 v[32:35], v[24:27], v[56:59], v[32:35]
	ds_read2_b64 v[24:27], v67 offset0:176 offset1:180
	v_mfma_f32_16x16x32_bf16 v[36:39], v[52:55], v[56:59], v[36:39]
	ds_read2_b64 v[52:55], v80 offset0:208 offset1:212
	s_waitcnt lgkmcnt(1)
	v_mfma_f32_16x16x32_bf16 v[40:43], v[24:27], v[56:59], v[40:43]
	ds_read2_b64 v[24:27], v81 offset0:240 offset1:244
	s_waitcnt lgkmcnt(1)
	v_mfma_f32_16x16x32_bf16 v[44:47], v[52:55], v[56:59], v[44:47]
	ds_read_b128 v[52:55], v62 offset:26112
	s_waitcnt lgkmcnt(1)
	v_mfma_f32_16x16x32_bf16 v[48:51], v[24:27], v[56:59], v[48:51]
	ds_read_b128 v[24:27], v62 offset:26176
	s_waitcnt lgkmcnt(1)
	v_mfma_f32_16x16x32_bf16 v[52:55], v[52:55], v[0:3], 0
	v_mfma_f32_16x16x32_bf16 v[28:31], v[92:95], v[56:59], v[28:31]
	ds_read_b128 v[56:59], v62 offset:26240
	s_waitcnt lgkmcnt(1)
	v_mfma_f32_16x16x32_bf16 v[24:27], v[24:27], v[4:7], v[52:55]
	s_nop 3
	v_or_b32_e32 v52, 0x60, v61
	v_sub_u32_e32 v92, v78, v52
	ds_read_b128 v[52:55], v62 offset:26304
	v_cvt_f32_u32_e32 v93, v92
	s_waitcnt lgkmcnt(1)
	v_mfma_f32_16x16x32_bf16 v[24:27], v[56:59], v[8:11], v[24:27]
	v_cvt_f32_i32_e32 v57, v92
	v_cmp_lt_i32_e64 s[0:1], -1, v92
	v_mul_f32_e32 v56, v79, v93
	v_cmp_gt_f32_e32 vcc, s3, v56
	s_waitcnt lgkmcnt(0)
	v_mfma_f32_16x16x32_bf16 v[24:27], v[52:55], v[12:15], v[24:27]
	v_mul_f32_e32 v53, v57, v73
	v_cndmask_b32_e32 v56, 0, v82, vcc
	v_cndmask_b32_e32 v52, 0, v86, vcc
	v_cmp_gt_f32_e32 vcc, s3, v53
	v_fmac_f32_e32 v56, v79, v93
	v_exp_f32_e32 v56, v56
	v_cndmask_b32_e32 v53, 0, v82, vcc
	v_fmac_f32_e32 v53, v57, v73
	v_exp_f32_e32 v53, v53
	v_cndmask_b32_e32 v54, 0, v86, vcc
	v_ldexp_f32 v52, v56, v52
	v_cmp_gt_i32_e32 vcc, 1, v92
	v_ldexp_f32 v53, v53, v54
	v_or_b32_e32 v54, 0x61, v61
	v_sub_u32_e32 v54, v78, v54
	v_cvt_f32_u32_e32 v55, v54
	v_cndmask_b32_e64 v52, 0, v52, s[0:1]
	v_cndmask_b32_e32 v53, 0, v53, vcc
	v_add_f32_e32 v52, v52, v53
	v_mul_f32_e32 v53, v79, v55
	v_cmp_gt_f32_e32 vcc, s3, v53
	v_mul_f32_e32 v24, v52, v24
	v_cmp_lt_i32_e64 s[0:1], -1, v54
	v_cndmask_b32_e32 v53, 0, v82, vcc
	v_fmac_f32_e32 v53, v79, v55
	v_exp_f32_e32 v53, v53
	v_cvt_f32_i32_e32 v55, v54
	v_cndmask_b32_e32 v52, 0, v86, vcc
	v_ldexp_f32 v52, v53, v52
	v_mul_f32_e32 v53, v55, v73
	v_cmp_gt_f32_e32 vcc, s3, v53
	v_cndmask_b32_e64 v52, 0, v52, s[0:1]
	s_nop 0
	v_cndmask_b32_e32 v53, 0, v82, vcc
	v_fmac_f32_e32 v53, v55, v73
	v_exp_f32_e32 v53, v53
	v_cndmask_b32_e32 v55, 0, v86, vcc
	v_cmp_gt_i32_e32 vcc, 1, v54
	v_ldexp_f32 v53, v53, v55
	v_or_b32_e32 v55, 0x62, v61
	v_sub_u32_e32 v55, v78, v55
	v_cvt_f32_u32_e32 v56, v55
	v_cndmask_b32_e32 v53, 0, v53, vcc
	v_add_f32_e32 v52, v52, v53
	v_cvt_f32_i32_e32 v54, v55
	v_mul_f32_e32 v53, v79, v56
	v_cmp_gt_f32_e32 vcc, s3, v53
	v_mul_f32_e32 v25, v52, v25
	v_cmp_lt_i32_e64 s[0:1], -1, v55
	v_cndmask_b32_e32 v53, 0, v82, vcc
	v_fmac_f32_e32 v53, v79, v56
	v_exp_f32_e32 v53, v53
	v_cndmask_b32_e32 v52, 0, v86, vcc
	v_ldexp_f32 v52, v53, v52
	v_mul_f32_e32 v53, v54, v73
	v_cmp_gt_f32_e32 vcc, s3, v53
	v_cndmask_b32_e64 v52, 0, v52, s[0:1]
	s_nop 0
	v_cndmask_b32_e32 v53, 0, v82, vcc
	v_fmac_f32_e32 v53, v54, v73
	v_exp_f32_e32 v53, v53
	v_cndmask_b32_e32 v54, 0, v86, vcc
	v_cmp_gt_i32_e32 vcc, 1, v55
	v_ldexp_f32 v53, v53, v54
	v_or_b32_e32 v54, 0x63, v61
	v_sub_u32_e32 v92, v78, v54
	v_cvt_f32_u32_e32 v54, v92
	v_cndmask_b32_e32 v53, 0, v53, vcc
	v_add_f32_e32 v52, v52, v53
	v_cvt_f32_i32_e32 v56, v92
	v_mul_f32_e32 v53, v79, v54
	v_cmp_gt_f32_e32 vcc, s3, v53
	v_mul_f32_e32 v26, v52, v26
	v_mul_f32_e32 v57, v56, v73
	v_cndmask_b32_e32 v53, 0, v82, vcc
	v_fmac_f32_e32 v53, v79, v54
	v_exp_f32_e32 v53, v53
	v_cndmask_b32_e32 v52, 0, v86, vcc
	v_cmp_gt_f32_e32 vcc, s3, v57
	v_cmp_lt_i32_e64 s[0:1], -1, v92
	v_ldexp_f32 v93, v53, v52
	ds_read_b128 v[52:55], v62 offset:30464
	v_cndmask_b32_e32 v57, 0, v82, vcc
	v_fmac_f32_e32 v57, v56, v73
	v_exp_f32_e32 v94, v57
	ds_read_b128 v[56:59], v62 offset:30528
	s_waitcnt lgkmcnt(1)
	v_mfma_f32_16x16x32_bf16 v[0:3], v[52:55], v[0:3], 0
	ds_read_b128 v[52:55], v62 offset:30592
	v_cndmask_b32_e32 v95, 0, v86, vcc
	v_ldexp_f32 v94, v94, v95
	s_waitcnt lgkmcnt(1)
	v_mfma_f32_16x16x32_bf16 v[0:3], v[56:59], v[4:7], v[0:3]
	v_or_b32_e32 v4, 0x70, v61
	v_sub_u32_e32 v56, v78, v4
	ds_read_b128 v[4:7], v62 offset:30656
	v_cvt_f32_u32_e32 v57, v56
	s_waitcnt lgkmcnt(1)
	v_mfma_f32_16x16x32_bf16 v[0:3], v[52:55], v[8:11], v[0:3]
	v_cvt_f32_i32_e32 v9, v56
	v_cmp_gt_i32_e32 vcc, 1, v92
	v_mul_f32_e32 v8, v79, v57
	s_waitcnt lgkmcnt(0)
; #define LAS __attribute__((address_space(3)))
; #define MFMA16(a, b, c) __builtin_amdgcn_mfma_f32_16x16x32_bf16((a), (b), (c), 0, 0, 0)
; DI void ret_out_item(const Params& p, int l, int b, int h, int c, LAS unsigned char* lds) {
;     ...
;         for (int d = 0; d < 8; ++d) {
;             const u32x2 lo = *(const LAS u32x2*)(vtp + d * 16 * RS + kc * 64), hi = *(const LAS u32x2*)(vtp + d * 16 * RS + kc * 64 + 32);
;             u32x4 a4; a4.x = lo.x; a4.y = lo.y; a4.z = hi.x; a4.w = hi.y;
;             oacc[d] = MFMA16(__builtin_bit_cast(bf16x8, a4), pb, oacc[d]);
;         }
;     }
;     float sum = 0.f;
; #pragma unroll
;     for (int d = 0; d < 8; ++d) sum += oacc[d][0] + oacc[d][1] + oacc[d][2] + oacc[d][3];
;     sum += __shfl_xor(sum, 16); sum += __shfl_xor(sum, 32);
;     const float mu = sum * (1.f / 128.f);
;     float sq = 0.f;
; #pragma unroll
;     for (int d = 0; d < 8; ++d) { oacc[d] -= mu; sq += oacc[d][0] * oacc[d][0] + oacc[d][1] * oacc[d][1] + oacc[d][2] * oacc[d][2] + oacc[d][3] * oacc[d][3]; }
;     sq += __shfl_xor(sq, 16); sq += __shfl_xor(sq, 32);
	v_mfma_f32_16x16x32_bf16 v[0:3], v[4:7], v[12:15], v[0:3]
	v_cndmask_b32_e32 v92, 0, v94, vcc
	v_cmp_gt_f32_e32 vcc, s3, v8
	v_mul_f32_e32 v5, v9, v73
	v_cndmask_b32_e64 v93, 0, v93, s[0:1]
	v_cndmask_b32_e32 v8, 0, v82, vcc
	v_cndmask_b32_e32 v4, 0, v86, vcc
	v_cmp_gt_f32_e32 vcc, s3, v5
	v_fmac_f32_e32 v8, v79, v57
	v_exp_f32_e32 v8, v8
	v_cndmask_b32_e32 v5, 0, v82, vcc
	v_fmac_f32_e32 v5, v9, v73
	v_exp_f32_e32 v5, v5
	v_cndmask_b32_e32 v6, 0, v86, vcc
	v_ldexp_f32 v4, v8, v4
	v_cmp_lt_i32_e64 s[0:1], -1, v56
	v_ldexp_f32 v5, v5, v6
	v_or_b32_e32 v6, 0x71, v61
	v_sub_u32_e32 v6, v78, v6
	v_cvt_f32_u32_e32 v7, v6
	v_cmp_gt_i32_e32 vcc, 1, v56
	v_cndmask_b32_e64 v4, 0, v4, s[0:1]
	v_cmp_lt_i32_e64 s[0:1], -1, v6
	v_cndmask_b32_e32 v5, 0, v5, vcc
	v_add_f32_e32 v4, v4, v5
	v_mul_f32_e32 v5, v79, v7
	v_cmp_gt_f32_e32 vcc, s3, v5
	v_mul_f32_e32 v4, v4, v0
	v_add_f32_e32 v92, v93, v92
	v_cndmask_b32_e32 v5, 0, v82, vcc
	v_fmac_f32_e32 v5, v79, v7
	v_exp_f32_e32 v5, v5
	v_cvt_f32_i32_e32 v7, v6
	v_cndmask_b32_e32 v0, 0, v86, vcc
	v_mul_f32_e32 v27, v92, v27
	v_ldexp_f32 v0, v5, v0
	v_mul_f32_e32 v5, v7, v73
	v_cmp_gt_f32_e32 vcc, s3, v5
	v_cndmask_b32_e64 v0, 0, v0, s[0:1]
	s_nop 0
	v_cndmask_b32_e32 v5, 0, v82, vcc
	v_fmac_f32_e32 v5, v7, v73
	v_exp_f32_e32 v5, v5
	v_cndmask_b32_e32 v7, 0, v86, vcc
	v_cmp_gt_i32_e32 vcc, 1, v6
	v_ldexp_f32 v5, v5, v7
	v_or_b32_e32 v7, 0x72, v61
	v_sub_u32_e32 v7, v78, v7
	v_cvt_f32_u32_e32 v8, v7
	v_cndmask_b32_e32 v5, 0, v5, vcc
	v_cvt_f32_i32_e32 v6, v7
	v_add_f32_e32 v0, v0, v5
	v_mul_f32_e32 v5, v79, v8
	v_cmp_gt_f32_e32 vcc, s3, v5
	v_cmp_lt_i32_e64 s[0:1], -1, v7
	s_nop 0
	v_cndmask_b32_e32 v5, 0, v82, vcc
	v_fmac_f32_e32 v5, v79, v8
	v_mul_f32_e32 v8, v0, v1
	v_mul_f32_e32 v1, v6, v73
	v_cndmask_b32_e32 v0, 0, v86, vcc
	v_cmp_gt_f32_e32 vcc, s3, v1
	v_exp_f32_e32 v5, v5
	s_nop 0
	v_cndmask_b32_e32 v1, 0, v82, vcc
	v_fmac_f32_e32 v1, v6, v73
	v_exp_f32_e32 v1, v1
	v_ldexp_f32 v0, v5, v0
	v_cndmask_b32_e32 v5, 0, v86, vcc
	v_cmp_gt_i32_e32 vcc, 1, v7
	v_ldexp_f32 v1, v1, v5
	v_or_b32_e32 v5, 0x73, v61
	v_sub_u32_e32 v5, v78, v5
	v_cvt_f32_u32_e32 v6, v5
	v_cndmask_b32_e64 v0, 0, v0, s[0:1]
	v_cndmask_b32_e32 v1, 0, v1, vcc
	v_add_f32_e32 v0, v0, v1
	v_mul_f32_e32 v1, v79, v6
	v_cmp_gt_f32_e32 vcc, s3, v1
	v_mul_f32_e32 v7, v0, v2
	v_cmp_lt_i32_e64 s[0:1], -1, v5
	v_cndmask_b32_e32 v1, 0, v82, vcc
	v_fmac_f32_e32 v1, v79, v6
	v_exp_f32_e32 v1, v1
	v_cvt_f32_i32_e32 v6, v5
	v_cndmask_b32_e32 v0, 0, v86, vcc
	v_ldexp_f32 v0, v1, v0
	v_mul_f32_e32 v1, v6, v73
	v_cmp_gt_f32_e32 vcc, s3, v1
	v_cndmask_b32_e64 v0, 0, v0, s[0:1]
	s_nop 0
	v_cndmask_b32_e32 v1, 0, v82, vcc
	v_fmac_f32_e32 v1, v6, v73
	v_exp_f32_e32 v1, v1
	v_cndmask_b32_e32 v2, 0, v86, vcc
	v_cmp_gt_i32_e32 vcc, 1, v5
	v_ldexp_f32 v1, v1, v2
	s_nop 0
	v_cndmask_b32_e32 v1, 0, v1, vcc
	v_add_f32_e32 v0, v0, v1
	v_mul_f32_e32 v3, v0, v3
	v_cvt_pk_bf16_f32 v0, v24, v25
	v_cvt_pk_bf16_f32 v1, v26, v27
	v_cvt_pk_bf16_f32 v2, v4, v8
	v_cvt_pk_bf16_f32 v3, v7, v3
	ds_read2_b64 v[4:7], v60 offset0:24 offset1:28
	s_waitcnt lgkmcnt(0)
	v_mfma_f32_16x16x32_bf16 v[52:55], v[4:7], v[0:3], v[16:19]
	ds_read2_b64 v[4:7], v63 offset0:56 offset1:60
	v_cmp_lt_i32_e32 vcc, v88, v89
	s_waitcnt lgkmcnt(0)
	v_mfma_f32_16x16x32_bf16 v[24:27], v[4:7], v[0:3], v[20:23]
	ds_read2_b64 v[4:7], v64 offset0:88 offset1:92
	s_waitcnt lgkmcnt(0)
	v_mfma_f32_16x16x32_bf16 v[20:23], v[4:7], v[0:3], v[28:31]
	ds_read2_b64 v[4:7], v65 offset0:120 offset1:124
	s_nop 1
	ds_read2_b64 v[28:31], v81 offset0:248 offset1:252
	s_waitcnt lgkmcnt(1)
	v_mfma_f32_16x16x32_bf16 v[16:19], v[4:7], v[0:3], v[32:35]
	ds_read2_b64 v[4:7], v66 offset0:152 offset1:156
	s_waitcnt lgkmcnt(0)
	v_mfma_f32_16x16x32_bf16 v[12:15], v[4:7], v[0:3], v[36:39]
	ds_read2_b64 v[4:7], v67 offset0:184 offset1:188
	s_waitcnt lgkmcnt(0)
	v_mfma_f32_16x16x32_bf16 v[8:11], v[4:7], v[0:3], v[40:43]
	ds_read2_b64 v[4:7], v80 offset0:216 offset1:220
	s_nop 1
	v_lshl_add_u64 v[42:43], v[76:77], 0, v[68:69]
	s_waitcnt lgkmcnt(0)
	v_mfma_f32_16x16x32_bf16 v[4:7], v[4:7], v[0:3], v[44:47]
	v_mfma_f32_16x16x32_bf16 v[0:3], v[28:31], v[0:3], v[48:51]
	v_mov_b32_e32 v28, v52
	v_mov_b32_e32 v29, v24
	v_mov_b32_e32 v30, v53
	v_mov_b32_e32 v31, v25
	v_pk_add_f32 v[28:29], v[28:29], v[30:31]
	v_mov_b32_e32 v30, v54
	v_mov_b32_e32 v31, v26
	v_pk_add_f32 v[28:29], v[30:31], v[28:29]
	v_mov_b32_e32 v30, v55
	v_mov_b32_e32 v31, v27
	v_pk_add_f32 v[28:29], v[30:31], v[28:29]
	v_mov_b32_e32 v30, v21
	v_add_f32_e32 v28, 0, v28
	v_add_f32_e32 v32, v28, v29
	v_mov_b32_e32 v28, v20
	v_mov_b32_e32 v29, v16
	v_mov_b32_e32 v31, v17
	v_pk_add_f32 v[28:29], v[28:29], v[30:31]
	v_mov_b32_e32 v30, v22
	v_mov_b32_e32 v31, v18
	v_pk_add_f32 v[28:29], v[30:31], v[28:29]
	v_mov_b32_e32 v30, v23
	v_mov_b32_e32 v31, v19
	v_pk_add_f32 v[28:29], v[30:31], v[28:29]
	v_mov_b32_e32 v30, v13
	v_add_f32_e32 v28, v32, v28
	v_add_f32_e32 v32, v28, v29
	v_mov_b32_e32 v28, v12
	v_mov_b32_e32 v29, v8
	v_mov_b32_e32 v31, v9
	v_pk_add_f32 v[28:29], v[28:29], v[30:31]
	v_mov_b32_e32 v30, v14
	v_mov_b32_e32 v31, v10
	v_pk_add_f32 v[28:29], v[30:31], v[28:29]
	v_mov_b32_e32 v30, v15
	v_mov_b32_e32 v31, v11
	v_pk_add_f32 v[28:29], v[30:31], v[28:29]
	v_mov_b32_e32 v30, v5
	v_add_f32_e32 v28, v32, v28
	v_add_f32_e32 v32, v28, v29
	v_mov_b32_e32 v28, v4
	v_mov_b32_e32 v29, v0
	v_mov_b32_e32 v31, v1
	v_pk_add_f32 v[28:29], v[28:29], v[30:31]
	v_mov_b32_e32 v30, v6
	v_mov_b32_e32 v31, v2
	v_pk_add_f32 v[28:29], v[30:31], v[28:29]
	v_mov_b32_e32 v30, v7
	v_mov_b32_e32 v31, v3
	v_pk_add_f32 v[28:29], v[30:31], v[28:29]
	s_nop 0
	v_add_f32_e32 v28, v32, v28
	v_add_f32_e32 v28, v28, v29
	v_cndmask_b32_e32 v29, v87, v88, vcc
	v_lshlrev_b32_e32 v50, 2, v29
	ds_bpermute_b32 v29, v50, v28
	v_cmp_lt_i32_e32 vcc, v90, v89
	s_waitcnt lgkmcnt(0)
; DI float silu(float v) { return v * __builtin_amdgcn_rcpf(1.f + __builtin_amdgcn_exp2f(-1.4426950408889634f * v)); }
; DI void st_bf16x4(bf16_t* p, f32x4 v) { u32x2 w; w.x = cvt_pk_bf16(v[0], v[1]); w.y = cvt_pk_bf16(v[2], v[3]); *(u32x2*)p = w; }
; DI void ret_out_item(const Params& p, int l, int b, int h, int c, LAS unsigned char* lds) {
;     ...
;     float sum = 0.f;
; #pragma unroll
;     for (int d = 0; d < 8; ++d) sum += oacc[d][0] + oacc[d][1] + oacc[d][2] + oacc[d][3];
;     sum += __shfl_xor(sum, 16); sum += __shfl_xor(sum, 32);
;     const float mu = sum * (1.f / 128.f);
;     float sq = 0.f;
; #pragma unroll
;     for (int d = 0; d < 8; ++d) { oacc[d] -= mu; sq += oacc[d][0] * oacc[d][0] + oacc[d][1] * oacc[d][1] + oacc[d][2] * oacc[d][2] + oacc[d][3] * oacc[d][3]; }
;     sq += __shfl_xor(sq, 16); sq += __shfl_xor(sq, 32);
;     const float rs = rsqrtf(sq * (1.f / 128.f) + 1e-5f);
;     const bf16_t* gp = P + row * INP + C_RG + h * 128 + q4 * 4;
;     bf16_t* op = (bf16_t*)(ws + WS_YMIX) + row * DM + 1408 + h * 128 + q4 * 4;
; #pragma unroll
;     for (int d = 0; d < 8; ++d) {
;         const u32x2 g2 = *(const u32x2*)(gp + d * 16);
;         f32x4 g; g[0] = __uint_as_float(g2.x << 16); g[1] = __uint_as_float(g2.x & 0xffff0000u); g[2] = __uint_as_float(g2.y << 16); g[3] = __uint_as_float(g2.y & 0xffff0000u);
;         f32x4 y;
; #pragma unroll
;         for (int j = 0; j < 4; ++j) y[j] = oacc[d][j] * rs * silu(g[j]);
;         st_bf16x4(op + d * 16, y);
;     }
	v_add_f32_e32 v28, v28, v29
	v_cndmask_b32_e32 v29, v87, v90, vcc
	v_lshlrev_b32_e32 v51, 2, v29
	ds_bpermute_b32 v29, v51, v28
	s_waitcnt lgkmcnt(0)
	v_add_f32_e32 v56, v28, v29
	v_add_co_u32_e32 v28, vcc, s35, v42
	v_fmamk_f32 v38, v56, 0xbc000000, v53
	s_nop 0
	v_addc_co_u32_e32 v29, vcc, 0, v43, vcc
	global_load_dwordx2 v[44:45], v[28:29], off offset:2432
	global_load_dwordx2 v[140:141], v[28:29], off offset:2464
	global_load_dwordx2 v[142:143], v[28:29], off offset:2496
	global_load_dwordx2 v[144:145], v[28:29], off offset:2528
	global_load_dwordx2 v[146:147], v[28:29], off offset:2560
	global_load_dwordx2 v[148:149], v[28:29], off offset:2592
	global_load_dwordx2 v[150:151], v[28:29], off offset:2624
	global_load_dwordx2 v[152:153], v[28:29], off offset:2656
	v_fmamk_f32 v39, v56, 0xbc000000, v25
	v_fmac_f32_e32 v24, 0xbc000000, v56
	v_fmac_f32_e32 v52, 0xbc000000, v56
	v_fmamk_f32 v31, v56, 0xbc000000, v27
	v_fmamk_f32 v35, v56, 0xbc000000, v26
	v_mov_b32_e32 v53, v24
	v_pk_mul_f32 v[26:27], v[38:39], v[38:39]
	v_fmamk_f32 v34, v56, 0xbc000000, v54
	v_pk_fma_f32 v[26:27], v[52:53], v[52:53], v[26:27]
	v_fmamk_f32 v30, v56, 0xbc000000, v55
	v_pk_fma_f32 v[26:27], v[34:35], v[34:35], v[26:27]
	v_fmamk_f32 v29, v56, 0xbc000000, v13
	v_fmac_f32_e32 v12, 0xbc000000, v56
	v_fmamk_f32 v28, v56, 0xbc000000, v9
	v_pk_fma_f32 v[46:47], v[30:31], v[30:31], v[26:27]
	v_fmamk_f32 v37, v56, 0xbc000000, v22
	v_fmamk_f32 v41, v56, 0xbc000000, v21
	v_fmac_f32_e32 v20, 0xbc000000, v56
	v_fmamk_f32 v40, v56, 0xbc000000, v17
	v_fmamk_f32 v22, v56, 0xbc000000, v11
	v_fmamk_f32 v26, v56, 0xbc000000, v10
	v_fmac_f32_e32 v8, 0xbc000000, v56
	v_mov_b32_e32 v9, v12
	v_pk_mul_f32 v[10:11], v[28:29], v[28:29]
	v_fmamk_f32 v32, v56, 0xbc000000, v19
	v_fmamk_f32 v36, v56, 0xbc000000, v18
	v_fmac_f32_e32 v16, 0xbc000000, v56
	v_mov_b32_e32 v17, v20
	v_pk_mul_f32 v[18:19], v[40:41], v[40:41]
	v_fmamk_f32 v27, v56, 0xbc000000, v14
	v_pk_fma_f32 v[10:11], v[8:9], v[8:9], v[10:11]
	v_fmamk_f32 v33, v56, 0xbc000000, v23
	v_pk_fma_f32 v[18:19], v[16:17], v[16:17], v[18:19]
	v_fmamk_f32 v23, v56, 0xbc000000, v15
	v_pk_fma_f32 v[10:11], v[26:27], v[26:27], v[10:11]
	v_fmamk_f32 v15, v56, 0xbc000000, v5
	v_fmac_f32_e32 v4, 0xbc000000, v56
	v_fmamk_f32 v14, v56, 0xbc000000, v1
	v_pk_fma_f32 v[18:19], v[36:37], v[36:37], v[18:19]
	v_pk_fma_f32 v[48:49], v[22:23], v[22:23], v[10:11]
	v_fmamk_f32 v11, v56, 0xbc000000, v6
	v_fmamk_f32 v6, v56, 0xbc000000, v3
	v_fmamk_f32 v10, v56, 0xbc000000, v2
	v_fmac_f32_e32 v0, 0xbc000000, v56
	v_mov_b32_e32 v1, v4
	v_pk_mul_f32 v[2:3], v[14:15], v[14:15]
	v_pk_fma_f32 v[18:19], v[32:33], v[32:33], v[18:19]
	v_pk_fma_f32 v[2:3], v[0:1], v[0:1], v[2:3]
	v_add_f32_e32 v1, v46, v47
	v_add_f32_e32 v1, v19, v1
	v_add_f32_e32 v1, v18, v1
	v_fmamk_f32 v7, v56, 0xbc000000, v7
	v_pk_fma_f32 v[2:3], v[10:11], v[10:11], v[2:3]
	v_add_f32_e32 v1, v49, v1
	v_pk_fma_f32 v[2:3], v[6:7], v[6:7], v[2:3]
	v_add_f32_e32 v1, v48, v1
	v_add_f32_e32 v1, v3, v1
	v_add_f32_e32 v1, v2, v1
	ds_bpermute_b32 v2, v50, v1
	v_lshl_add_u64 v[18:19], v[42:43], 0, s[12:13]
	v_mov_b32_e32 v49, v52
	s_waitcnt lgkmcnt(0)
	v_add_f32_e32 v1, v1, v2
	ds_bpermute_b32 v2, v51, v1
	v_mov_b32_e32 v51, v24
	s_waitcnt lgkmcnt(0)
	v_add_f32_e32 v1, v1, v2
	v_fmamk_f32 v1, v1, 0x3c000000, v91
	v_mul_f32_e32 v2, 0x4b800000, v1
	v_cmp_gt_f32_e32 vcc, s34, v1
	s_waitcnt vmcnt(7)
	v_and_b32_e32 v42, 0xffff0000, v44
	v_cndmask_b32_e32 v1, v1, v2, vcc
	v_rsq_f32_e32 v1, v1
	v_and_b32_e32 v46, 0xffff0000, v45
	v_mul_f32_e32 v2, 0x45800000, v1
	v_cndmask_b32_e32 v3, v1, v2, vcc
	v_lshlrev_b32_e32 v2, 16, v44
	v_mul_f32_e32 v1, 0xbfb8aa3b, v2
	v_exp_f32_e32 v1, v1
	v_lshlrev_b32_e32 v44, 16, v45
	v_mov_b32_e32 v43, v3
	v_mov_b32_e32 v45, v3
	v_add_f32_e32 v1, 1.0, v1
	v_rcp_f32_e32 v48, v1
	v_mul_f32_e32 v1, 0xbfb8aa3b, v42
	v_exp_f32_e32 v1, v1
	v_mov_b32_e32 v47, v3
	v_pk_mul_f32 v[48:49], v[48:49], v[2:3]
	v_add_f32_e32 v1, 1.0, v1
	v_mul_f32_e32 v2, v48, v49
	v_rcp_f32_e32 v48, v1
	v_mul_f32_e32 v1, 0xbfb8aa3b, v44
	v_exp_f32_e32 v1, v1
	v_mov_b32_e32 v49, v38
	v_pk_mul_f32 v[42:43], v[48:49], v[42:43]
	v_add_f32_e32 v1, 1.0, v1
	v_mul_f32_e32 v5, v42, v43
	v_rcp_f32_e32 v42, v1
	v_mul_f32_e32 v1, 0xbfb8aa3b, v46
	v_exp_f32_e32 v1, v1
	v_mov_b32_e32 v43, v34
	v_pk_mul_f32 v[42:43], v[42:43], v[44:45]
	v_mov_b32_e32 v45, v30
	v_add_f32_e32 v1, 1.0, v1
	v_rcp_f32_e32 v44, v1
	v_mul_f32_e32 v1, v42, v43
	v_pk_mul_f32 v[42:43], v[44:45], v[46:47]
	s_nop 0
	v_mul_f32_e32 v9, v42, v43
	v_cvt_pk_bf16_f32 v42, v2, v5
	v_cvt_pk_bf16_f32 v43, v1, v9
	s_waitcnt vmcnt(6)
	v_mov_b32_e32 v44, v140
	v_mov_b32_e32 v45, v141
	v_lshlrev_b64 v[46:47], 12, v[74:75]
	v_lshl_add_u64 v[46:47], s[50:51], 0, v[46:47]
	v_lshl_add_u64 v[46:47], v[46:47], 0, s[16:17]
	v_lshl_add_u64 v[46:47], v[46:47], 0, v[68:69]
	v_add_co_u32_e32 v48, vcc, s36, v46
	v_lshlrev_b32_e32 v2, 16, v44
	v_mul_f32_e32 v1, 0xbfb8aa3b, v2
	v_exp_f32_e32 v1, v1
	v_addc_co_u32_e32 v49, vcc, 0, v47, vcc
	global_store_dwordx2 v[48:49], v[42:43], off offset:2816
	v_add_f32_e32 v1, 1.0, v1
	v_rcp_f32_e32 v50, v1
	v_and_b32_e32 v42, 0xffff0000, v44
	v_lshlrev_b32_e32 v44, 16, v45
	v_mul_f32_e32 v5, 0xbfb8aa3b, v42
	v_and_b32_e32 v48, 0xffff0000, v45
	v_exp_f32_e32 v5, v5
	v_pk_mul_f32 v[24:25], v[50:51], v[2:3]
	v_mul_f32_e32 v2, 0xbfb8aa3b, v44
	v_exp_f32_e32 v2, v2
	v_mul_f32_e32 v9, 0xbfb8aa3b, v48
	v_exp_f32_e32 v9, v9
	v_add_f32_e32 v1, 1.0, v5
	v_rcp_f32_e32 v38, v1
	v_add_f32_e32 v2, 1.0, v2
	v_rcp_f32_e32 v34, v2
	v_add_f32_e32 v2, 1.0, v9
	v_rcp_f32_e32 v30, v2
	v_mov_b32_e32 v43, v3
	v_mul_f32_e32 v1, v24, v25
	v_pk_mul_f32 v[24:25], v[38:39], v[42:43]
	v_mov_b32_e32 v45, v3
	v_mul_f32_e32 v5, v24, v25
	v_pk_mul_f32 v[24:25], v[34:35], v[44:45]
	v_mov_b32_e32 v49, v3
	v_mul_f32_e32 v2, v24, v25
	v_pk_mul_f32 v[24:25], v[30:31], v[48:49]
	v_cvt_pk_bf16_f32 v30, v1, v5
	v_mov_b32_e32 v43, v20
	v_mul_f32_e32 v9, v24, v25
	v_cvt_pk_bf16_f32 v31, v2, v9
	s_waitcnt vmcnt(6)
; DI float silu(float v) { return v * __builtin_amdgcn_rcpf(1.f + __builtin_amdgcn_exp2f(-1.4426950408889634f * v)); }
; DI void st_bf16x4(bf16_t* p, f32x4 v) { u32x2 w; w.x = cvt_pk_bf16(v[0], v[1]); w.y = cvt_pk_bf16(v[2], v[3]); *(u32x2*)p = w; }
; DI void ret_out_item(const Params& p, int l, int b, int h, int c, LAS unsigned char* lds) {
;     ...
;     const bf16_t* gp = P + row * INP + C_RG + h * 128 + q4 * 4;
;     bf16_t* op = (bf16_t*)(ws + WS_YMIX) + row * DM + 1408 + h * 128 + q4 * 4;
; #pragma unroll
;     for (int d = 0; d < 8; ++d) {
;         const u32x2 g2 = *(const u32x2*)(gp + d * 16);
;         f32x4 g; g[0] = __uint_as_float(g2.x << 16); g[1] = __uint_as_float(g2.x & 0xffff0000u); g[2] = __uint_as_float(g2.y << 16); g[3] = __uint_as_float(g2.y & 0xffff0000u);
;         f32x4 y;
; #pragma unroll
;         for (int j = 0; j < 4; ++j) y[j] = oacc[d][j] * rs * silu(g[j]);
;         st_bf16x4(op + d * 16, y);
;     }
	v_mov_b32_e32 v34, v142
	v_mov_b32_e32 v35, v143
	v_lshl_add_u64 v[24:25], v[46:47], 0, s[14:15]
	global_store_dwordx2 v[24:25], v[30:31], off offset:32
	v_mov_b32_e32 v31, v3
	v_mov_b32_e32 v39, v3
	v_lshlrev_b32_e32 v2, 16, v34
	v_mul_f32_e32 v1, 0xbfb8aa3b, v2
	v_exp_f32_e32 v1, v1
	v_and_b32_e32 v30, 0xffff0000, v34
	v_lshlrev_b32_e32 v34, 16, v35
	v_and_b32_e32 v38, 0xffff0000, v35
	v_add_f32_e32 v1, 1.0, v1
	v_rcp_f32_e32 v42, v1
	v_mul_f32_e32 v1, 0xbfb8aa3b, v30
	v_exp_f32_e32 v1, v1
	v_mov_b32_e32 v35, v3
	v_pk_mul_f32 v[20:21], v[42:43], v[2:3]
	v_add_f32_e32 v1, 1.0, v1
	v_mul_f32_e32 v2, v20, v21
	v_rcp_f32_e32 v20, v1
	v_mul_f32_e32 v1, 0xbfb8aa3b, v34
	v_exp_f32_e32 v1, v1
	v_mov_b32_e32 v21, v41
	v_pk_mul_f32 v[20:21], v[20:21], v[30:31]
	v_mov_b32_e32 v31, v33
	v_add_f32_e32 v1, 1.0, v1
	v_mul_f32_e32 v5, v20, v21
	v_rcp_f32_e32 v20, v1
	v_mul_f32_e32 v1, 0xbfb8aa3b, v38
	v_exp_f32_e32 v1, v1
	v_mov_b32_e32 v21, v37
	v_pk_mul_f32 v[20:21], v[20:21], v[34:35]
	v_mov_b32_e32 v33, v12
	v_add_f32_e32 v1, 1.0, v1
	v_rcp_f32_e32 v30, v1
	v_mul_f32_e32 v1, v20, v21
	v_pk_mul_f32 v[20:21], v[30:31], v[38:39]
	s_nop 0
	v_mul_f32_e32 v9, v20, v21
	v_cvt_pk_bf16_f32 v20, v2, v5
	v_cvt_pk_bf16_f32 v21, v1, v9
	s_waitcnt vmcnt(6)
	v_mov_b32_e32 v30, v144
	v_mov_b32_e32 v31, v145
	v_mov_b32_e32 v39, v16
	global_store_dwordx2 v[24:25], v[20:21], off offset:64
	v_mov_b32_e32 v21, v3
	v_lshlrev_b32_e32 v2, 16, v30
	v_mul_f32_e32 v1, 0xbfb8aa3b, v2
	v_exp_f32_e32 v1, v1
	v_and_b32_e32 v20, 0xffff0000, v30
	v_lshlrev_b32_e32 v30, 16, v31
	v_and_b32_e32 v34, 0xffff0000, v31
	v_add_f32_e32 v1, 1.0, v1
	v_rcp_f32_e32 v38, v1
	v_mul_f32_e32 v1, 0xbfb8aa3b, v20
	v_exp_f32_e32 v1, v1
	v_mov_b32_e32 v31, v3
	v_pk_mul_f32 v[16:17], v[38:39], v[2:3]
	v_add_f32_e32 v1, 1.0, v1
	v_mul_f32_e32 v2, v16, v17
	v_rcp_f32_e32 v16, v1
	v_mul_f32_e32 v1, 0xbfb8aa3b, v30
	v_exp_f32_e32 v1, v1
	v_mov_b32_e32 v17, v40
	v_pk_mul_f32 v[16:17], v[16:17], v[20:21]
	v_mov_b32_e32 v21, v32
	v_add_f32_e32 v1, 1.0, v1
	v_mul_f32_e32 v5, v16, v17
	v_rcp_f32_e32 v16, v1
	v_mul_f32_e32 v1, 0xbfb8aa3b, v34
	v_exp_f32_e32 v1, v1
	v_mov_b32_e32 v17, v36
	v_pk_mul_f32 v[16:17], v[16:17], v[30:31]
	v_add_f32_e32 v1, 1.0, v1
	v_rcp_f32_e32 v20, v1
	v_mul_f32_e32 v1, v16, v17
	v_pk_mul_f32 v[16:17], v[20:21], v[34:35]
	s_nop 0
	v_mul_f32_e32 v9, v16, v17
	v_cvt_pk_bf16_f32 v16, v2, v5
	v_cvt_pk_bf16_f32 v17, v1, v9
	s_waitcnt vmcnt(6)
	v_mov_b32_e32 v20, v146
	v_mov_b32_e32 v21, v147
	v_lshlrev_b32_e32 v2, 16, v20
	v_mul_f32_e32 v1, 0xbfb8aa3b, v2
	v_exp_f32_e32 v1, v1
	global_store_dwordx2 v[24:25], v[16:17], off offset:96
	v_and_b32_e32 v16, 0xffff0000, v20
	v_lshlrev_b32_e32 v20, 16, v21
	v_add_f32_e32 v1, 1.0, v1
	v_rcp_f32_e32 v32, v1
	v_mul_f32_e32 v1, 0xbfb8aa3b, v16
	v_exp_f32_e32 v1, v1
	v_mov_b32_e32 v17, v3
	v_pk_mul_f32 v[12:13], v[32:33], v[2:3]
	v_and_b32_e32 v30, 0xffff0000, v21
	v_add_f32_e32 v1, 1.0, v1
	v_mul_f32_e32 v2, v12, v13
	v_rcp_f32_e32 v12, v1
	v_mul_f32_e32 v1, 0xbfb8aa3b, v20
	v_exp_f32_e32 v1, v1
	v_mov_b32_e32 v13, v29
	v_pk_mul_f32 v[12:13], v[12:13], v[16:17]
	v_mov_b32_e32 v21, v3
	v_add_f32_e32 v1, 1.0, v1
	v_mul_f32_e32 v5, v12, v13
	v_rcp_f32_e32 v12, v1
	v_mul_f32_e32 v1, 0xbfb8aa3b, v30
	v_exp_f32_e32 v1, v1
	v_mov_b32_e32 v13, v27
	v_pk_mul_f32 v[12:13], v[12:13], v[20:21]
	v_mov_b32_e32 v17, v23
	v_add_f32_e32 v1, 1.0, v1
	v_rcp_f32_e32 v16, v1
	v_mul_f32_e32 v1, v12, v13
	v_mov_b32_e32 v20, v3
	v_pk_mul_f32 v[12:13], v[16:17], v[30:31]
	s_nop 0
	v_mul_f32_e32 v9, v12, v13
	v_cvt_pk_bf16_f32 v12, v2, v5
	v_cvt_pk_bf16_f32 v13, v1, v9
	s_waitcnt vmcnt(6)
	v_mov_b32_e32 v16, v148
	v_mov_b32_e32 v17, v149
	v_mov_b32_e32 v30, v3
	global_store_dwordx2 v[24:25], v[12:13], off offset:128
	v_mov_b32_e32 v12, v3
	v_lshlrev_b32_e32 v13, 16, v16
	v_and_b32_e32 v21, 0xffff0000, v16
	v_mul_f32_e32 v1, 0xbfb8aa3b, v13
	v_exp_f32_e32 v1, v1
	v_mul_f32_e32 v2, 0xbfb8aa3b, v21
	v_exp_f32_e32 v2, v2
	v_lshlrev_b32_e32 v31, 16, v17
	v_add_f32_e32 v1, 1.0, v1
	v_rcp_f32_e32 v9, v1
	v_add_f32_e32 v1, 1.0, v2
	v_rcp_f32_e32 v29, v1
	v_and_b32_e32 v17, 0xffff0000, v17
	v_pk_mul_f32 v[8:9], v[8:9], v[12:13]
	v_mul_f32_e32 v2, 0xbfb8aa3b, v31
	v_mul_f32_e32 v1, v8, v9
	v_pk_mul_f32 v[8:9], v[28:29], v[20:21]
	v_exp_f32_e32 v2, v2
	v_mul_f32_e32 v5, v8, v9
	v_mul_f32_e32 v8, 0xbfb8aa3b, v17
	v_exp_f32_e32 v8, v8
	v_add_f32_e32 v2, 1.0, v2
	v_rcp_f32_e32 v27, v2
	v_mov_b32_e32 v16, v3
	v_add_f32_e32 v2, 1.0, v8
	v_rcp_f32_e32 v23, v2
	v_pk_mul_f32 v[8:9], v[26:27], v[30:31]
	s_nop 0
	v_mul_f32_e32 v2, v8, v9
	v_pk_mul_f32 v[8:9], v[22:23], v[16:17]
	s_nop 0
	v_mul_f32_e32 v9, v8, v9
	v_cvt_pk_bf16_f32 v8, v1, v5
	v_cvt_pk_bf16_f32 v9, v2, v9
	s_waitcnt vmcnt(6)
	v_mov_b32_e32 v12, v150
	v_mov_b32_e32 v13, v151
	v_and_b32_e32 v17, 0xffff0000, v12
	global_store_dwordx2 v[24:25], v[8:9], off offset:160
	v_lshlrev_b32_e32 v9, 16, v12
	v_mul_f32_e32 v1, 0xbfb8aa3b, v9
	v_exp_f32_e32 v1, v1
	v_mov_b32_e32 v8, v3
	v_lshlrev_b32_e32 v21, 16, v13
	v_and_b32_e32 v13, 0xffff0000, v13
	v_add_f32_e32 v1, 1.0, v1
	v_rcp_f32_e32 v5, v1
	v_mul_f32_e32 v1, 0xbfb8aa3b, v17
	v_exp_f32_e32 v1, v1
	v_mov_b32_e32 v12, v3
	v_pk_mul_f32 v[4:5], v[4:5], v[8:9]
	v_mov_b32_e32 v8, v7
	v_add_f32_e32 v1, 1.0, v1
	v_mul_f32_e32 v2, v4, v5
	v_rcp_f32_e32 v5, v1
	v_mul_f32_e32 v1, 0xbfb8aa3b, v21
	v_exp_f32_e32 v1, v1
	v_mov_b32_e32 v4, v15
	v_pk_mul_f32 v[4:5], v[4:5], v[16:17]
	v_add_f32_e32 v1, 1.0, v1
	v_mul_f32_e32 v15, v4, v5
	v_rcp_f32_e32 v5, v1
	v_mul_f32_e32 v1, 0xbfb8aa3b, v13
	v_exp_f32_e32 v1, v1
	v_mov_b32_e32 v4, v11
	v_pk_mul_f32 v[4:5], v[4:5], v[20:21]
	v_add_f32_e32 v1, 1.0, v1
	v_rcp_f32_e32 v9, v1
	v_mul_f32_e32 v1, v4, v5
	v_pk_mul_f32 v[4:5], v[8:9], v[12:13]
	s_nop 0
	v_mul_f32_e32 v5, v4, v5
	v_cvt_pk_bf16_f32 v4, v2, v15
	v_cvt_pk_bf16_f32 v5, v1, v5
	s_waitcnt vmcnt(6)
	v_mov_b32_e32 v8, v152
	v_mov_b32_e32 v9, v153
	v_and_b32_e32 v13, 0xffff0000, v8
	global_store_dwordx2 v[24:25], v[4:5], off offset:192
	v_lshlrev_b32_e32 v5, 16, v8
	v_mul_f32_e32 v1, 0xbfb8aa3b, v5
	v_exp_f32_e32 v1, v1
	v_mul_f32_e32 v2, 0xbfb8aa3b, v13
	v_exp_f32_e32 v2, v2
	v_mov_b32_e32 v4, v3
	v_add_f32_e32 v1, 1.0, v1
	v_rcp_f32_e32 v1, v1
	v_add_f32_e32 v2, 1.0, v2
	v_rcp_f32_e32 v15, v2
	v_lshlrev_b32_e32 v17, 16, v9
	v_pk_mul_f32 v[0:1], v[0:1], v[4:5]
	v_and_b32_e32 v9, 0xffff0000, v9
	v_mul_f32_e32 v2, v0, v1
	v_pk_mul_f32 v[0:1], v[14:15], v[12:13]
	v_mul_f32_e32 v4, 0xbfb8aa3b, v17
	v_exp_f32_e32 v4, v4
	v_mul_f32_e32 v5, v0, v1
	v_mul_f32_e32 v0, 0xbfb8aa3b, v9
	v_exp_f32_e32 v0, v0
	v_add_f32_e32 v1, 1.0, v4
	v_rcp_f32_e32 v11, v1
	v_mov_b32_e32 v8, v3
	v_add_f32_e32 v0, 1.0, v0
	v_rcp_f32_e32 v7, v0
	v_pk_mul_f32 v[0:1], v[10:11], v[16:17]
	s_nop 0
	v_mul_f32_e32 v4, v0, v1
	v_pk_mul_f32 v[0:1], v[6:7], v[8:9]
	s_nop 0
	v_mul_f32_e32 v1, v0, v1
	v_cvt_pk_bf16_f32 v0, v2, v5
	v_cvt_pk_bf16_f32 v1, v4, v1
	global_store_dwordx2 v[24:25], v[0:1], off offset:224
	s_barrier
; DI int otid() { int t = threadIdx.x; asm volatile("" : "+v"(t)); return t; }
; DI void na_block_item(const Params& p, int l, int b, int h, int rp, LAS unsigned char* lds) {
;     const int tid = otid(), lane = tid & 63, wid = tid >> 6, r16 = lane & 15, q4 = lane >> 4;
;     unsigned char* ws = p.ws;
;     const bf16_t* P = (const bf16_t*)(ws + WS_P);
;     constexpr int KROW = 272, KTILE = 64 * KROW, VROW = 144, VTILE = 128 * VROW;
;     const int gr = 2 * rp + (wid >> 2), jq = wid & 3;
;     const int gc = jq * 16 + r16, r0w = min(max(gr - 4, 0), 24), band = min(max(jq * 16 - 8, 0), 32), cs = min(max(gc - 8, 0), 48);
;     const int r0a = min(max(2 * rp - 4, 0), 24), r0b = min(max(2 * rp - 3, 0), 24), nloc = r0b + 8 - r0a, ntl = nloc + 4;
;     const size_t rowb = (size_t)b * RB, rowq = rowb + CL + gr * 64 + gc;
;     const float sl2 = 0.08838834764831845f * 1.4426950408889634f;
;     const float* rpb = p.in[11] + (size_t)(l * 6 + h) * 15 * 31;
;     ...
;             if (local) {
; #pragma unroll
;                 for (int hf = 0; hf < 2; ++hf)
; #pragma unroll
;                     for (int j = 0; j < 4; ++j) {
;                         const int kcol = band + hf * 16 + q4 * 4 + j; const bool inw = kcol >= cs && kcol < cs + 16;
;                         s[hf][j] = inw ? s[hf][j] * sl2 + bias8[hf * 4 + j] * 1.4426950408889634f : -1e30f;
;                     }
	s_and_saveexec_b64 s[0:1], s[24:25]
	s_cbranch_execz .LBB0_1179
	s_mov_b64 s[18:19], exec
	v_mbcnt_lo_u32_b32 v0, s18, 0
	v_mbcnt_hi_u32_b32 v0, s19, v0
	v_cmp_eq_u32_e32 vcc, 0, v0
	s_and_saveexec_b64 s[16:17], vcc
	s_cbranch_execz .LBB0_1178
	s_bcnt1_i32_b64 s18, s[18:19]
	v_mov_b32_e32 v1, s18
	global_atomic_add v1, v69, v1, s[42:43] sc0
	s_branch .LBB0_1178
.LBB0_1183:
	s_cmpk_gt_u32 s28, 0x3b3
	s_cbranch_scc1 .LBB0_1277
	s_mov_b32 s29, s28
	s_mov_b32 s22, 0x3e0293ee
	s_mov_b32 s23, 0x3fb8aa3b
	v_and_b32_e32 v196, 15, v202
	v_bfe_u32 v197, v202, 4, 2
	v_lshrrev_b32_e32 v198, 6, v202
	s_nop 0
	v_readfirstlane_b32 s74, v198
	v_mov_b32_e32 v199, v202
	v_lshrrev_b32_e32 v200, 4, v199
	v_and_b32_e32 v201, 15, v199
	v_lshlrev_b32_e32 v201, 4, v201
	v_mul_u32_u24_e32 v230, 0x3000, v200
	v_add_u32_e32 v230, v230, v201
	v_mul_u32_u24_e32 v234, 0x110, v200
	v_add_u32_e32 v234, v234, v201
	v_lshrrev_b32_e32 v200, 3, v199
	v_and_b32_e32 v201, 7, v199
	v_lshlrev_b32_e32 v201, 4, v201
	v_mul_u32_u24_e32 v232, 0x1200, v200
	v_add_u32_e32 v232, v232, v201
	v_mul_u32_u24_e32 v236, 0x90, v200
	v_add_u32_e32 v236, v236, v201
	v_add_u32_e32 v236, 0xcc00, v236
	v_add_u32_e32 v199, 0x200, v202
	v_lshrrev_b32_e32 v200, 4, v199
	v_and_b32_e32 v201, 15, v199
	v_lshlrev_b32_e32 v201, 4, v201
	v_mul_u32_u24_e32 v231, 0x3000, v200
	v_add_u32_e32 v231, v231, v201
	v_mul_u32_u24_e32 v235, 0x110, v200
	v_add_u32_e32 v235, v235, v201
	v_lshrrev_b32_e32 v200, 3, v199
	v_and_b32_e32 v201, 7, v199
	v_lshlrev_b32_e32 v201, 4, v201
	v_mul_u32_u24_e32 v233, 0x1200, v200
	v_add_u32_e32 v233, v233, v201
	v_mul_u32_u24_e32 v237, 0x90, v200
	v_add_u32_e32 v237, v237, v201
	v_add_u32_e32 v237, 0xcc00, v237
	v_mul_u32_u24_e32 v199, 0x110, v196
	v_lshl_add_u32 v238, v197, 4, v199
	v_mul_u32_u24_e32 v199, 0x90, v196
	v_lshl_add_u32 v199, v197, 3, v199
	v_add_u32_e32 v239, 0xcc00, v199
	v_mul_u32_u24_e32 v199, 0x3000, v196
	v_lshl_add_u32 v251, v197, 4, v199
	v_lshlrev_b32_e32 v199, 12, v196
	v_lshl_add_u32 v246, v197, 3, v199
	s_and_b32 s73, s74, 3
	s_lshl_b32 s73, s73, 4
	s_sub_i32 s56, s73, 8
	s_max_i32 s56, s56, 0
	s_min_i32 s56, s56, 32
	v_add_u32_e32 v220, s73, v196
	v_subrev_u32_e32 v221, 8, v220
	v_max_i32_e32 v221, 0, v221
	v_min_i32_e32 v221, 48, v221
	v_add_u32_e32 v222, 16, v221
	v_lshlrev_b32_e32 v223, 2, v197
	v_mov_b32_e32 v224, 0xf149f2ca
	v_mov_b32_e32 v225, 0x7f7fffff
	s_add_u32 s57, s56, 0
	v_add_u32_e32 v199, s57, v223
	v_sub_u32_e32 v200, v199, v220
	v_add_u32_e32 v200, 15, v200
	v_max_i32_e32 v200, 0, v200
	v_min_i32_e32 v200, 30, v200
	v_lshlrev_b32_e32 v200, 2, v200
	v_add_u32_e32 v132, 0x1a400, v200
	v_cmp_ge_i32_e32 vcc, v199, v221
	v_cmp_lt_i32_e64 s[0:1], v199, v222
	s_and_b64 vcc, vcc, s[0:1]
	v_cndmask_b32_e32 v140, v224, v225, vcc
	s_add_u32 s57, s56, 1
	v_add_u32_e32 v199, s57, v223
	v_sub_u32_e32 v200, v199, v220
	v_add_u32_e32 v200, 15, v200
	v_max_i32_e32 v200, 0, v200
	v_min_i32_e32 v200, 30, v200
	v_lshlrev_b32_e32 v200, 2, v200
	v_add_u32_e32 v133, 0x1a400, v200
	v_cmp_ge_i32_e32 vcc, v199, v221
	v_cmp_lt_i32_e64 s[0:1], v199, v222
	s_and_b64 vcc, vcc, s[0:1]
	v_cndmask_b32_e32 v141, v224, v225, vcc
	s_add_u32 s57, s56, 2
	v_add_u32_e32 v199, s57, v223
	v_sub_u32_e32 v200, v199, v220
	v_add_u32_e32 v200, 15, v200
	v_max_i32_e32 v200, 0, v200
	v_min_i32_e32 v200, 30, v200
	v_lshlrev_b32_e32 v200, 2, v200
	v_add_u32_e32 v134, 0x1a400, v200
	v_cmp_ge_i32_e32 vcc, v199, v221
	v_cmp_lt_i32_e64 s[0:1], v199, v222
	s_and_b64 vcc, vcc, s[0:1]
	v_cndmask_b32_e32 v142, v224, v225, vcc
	s_add_u32 s57, s56, 3
	v_add_u32_e32 v199, s57, v223
	v_sub_u32_e32 v200, v199, v220
	v_add_u32_e32 v200, 15, v200
	v_max_i32_e32 v200, 0, v200
	v_min_i32_e32 v200, 30, v200
	v_lshlrev_b32_e32 v200, 2, v200
	v_add_u32_e32 v135, 0x1a400, v200
	v_cmp_ge_i32_e32 vcc, v199, v221
	v_cmp_lt_i32_e64 s[0:1], v199, v222
	s_and_b64 vcc, vcc, s[0:1]
	v_cndmask_b32_e32 v143, v224, v225, vcc
	s_add_u32 s57, s56, 16
	v_add_u32_e32 v199, s57, v223
	v_sub_u32_e32 v200, v199, v220
	v_add_u32_e32 v200, 15, v200
	v_max_i32_e32 v200, 0, v200
	v_min_i32_e32 v200, 30, v200
	v_lshlrev_b32_e32 v200, 2, v200
	v_add_u32_e32 v136, 0x1a400, v200
	v_cmp_ge_i32_e32 vcc, v199, v221
	v_cmp_lt_i32_e64 s[0:1], v199, v222
	s_and_b64 vcc, vcc, s[0:1]
	v_cndmask_b32_e32 v144, v224, v225, vcc
	s_add_u32 s57, s56, 17
	v_add_u32_e32 v199, s57, v223
	v_sub_u32_e32 v200, v199, v220
	v_add_u32_e32 v200, 15, v200
	v_max_i32_e32 v200, 0, v200
	v_min_i32_e32 v200, 30, v200
	v_lshlrev_b32_e32 v200, 2, v200
	v_add_u32_e32 v137, 0x1a400, v200
	v_cmp_ge_i32_e32 vcc, v199, v221
	v_cmp_lt_i32_e64 s[0:1], v199, v222
	s_and_b64 vcc, vcc, s[0:1]
	v_cndmask_b32_e32 v145, v224, v225, vcc
	s_add_u32 s57, s56, 18
	v_add_u32_e32 v199, s57, v223
	v_sub_u32_e32 v200, v199, v220
	v_add_u32_e32 v200, 15, v200
	v_max_i32_e32 v200, 0, v200
	v_min_i32_e32 v200, 30, v200
	v_lshlrev_b32_e32 v200, 2, v200
	v_add_u32_e32 v138, 0x1a400, v200
	v_cmp_ge_i32_e32 vcc, v199, v221
	v_cmp_lt_i32_e64 s[0:1], v199, v222
	s_and_b64 vcc, vcc, s[0:1]
	v_cndmask_b32_e32 v146, v224, v225, vcc
	s_add_u32 s57, s56, 19
	v_add_u32_e32 v199, s57, v223
	v_sub_u32_e32 v200, v199, v220
	v_add_u32_e32 v200, 15, v200
	v_max_i32_e32 v200, 0, v200
	v_min_i32_e32 v200, 30, v200
	v_lshlrev_b32_e32 v200, 2, v200
	v_add_u32_e32 v139, 0x1a400, v200
	v_cmp_ge_i32_e32 vcc, v199, v221
	v_cmp_lt_i32_e64 s[0:1], v199, v222
	s_and_b64 vcc, vcc, s[0:1]
	v_cndmask_b32_e32 v147, v224, v225, vcc
	v_readlane_b32 s10, v255, 62
	v_readlane_b32 s11, v255, 63
	s_nop 4
	s_load_dwordx2 s[8:9], s[10:11], 0x58
	s_waitcnt lgkmcnt(0)
	v_writelane_b32 v254, s8, 0
	v_writelane_b32 v254, s9, 1
	v_writelane_b32 v254, s74, 2
; #define LAS __attribute__((address_space(3)))
; DI int otid() { int t = threadIdx.x; asm volatile("" : "+v"(t)); return t; }
; #define NA_LOAD(t, ks_, vs_) do { const int tb_ = NA_TB(t); \
;         _Pragma("unroll") for (int i = 0; i < 2; ++i) { const int cid = tid + i * 512; \
;             ks_[i] = *(const u32x4*)(kg + (size_t)(tb_ + (cid >> 4)) * INP + (cid & 15) * 8); \
;             vs_[i] = *(const u32x4*)(vg + (size_t)(cid >> 3) * RB + tb_ + (cid & 7) * 8); } } while (0)
; DI void na_block_item(const Params& p, int l, int b, int h, int rp, LAS unsigned char* lds) {
;     const int tid = otid(), lane = tid & 63, wid = tid >> 6, r16 = lane & 15, q4 = lane >> 4;
;     unsigned char* ws = p.ws;
;     const bf16_t* P = (const bf16_t*)(ws + WS_P);
;     constexpr int KROW = 272, KTILE = 64 * KROW, VROW = 144, VTILE = 128 * VROW;
;     const int gr = 2 * rp + (wid >> 2), jq = wid & 3;
;     const int gc = jq * 16 + r16, r0w = min(max(gr - 4, 0), 24), band = min(max(jq * 16 - 8, 0), 32), cs = min(max(gc - 8, 0), 48);
;     const int r0a = min(max(2 * rp - 4, 0), 24), r0b = min(max(2 * rp - 3, 0), 24), nloc = r0b + 8 - r0a, ntl = nloc + 4;
;     const size_t rowb = (size_t)b * RB, rowq = rowb + CL + gr * 64 + gc;
;     const float sl2 = 0.08838834764831845f * 1.4426950408889634f;
;     const float* rpb = p.in[11] + (size_t)(l * 6 + h) * 15 * 31;
;     bf16x8 qf[4];
; #pragma unroll
;     for (int ks = 0; ks < 4; ++ks) qf[ks] = *(const bf16x8*)(P + rowq * INP + C_NAQ + h * 128 + ks * 32 + q4 * 8);
;     f32x4 oacc[8];
; #pragma unroll
;     for (int d = 0; d < 8; ++d) oacc[d] = (f32x4){0.f, 0.f, 0.f, 0.f};
;     float mrun = -1e30f, lsum = 0.f;
;     const bf16_t* kg = P + rowb * INP + C_NAK + h * 128;
;     const bf16_t* vg = (const bf16_t*)(ws + WS_VTNA) + ((size_t)b * 768 + h * 128) * RB;
;     u32x4 kstA[2], vstA[2], kstB[2], vstB[2];
;     ...
;     LAS float* s_rpb = (LAS float*)(lds + 3 * KTILE + 3 * VTILE);
;     if (tid < 465) s_rpb[tid] = rpb[tid];
;     NA_LOAD(0, kstA, vstA); NA_LOAD(1, kstB, vstB);
;     NA_STORE(0, kstA, vstA);
;     NA_LOAD(2, kstA, vstA);
;     __syncthreads();
na0_item:
	s_sub_u32 s57, s29, 0x234
	s_and_b32 s71, s57, 15
	s_lshr_b32 s57, s57, 4
	s_mul_i32 s73, s57, 43
	s_lshr_b32 s73, s73, 8
	s_mul_i32 s63, s73, 6
	s_sub_u32 s72, s57, s63
	s_lshl_b32 s57, s71, 1
	s_sub_i32 s36, s57, 4
	s_max_i32 s36, s36, 0
	s_min_i32 s36, s36, 24
	s_sub_i32 s63, s57, 3
	s_max_i32 s63, s63, 0
	s_min_i32 s63, s63, 24
	s_sub_u32 s30, s63, s36
	s_add_u32 s30, s30, 8
	s_add_u32 s31, s30, 4
	v_readlane_b32 s74, v254, 2
	s_lshr_b32 s63, s74, 2
	s_add_u32 s37, s57, s63
	s_sub_i32 s54, s37, 4
	s_max_i32 s54, s54, 0
	s_min_i32 s54, s54, 24
	s_mul_i32 s68, s73, 0x900
	s_mul_i32 s57, s68, 0x3000
	s_lshl_b32 s63, s72, 8
	s_add_u32 s57, s57, s63
	s_add_u32 s57, s57, 0x113a0600
	s_add_u32 s2, s50, s57
	s_addc_u32 s3, s51, 0
	s_mul_i32 s57, s73, 0x300
	s_lshl_b32 s69, s72, 7
	s_add_u32 s57, s57, s69
	s_mul_i32 s57, s57, 0x1200
	s_add_u32 s57, s57, 0x17fa0000
	s_add_u32 s4, s50, s57
	s_addc_u32 s5, s51, 0
	s_and_b32 s69, s74, 3
	s_lshl_b32 s69, s69, 4
	s_lshl_b32 s70, s37, 6
	s_add_u32 s69, s69, s70
	s_add_u32 s69, s69, s68
	s_addk_i32 s69, 0x100
	s_mul_i32 s57, s69, 0x3000
	s_add_u32 s57, s57, s63
	s_add_u32 s57, s57, 0x113a0000
	s_add_u32 s6, s50, s57
	s_addc_u32 s7, s51, 0
	global_load_dwordx4 v[0:3], v251, s[6:7] offset:0
	global_load_dwordx4 v[4:7], v251, s[6:7] offset:64
	global_load_dwordx4 v[8:11], v251, s[6:7] offset:128
	global_load_dwordx4 v[12:15], v251, s[6:7] offset:192
	s_lshl_b32 s57, s69, 12
	s_add_u32 s57, s57, s63
	s_add_u32 s57, s57, 0x1d9a0000
	s_add_u32 s10, s50, s57
	s_addc_u32 s11, s51, 0
	v_readlane_b32 s6, v254, 0
	v_readlane_b32 s7, v254, 1
	s_mul_i32 s57, s72, 0x744
	s_add_u32 s57, s57, 0x0
	s_nop 2
	s_add_u32 s6, s6, s57
	s_addc_u32 s7, s7, 0
	v_lshlrev_b32_e32 v196, 2, v202
	v_cmp_gt_u32_e32 vcc, 0x1d1, v202
	s_and_saveexec_b64 s[0:1], vcc
	global_load_dword v197, v196, s[6:7]
	s_or_b64 exec, exec, s[0:1]
	s_mov_b32 s70, 0
	s_add_u32 s57, s36, s70
	s_lshl_b32 s57, s57, 6
	s_addk_i32 s57, 0x100
	s_sub_u32 s63, s70, s30
	s_lshl_b32 s63, s63, 6
	s_cmp_lt_u32 s70, s30
	s_cselect_b32 s57, s57, s63
	s_mul_i32 s63, s57, 0x3000
	s_add_u32 s6, s2, s63
	s_addc_u32 s7, s3, 0
	s_lshl_b32 s63, s57, 1
	s_add_u32 s8, s4, s63
	s_addc_u32 s9, s5, 0
	global_load_dwordx4 v[148:151], v230, s[6:7]
	global_load_dwordx4 v[152:155], v231, s[6:7]
	global_load_dwordx4 v[156:159], v232, s[8:9]
	global_load_dwordx4 v[160:163], v233, s[8:9]
	s_mov_b32 s70, 1
	s_add_u32 s57, s36, s70
	s_lshl_b32 s57, s57, 6
	s_addk_i32 s57, 0x100
	s_sub_u32 s63, s70, s30
	s_lshl_b32 s63, s63, 6
	s_cmp_lt_u32 s70, s30
	s_cselect_b32 s57, s57, s63
	s_mul_i32 s63, s57, 0x3000
	s_add_u32 s6, s2, s63
	s_addc_u32 s7, s3, 0
	s_lshl_b32 s63, s57, 1
	s_add_u32 s8, s4, s63
	s_addc_u32 s9, s5, 0
	global_load_dwordx4 v[164:167], v230, s[6:7]
	global_load_dwordx4 v[168:171], v231, s[6:7]
	global_load_dwordx4 v[172:175], v232, s[8:9]
	global_load_dwordx4 v[176:179], v233, s[8:9]
	s_mov_b32 s70, 2
	s_add_u32 s57, s36, s70
	s_lshl_b32 s57, s57, 6
	s_addk_i32 s57, 0x100
	s_sub_u32 s63, s70, s30
	s_lshl_b32 s63, s63, 6
	s_cmp_lt_u32 s70, s30
	s_cselect_b32 s57, s57, s63
	s_mul_i32 s63, s57, 0x3000
	s_add_u32 s6, s2, s63
	s_addc_u32 s7, s3, 0
	s_lshl_b32 s63, s57, 1
	s_add_u32 s8, s4, s63
	s_addc_u32 s9, s5, 0
	global_load_dwordx4 v[180:183], v230, s[6:7]
	global_load_dwordx4 v[184:187], v231, s[6:7]
	global_load_dwordx4 v[188:191], v232, s[8:9]
	global_load_dwordx4 v[192:195], v233, s[8:9]
	s_mov_b32 s70, 3
	s_add_u32 s57, s36, s70
	s_lshl_b32 s57, s57, 6
	s_addk_i32 s57, 0x100
	s_sub_u32 s63, s70, s30
	s_lshl_b32 s63, s63, 6
	s_cmp_lt_u32 s70, s30
	s_cselect_b32 s57, s57, s63
	s_mul_i32 s63, s57, 0x3000
	s_add_u32 s6, s2, s63
	s_addc_u32 s7, s3, 0
	s_lshl_b32 s63, s57, 1
	s_add_u32 s8, s4, s63
	s_addc_u32 s9, s5, 0
	global_load_dwordx4 v[204:207], v230, s[6:7]
	global_load_dwordx4 v[208:211], v231, s[6:7]
	global_load_dwordx4 v[212:215], v232, s[8:9]
	global_load_dwordx4 v[216:219], v233, s[8:9]
	v_mov_b32_e32 v16, 0
	v_mov_b32_e32 v17, 0
	v_mov_b32_e32 v18, 0
	v_mov_b32_e32 v19, 0
	v_mov_b32_e32 v20, 0
	v_mov_b32_e32 v21, 0
	v_mov_b32_e32 v22, 0
	v_mov_b32_e32 v23, 0
	v_mov_b32_e32 v24, 0
	v_mov_b32_e32 v25, 0
	v_mov_b32_e32 v26, 0
	v_mov_b32_e32 v27, 0
	v_mov_b32_e32 v28, 0
	v_mov_b32_e32 v29, 0
	v_mov_b32_e32 v30, 0
	v_mov_b32_e32 v31, 0
	v_mov_b32_e32 v32, 0
	v_mov_b32_e32 v33, 0
	v_mov_b32_e32 v34, 0
	v_mov_b32_e32 v35, 0
	v_mov_b32_e32 v36, 0
	v_mov_b32_e32 v37, 0
	v_mov_b32_e32 v38, 0
	v_mov_b32_e32 v39, 0
	v_mov_b32_e32 v40, 0
	v_mov_b32_e32 v41, 0
	v_mov_b32_e32 v42, 0
	v_mov_b32_e32 v43, 0
	v_mov_b32_e32 v44, 0
	v_mov_b32_e32 v45, 0
	v_mov_b32_e32 v46, 0
	v_mov_b32_e32 v47, 0
	v_mov_b32_e32 v242, 0xf149f2ca
	v_mov_b32_e32 v243, 0
	s_waitcnt vmcnt(12)
	v_cmp_gt_u32_e32 vcc, 0x1d1, v202
	s_and_saveexec_b64 s[0:1], vcc
	v_add_u32_e32 v196, 0x1a400, v196
	ds_write_b32 v196, v197
	s_or_b64 exec, exec, s[0:1]
	ds_write_b128 v234, v[148:151]
	ds_write_b128 v235, v[152:155]
	ds_write_b128 v236, v[156:159]
	ds_write_b128 v237, v[160:163]
	s_waitcnt lgkmcnt(0)
	s_mov_b32 s70, 4
	s_add_u32 s57, s36, s70
	s_lshl_b32 s57, s57, 6
	s_addk_i32 s57, 0x100
	s_sub_u32 s63, s70, s30
	s_lshl_b32 s63, s63, 6
	s_cmp_lt_u32 s70, s30
	s_cselect_b32 s57, s57, s63
	s_mul_i32 s63, s57, 0x3000
	s_add_u32 s6, s2, s63
	s_addc_u32 s7, s3, 0
	s_lshl_b32 s63, s57, 1
	s_add_u32 s8, s4, s63
	s_addc_u32 s9, s5, 0
	global_load_dwordx4 v[148:151], v230, s[6:7]
	global_load_dwordx4 v[152:155], v231, s[6:7]
	global_load_dwordx4 v[156:159], v232, s[8:9]
	global_load_dwordx4 v[160:163], v233, s[8:9]
	s_barrier
	s_mov_b32 s27, 0

; DI void phase_mixers(const Params& p, int l, LAS unsigned char* lds) {
;     ...
;     int it = next_item(ctr, slot);
;     while (it < e0) { dense192_item(ws, lds, it / 40, (it >> 3) % 5, CL + (it & 7) * 256, RB); it = next_item(ctr, slot); }
;     while (it < e1) { const int i2 = it - e0, c = (i2 % nc) + (18 - nc), bh = i2 / nc; ret_out_item(p, l, bh / 5, bh % 5, c, lds); it = next_item(ctr, slot); }
;     while (it < e2) { const int i2 = it - e1; na_block_item(p, l, i2 / 96, (i2 >> 4) % 6, i2 & 15, lds); it = next_item(ctr, slot); }
;     if (l == 0) {
;         while (it < e2 + 20) { const int i2 = it - e2; dense192_item(ws, lds, i2 / 5, i2 % 5, 0, CL); it = next_item(ctr, slot); }
na0_nq:
	s_or_b64 exec, exec, s[0:1]
	v_mov_b32_e32 v197, 0x22040
	s_waitcnt vmcnt(0) lgkmcnt(0)
	s_barrier
	ds_read_b32 v196, v197
	s_waitcnt lgkmcnt(0)
	v_readfirstlane_b32 s29, v196
	s_cmp_lt_u32 s29, 0x3b4
	s_cbranch_scc1 na0_item
	s_mov_b32 s28, s29
	v_mov_b32_e32 v133, 0
	s_branch .LBB0_1277
.LBB0_1234:
	s_cmpk_gt_u32 s28, 0xb3
	s_cbranch_scc1 .LBB0_1268
	s_add_u32 s2, s50, 0x1a3a0000
	s_addc_u32 s3, s51, 0
	s_add_u32 s4, s50, 0x1b480000
	s_addc_u32 s5, s51, 0
	s_add_u32 s27, s50, 0x1cb00000
	s_addc_u32 s30, s51, 0
	s_add_u32 s31, s50, 0x1bfc0000
	s_addc_u32 s34, s51, 0
	s_add_u32 s10, s50, 0x1bfc0080
	s_addc_u32 s11, s51, 0
	s_add_u32 s12, s50, 0x1b494000
	s_movk_i32 s14, 0xff00
	s_addc_u32 s13, s51, 0
	s_movk_i32 s35, 0xffe0
	v_mov_b32_e32 v133, 0
	s_movk_i32 s36, 0x780
	s_mov_b32 s37, 0x2aaaaaab
	s_mov_b32 s15, -1
	s_movk_i32 s70, 0x500
	s_movk_i32 s71, 0x1200
	s_movk_i32 s72, 0x190
	s_movk_i32 s73, 0x90
	s_mov_b32 s74, 0x3dd53b94
	s_mov_b32 s75, 0xc800
	s_mov_b64 s[16:17], 0x80
	s_mov_b64 s[18:19], 0x14000
	s_mov_b64 s[20:21], 0x1d9a0600
	s_add_i32 s76, 0, 0x22040
	v_mbcnt_hi_u32_b32 v182, -1, v203
	v_mov_b32_e32 v183, 0x1900
	v_mov_b32_e32 v184, 0x3200
	v_mov_b32_e32 v185, 0x4b00
	s_branch .LBB0_1238

; #define LAS __attribute__((address_space(3)))
; DI int otid() { int t = threadIdx.x; asm volatile("" : "+v"(t)); return t; }
; template <int DK>
; DI void dense_attn_item(LAS unsigned char* lds, const bf16_t* Qb, int ldq, const bf16_t* Kb, int ldk, const bf16_t* Kpe, const bf16_t* Vt, int nkeys, float sl2, bf16_t* Ob) {
;     const int tid = otid(), lane = tid & 63, wid = tid >> 6, r16 = lane & 15, q4 = lane >> 4;
;     constexpr int KS = DK / 32, KCH = DK / 8, KROW = DK * 2 + 16, KTILE = 64 * KROW, VROW = 144, VTILE = 128 * VROW, NKL = (64 * KCH) / 512;
;     bf16x8 qf[2][KS];
; #pragma unroll
;     for (int qg = 0; qg < 2; ++qg)
; #pragma unroll
;         for (int ks = 0; ks < KS; ++ks) qf[qg][ks] = *(const bf16x8*)(Qb + (size_t)(wid * 32 + qg * 16 + r16) * ldq + ks * 32 + q4 * 8);
;     f32x4 oacc[2][8];
; #pragma unroll
;     for (int qg = 0; qg < 2; ++qg)
; #pragma unroll
;         for (int d = 0; d < 8; ++d) oacc[qg][d] = (f32x4){0.f, 0.f, 0.f, 0.f};
;     float mrun[2] = {-1e30f, -1e30f}, lsum[2] = {0.f, 0.f};
;     u32x4 kst[NKL], vst[2];
;     const int ntiles = nkeys >> 6;
;     ...
;     DA_LOAD(0); DA_STORE(0);
.LBB0_1237:
	s_or_b64 exec, exec, s[0:1]
	v_mov_b32_e32 v0, s76
	s_waitcnt lgkmcnt(0)
	s_barrier
	ds_read_b32 v0, v0
	s_movk_i32 s0, 0xb3
	s_waitcnt lgkmcnt(0)
	v_cmp_lt_i32_e32 vcc, s0, v0
	v_readfirstlane_b32 s28, v0
	s_cbranch_vccnz .LBB0_1268
.LBB0_1238:
	s_add_i32 s0, s28, 0xffffff60
	s_mul_hi_i32 s1, s0, 0x66666667
	s_lshr_b32 s6, s1, 31
	s_ashr_i32 s77, s1, 1
	s_add_i32 s77, s77, s6
	s_mul_i32 s1, s77, 5
	s_sub_i32 s6, s0, s1
	s_mul_i32 s1, s77, 0x438000
	s_mul_hi_i32 s0, s77, 0x438000
	s_add_u32 s7, s2, s1
	s_addc_u32 s8, s3, s0
	s_mul_i32 s0, s6, 0xc0
	s_ashr_i32 s1, s0, 31
	s_lshl_b64 s[0:1], s[0:1], 1
	v_mov_b32_e32 v69, v202
	s_add_u32 s0, s7, s0
	s_addc_u32 s1, s8, s1
	v_and_b32_e32 v66, 15, v69
	v_bfe_u32 v68, v69, 4, 2
	v_ashrrev_i32_e32 v0, 1, v69
	v_and_or_b32 v136, v0, s35, v66
	v_lshlrev_b32_e32 v142, 4, v68
	v_mov_b32_e32 v143, v133
	v_lshl_add_u64 v[16:17], s[0:1], 0, v[142:143]
	v_or_b32_e32 v134, 16, v136
	v_mad_i64_i32 v[0:1], s[0:1], v136, s36, v[16:17]
	v_mad_i64_i32 v[16:17], s[0:1], v134, s36, v[16:17]
	global_load_dwordx4 v[28:31], v[0:1], off
	global_load_dwordx4 v[24:27], v[0:1], off offset:64
	global_load_dwordx4 v[12:15], v[0:1], off offset:128
	global_load_dwordx4 v[8:11], v[0:1], off offset:192
	global_load_dwordx4 v[4:7], v[0:1], off offset:256
	s_nop 0
	global_load_dwordx4 v[0:3], v[0:1], off offset:320
	s_nop 0
	global_load_dwordx4 v[44:47], v[16:17], off
	global_load_dwordx4 v[40:43], v[16:17], off offset:64
	global_load_dwordx4 v[36:39], v[16:17], off offset:128
	global_load_dwordx4 v[32:35], v[16:17], off offset:192
	global_load_dwordx4 v[20:23], v[16:17], off offset:256
	s_nop 0
	global_load_dwordx4 v[16:19], v[16:17], off offset:320
	s_mul_i32 s54, s77, 0x2d0000
	s_mul_hi_i32 s55, s77, 0x2d0000
	s_add_u32 s0, s4, s54
	s_addc_u32 s1, s5, s55
	s_lshl_b32 s56, s6, 7
	s_ashr_i32 s57, s56, 31
	s_waitcnt vmcnt(20)
	v_mul_hi_i32 v48, v69, s37
	s_lshl_b64 s[22:23], s[56:57], 1
	v_lshrrev_b32_e32 v49, 31, v48
	v_ashrrev_i32_e32 v48, 2, v48
	s_add_u32 s62, s0, s22
	v_add_u32_e32 v144, v48, v49
	s_addc_u32 s63, s1, s23
	s_mul_i32 s0, s77, 0x48000
	v_mul_lo_u32 v48, v144, 24
	s_mul_hi_i32 s1, s77, 0x48000
	s_add_u32 s0, s27, s0
	v_sub_u32_e32 v70, v69, v48
	s_addc_u32 s1, s30, s1
	v_cmp_lt_i32_e32 vcc, 15, v70
	v_ashrrev_i32_e32 v145, 31, v144
	v_lshlrev_b32_e32 v56, 3, v70
	s_and_saveexec_b64 s[6:7], vcc
	s_xor_b64 s[6:7], exec, s[6:7]
	v_lshlrev_b64 v[48:49], 7, v[144:145]
	v_lshl_add_u64 v[48:49], s[0:1], 0, v[48:49]
	v_mov_b32_e32 v57, v133
	v_lshl_add_u64 v[48:49], v[56:57], 1, v[48:49]
	v_lshl_add_u64 v[48:49], v[48:49], 0, s[14:15]
	s_or_saveexec_b64 s[6:7], s[6:7]
	v_ashrrev_i32_e32 v67, 31, v56
	s_xor_b64 exec, exec, s[6:7]
	v_mov_b64_e32 v[48:49], s[62:63]
	v_mad_i64_i32 v[48:49], s[8:9], v144, s70, v[48:49]
	v_mov_b32_e32 v57, v67
	v_lshl_add_u64 v[48:49], v[56:57], 1, v[48:49]
	s_or_b64 exec, exec, s[6:7]
	global_load_dwordx4 v[48:51], v[48:49], off
	v_add_u32_e32 v72, 0x200, v69
	v_mul_hi_i32 v52, v72, s37
	v_lshrrev_b32_e32 v53, 31, v52
	v_ashrrev_i32_e32 v52, 2, v52
	v_add_u32_e32 v146, v52, v53
	v_mul_lo_u32 v52, v146, 24
	v_sub_u32_e32 v57, v72, v52
	v_cmp_lt_i32_e64 s[6:7], 15, v57
	v_ashrrev_i32_e32 v147, 31, v146
	v_lshlrev_b32_e32 v58, 3, v57
	s_and_saveexec_b64 s[8:9], s[6:7]
	s_xor_b64 s[8:9], exec, s[8:9]
	v_lshlrev_b64 v[52:53], 7, v[146:147]
	v_lshl_add_u64 v[52:53], s[0:1], 0, v[52:53]
	v_mov_b32_e32 v59, v133
	v_lshl_add_u64 v[52:53], v[58:59], 1, v[52:53]
	v_lshl_add_u64 v[52:53], v[52:53], 0, s[14:15]
	s_or_saveexec_b64 s[8:9], s[8:9]
	v_ashrrev_i32_e32 v71, 31, v58
	s_xor_b64 exec, exec, s[8:9]
	v_mov_b64_e32 v[52:53], s[62:63]
	v_mad_i64_i32 v[52:53], s[28:29], v146, s70, v[52:53]
	v_mov_b32_e32 v59, v71
	v_lshl_add_u64 v[52:53], v[58:59], 1, v[52:53]
	s_or_b64 exec, exec, s[8:9]
	global_load_dwordx4 v[52:55], v[52:53], off
	v_add_u32_e32 v59, 0x400, v69
	v_mul_hi_i32 v60, v59, s37
	v_lshrrev_b32_e32 v61, 31, v60
	v_ashrrev_i32_e32 v60, 2, v60
	v_add_u32_e32 v148, v60, v61
	v_mul_lo_u32 v60, v148, 24
	v_sub_u32_e32 v59, v59, v60
	v_cmp_lt_i32_e64 s[8:9], 15, v59
	v_ashrrev_i32_e32 v149, 31, v148
	v_lshlrev_b32_e32 v132, 3, v59
	s_and_saveexec_b64 s[28:29], s[8:9]
	s_xor_b64 s[68:69], exec, s[28:29]
	v_lshlrev_b64 v[60:61], 7, v[148:149]
	v_lshl_add_u64 v[60:61], s[0:1], 0, v[60:61]
	v_lshl_add_u64 v[60:61], v[132:133], 1, v[60:61]
	v_lshl_add_u64 v[64:65], v[60:61], 0, s[14:15]
	v_mad_i64_i32 v[60:61], s[28:29], v148, s70, 0
	s_or_saveexec_b64 s[68:69], s[68:69]
	v_mov_b64_e32 v[62:63], v[132:133]
	s_xor_b64 exec, exec, s[68:69]
	v_mov_b64_e32 v[62:63], s[62:63]
	v_mad_i64_i32 v[64:65], s[28:29], v148, s70, v[62:63]
	v_ashrrev_i32_e32 v63, 31, v132
	v_mov_b32_e32 v62, v132
	v_mad_i64_i32 v[60:61], s[28:29], v148, s70, 0
	v_lshl_add_u64 v[64:65], v[62:63], 1, v[64:65]
	s_or_b64 exec, exec, s[68:69]
	s_mul_i32 s29, s77, 0x280
	s_mul_hi_i32 s28, s77, 0x280
	s_add_u32 s29, s29, s56
	s_addc_u32 s28, s28, s57
	s_mulk_i32 s28, 0x1200
	s_mul_hi_u32 s57, s29, 0x1200
	s_add_i32 s57, s57, s28
	s_mulk_i32 s29, 0x1200
	s_add_u32 s28, s31, s29
	global_load_dwordx4 v[74:77], v[64:65], off
	v_lshlrev_b32_e32 v64, 4, v69
	s_addc_u32 s29, s34, s57
	v_and_b32_e32 v64, 0x70, v64
	v_mov_b32_e32 v65, v133
	v_lshl_add_u64 v[78:79], s[28:29], 0, v[64:65]
	v_ashrrev_i32_e32 v65, 3, v69
	v_mad_i64_i32 v[80:81], s[28:29], v65, s71, v[78:79]
	v_ashrrev_i32_e32 v69, 3, v72
	v_mad_i64_i32 v[72:73], s[28:29], v69, s71, v[78:79]
	global_load_dwordx4 v[78:81], v[80:81], off
	s_nop 0
	global_load_dwordx4 v[82:85], v[72:73], off
	v_lshlrev_b32_e32 v186, 4, v70
	v_and_b32_e32 v70, 64, v182
	v_lshlrev_b32_e32 v138, 3, v68
	v_mul_lo_u32 v149, v144, s72
	v_lshlrev_b32_e32 v188, 4, v57
	v_lshlrev_b32_e32 v190, 4, v59
	v_xor_b32_e32 v68, 16, v182
	v_mov_b32_e32 v57, v133
	v_mov_b32_e32 v59, v133
	v_add_u32_e32 v70, 64, v70
	v_mul_lo_u32 v187, v146, s72
	v_xor_b32_e32 v72, 32, v182
	v_lshl_add_u64 v[150:151], v[132:133], 1, s[0:1]
	v_mul_u32_u24_e32 v191, 0x190, v66
	v_mad_u32_u24 v192, v66, s72, v183
	v_mul_u32_u24_e32 v139, 0x90, v66
	v_mad_u32_u24 v193, v66, s72, v184
	v_mad_u32_u24 v194, v66, s72, v185
	s_mul_hi_i32 s57, s56, 0x1200
	s_mulk_i32 s56, 0x1200
	v_add3_u32 v66, 0, v149, v186
	v_lshl_add_u64 v[152:153], v[56:57], 1, s[0:1]
	v_lshl_add_u64 v[154:155], v[58:59], 1, s[0:1]
	v_mov_b32_e32 v59, v71
	v_cmp_lt_i32_e64 s[0:1], v68, v70
	v_lshl_add_u64 v[60:61], v[62:63], 1, v[60:61]
	v_add3_u32 v73, 0, v187, v188
	v_mov_b64_e32 v[62:63], s[56:57]
	s_waitcnt vmcnt(4)
; template <int DK>
; DI void dense_attn_item(LAS unsigned char* lds, const bf16_t* Qb, int ldq, const bf16_t* Kb, int ldk, const bf16_t* Kpe, const bf16_t* Vt, int nkeys, float sl2, bf16_t* Ob) {
;     ...
;     DA_LOAD(0); DA_STORE(0);
;     __syncthreads();
	ds_write_b128 v66, v[48:51]
	s_waitcnt vmcnt(3)
	ds_write_b128 v73, v[52:55]
	v_cndmask_b32_e64 v54, v182, v68, s[0:1]
	v_cmp_lt_i32_e64 s[0:1], v72, v70
	v_lshlrev_b64 v[52:53], 1, v[58:59]
	v_mov_b32_e32 v57, v67
	v_cndmask_b32_e64 v55, v182, v72, s[0:1]
	v_mad_i64_i32 v[48:49], s[0:1], v65, s71, v[62:63]
	v_mad_i64_i32 v[50:51], s[0:1], v69, s71, v[62:63]
	v_mad_i64_i32 v[52:53], s[0:1], v146, s70, v[52:53]
	v_or_b32_e32 v48, v48, v64
	s_add_u32 s0, s12, s22
	v_lshl_add_u64 v[156:157], s[10:11], 0, v[48:49]
	s_addc_u32 s1, s13, s23
	v_mov_b64_e32 v[48:49], s[22:23]
	v_lshl_add_u64 v[160:161], s[0:1], 0, v[60:61]
	v_lshl_add_u64 v[162:163], s[0:1], 0, v[52:53]
	v_mad_i64_i32 v[48:49], s[0:1], v144, s70, v[48:49]
	v_mul_lo_u32 v189, v148, s72
	v_mul_lo_u32 v195, v65, s73
	v_mul_lo_u32 v196, v69, s73
	v_add_u32_e32 v197, 0, v64
	v_lshl_add_u64 v[48:49], v[56:57], 1, v[48:49]
	v_add3_u32 v86, 0, v189, v190
	v_add_u32_e32 v58, v197, v195
	v_add_u32_e32 v59, v197, v196
	v_or_b32_e32 v50, v50, v64
	v_lshl_add_u64 v[164:165], s[12:13], 0, v[48:49]
	v_mov_b32_e32 v48, 0
	v_ashrrev_i32_e32 v137, 31, v136
	v_ashrrev_i32_e32 v135, 31, v134
	s_mov_b32 s28, 0
	v_add_u32_e32 v147, 0, v138
	v_lshlrev_b32_e32 v145, 2, v54
	v_lshlrev_b32_e32 v143, 2, v55
	v_lshl_add_u64 v[158:159], s[10:11], 0, v[50:51]
	s_waitcnt vmcnt(2)
	ds_write_b128 v86, v[74:77]
	s_waitcnt vmcnt(1)
	ds_write_b128 v58, v[78:81] offset:51200
	s_waitcnt vmcnt(0)
	ds_write_b128 v59, v[82:85] offset:51200
	v_mov_b32_e32 v198, 0xf149f2ca
	v_mov_b32_e32 v199, 0xf149f2ca
	v_mov_b32_e32 v49, v48
	v_mov_b32_e32 v50, v48
	v_mov_b32_e32 v51, v48
	v_mov_b32_e32 v52, v48
	v_mov_b32_e32 v53, v48
	v_mov_b32_e32 v54, v48
	v_mov_b32_e32 v55, v48
	v_mov_b32_e32 v56, v48
	v_mov_b32_e32 v57, v48
	v_mov_b32_e32 v58, v48
	v_mov_b32_e32 v59, v48
	v_mov_b32_e32 v60, v48
	v_mov_b32_e32 v61, v48
	v_mov_b32_e32 v62, v48
	v_mov_b32_e32 v63, v48
	v_mov_b32_e32 v64, v48
	v_mov_b32_e32 v65, v48
	v_mov_b32_e32 v66, v48
	v_mov_b32_e32 v67, v48
	v_mov_b32_e32 v68, v48
	v_mov_b32_e32 v69, v48
	v_mov_b32_e32 v70, v48
	v_mov_b32_e32 v71, v48
	v_mov_b32_e32 v72, v48
	v_mov_b32_e32 v73, v48
	v_mov_b32_e32 v74, v48
	v_mov_b32_e32 v75, v48
	v_mov_b32_e32 v80, v48
	v_mov_b32_e32 v81, v48
	v_mov_b32_e32 v82, v48
	v_mov_b32_e32 v83, v48
	v_mov_b32_e32 v100, v48
	v_mov_b32_e32 v101, v48
	v_mov_b32_e32 v102, v48
	v_mov_b32_e32 v103, v48
	v_mov_b32_e32 v104, v48
	v_mov_b32_e32 v105, v48
	v_mov_b32_e32 v106, v48
	v_mov_b32_e32 v107, v48
	v_mov_b32_e32 v108, v48
	v_mov_b32_e32 v109, v48
	v_mov_b32_e32 v110, v48
	v_mov_b32_e32 v111, v48
	v_mov_b32_e32 v112, v48
	v_mov_b32_e32 v113, v48
	v_mov_b32_e32 v114, v48
	v_mov_b32_e32 v115, v48
	v_mov_b32_e32 v116, v48
	v_mov_b32_e32 v117, v48
	v_mov_b32_e32 v118, v48
	v_mov_b32_e32 v119, v48
	v_mov_b32_e32 v120, v48
	v_mov_b32_e32 v121, v48
	v_mov_b32_e32 v122, v48
	v_mov_b32_e32 v123, v48
	v_mov_b32_e32 v124, v48
	v_mov_b32_e32 v125, v48
	v_mov_b32_e32 v126, v48
	v_mov_b32_e32 v127, v48
	v_mov_b32_e32 v128, v48
	v_mov_b32_e32 v129, v48
	v_mov_b32_e32 v130, v48
	v_mov_b32_e32 v131, v48
	v_mov_b32_e32 v140, v48
	v_mov_b32_e32 v141, v48
	s_waitcnt lgkmcnt(0)
	s_barrier

; DI void phase_mixers(const Params& p, int l, LAS unsigned char* lds) {
;     ...
;         while (it < e3) {
;             const int i2 = it - e2 - 20, h = i2 % 6, b = i2 / 6; const size_t rowb = (size_t)b * RB;
;             const bf16_t* P = (const bf16_t*)(ws + WS_P);
;             dense_attn_item<128>(lds, P + rowb * INP + C_NAQ + h * 128, INP, P + rowb * INP + C_NAK + h * 128, INP, nullptr,
;                                  (const bf16_t*)(ws + WS_VTNA) + ((size_t)b * 768 + h * 128) * RB, CL, 0.08838834764831845f * 1.4426950408889634f, (bf16_t*)(ws + WS_YMIX) + rowb * DM + h * 128);
;             it = next_item(ctr, slot);
.LBB0_1268:
	s_cmpk_gt_u32 s28, 0xcb
	s_cbranch_scc1 .LBB0_1176
	s_add_u32 s2, s50, 0x113a0000
	s_addc_u32 s3, s51, 0
	s_add_u32 s4, s50, 0x17fa0000
	s_addc_u32 s5, s51, 0
	v_mbcnt_hi_u32_b32 v151, -1, v203
	s_add_u32 s14, s50, 0x1d9a0000
	v_and_b32_e32 v0, 64, v151
	s_addc_u32 s15, s51, 0
	s_movk_i32 s16, 0x1200
	s_movk_i32 s17, 0xffe0
	v_mov_b32_e32 v113, 0
	s_movk_i32 s18, 0x3000
	s_movk_i32 s19, 0x110
	s_movk_i32 s20, 0x90
	v_mov_b32_e32 v143, 0x1100
	v_mov_b32_e32 v148, 0x2200
	v_mov_b32_e32 v149, 0x3300
	v_mov_b32_e32 v150, 0x1200
	s_mov_b32 s21, 0x3e0293ee
	s_mov_b64 s[0:1], 0x80
	s_mov_b64 s[6:7], 0xc0000
	s_add_i32 s22, 0, 0x22040
	s_movk_i32 s23, 0xcc
	v_xor_b32_e32 v152, 16, v151
	v_add_u32_e32 v153, 64, v0
	v_xor_b32_e32 v154, 32, v151
	s_branch .LBB0_1272

; #define LAS __attribute__((address_space(3)))
; DI int otid() { int t = threadIdx.x; asm volatile("" : "+v"(t)); return t; }
; template <int DK>
; DI void dense_attn_item(LAS unsigned char* lds, const bf16_t* Qb, int ldq, const bf16_t* Kb, int ldk, const bf16_t* Kpe, const bf16_t* Vt, int nkeys, float sl2, bf16_t* Ob) {
;     const int tid = otid(), lane = tid & 63, wid = tid >> 6, r16 = lane & 15, q4 = lane >> 4;
;     constexpr int KS = DK / 32, KCH = DK / 8, KROW = DK * 2 + 16, KTILE = 64 * KROW, VROW = 144, VTILE = 128 * VROW, NKL = (64 * KCH) / 512;
;     bf16x8 qf[2][KS];
; #pragma unroll
;     for (int qg = 0; qg < 2; ++qg)
; #pragma unroll
;         for (int ks = 0; ks < KS; ++ks) qf[qg][ks] = *(const bf16x8*)(Qb + (size_t)(wid * 32 + qg * 16 + r16) * ldq + ks * 32 + q4 * 8);
;     f32x4 oacc[2][8];
; #pragma unroll
;     for (int qg = 0; qg < 2; ++qg)
; #pragma unroll
;         for (int d = 0; d < 8; ++d) oacc[qg][d] = (f32x4){0.f, 0.f, 0.f, 0.f};
;     float mrun[2] = {-1e30f, -1e30f}, lsum[2] = {0.f, 0.f};
;     u32x4 kst[NKL], vst[2];
;     const int ntiles = nkeys >> 6;
;     ...
;     DA_LOAD(0); DA_STORE(0);
; DI void phase_mixers(const Params& p, int l, LAS unsigned char* lds) {
;     ...
;         while (it < e3) {
;             const int i2 = it - e2 - 20, h = i2 % 6, b = i2 / 6; const size_t rowb = (size_t)b * RB;
;             const bf16_t* P = (const bf16_t*)(ws + WS_P);
;             dense_attn_item<128>(lds, P + rowb * INP + C_NAQ + h * 128, INP, P + rowb * INP + C_NAK + h * 128, INP, nullptr,
;                                  (const bf16_t*)(ws + WS_VTNA) + ((size_t)b * 768 + h * 128) * RB, CL, 0.08838834764831845f * 1.4426950408889634f, (bf16_t*)(ws + WS_YMIX) + rowb * DM + h * 128);
.LBB0_1272:
	v_mov_b32_e32 v6, v202
	s_add_i32 s8, s28, 0xffffff4c
	s_mul_hi_i32 s9, s8, 0x2aaaaaab
	v_ashrrev_i32_e32 v0, 31, v6
	v_lshrrev_b32_e32 v0, 28, v0
	s_lshr_b32 s10, s9, 31
	v_add_u32_e32 v4, v6, v0
	s_add_i32 s27, s9, s10
	v_ashrrev_i32_e32 v54, 4, v4
	v_and_b32_e32 v4, -16, v4
	s_mul_i32 s9, s27, 6
	v_sub_u32_e32 v7, v6, v4
	s_sub_i32 s8, s8, s9
	s_mul_i32 s35, s27, 0x1b00000
	v_lshlrev_b32_e32 v4, 3, v7
	s_mul_hi_i32 s34, s27, 0x1b00000
	s_add_u32 s12, s2, s35
	v_ashrrev_i32_e32 v5, 31, v4
	v_add_u32_e32 v8, 0x200, v6
	s_addc_u32 s13, s3, s34
	s_lshl_b32 s10, s8, 7
	s_waitcnt vmcnt(8)
	v_lshlrev_b64 v[48:49], 1, v[4:5]
	v_ashrrev_i32_e32 v4, 31, v8
	s_ashr_i32 s11, s10, 31
	v_lshrrev_b32_e32 v4, 28, v4
	s_lshl_b64 s[8:9], s[10:11], 1
	v_add_u32_e32 v4, v8, v4
	s_add_u32 s12, s12, s8
	v_ashrrev_i32_e32 v55, 4, v4
	v_and_b32_e32 v4, -16, v4
	s_addc_u32 s13, s13, s9
	s_mul_i32 s29, s27, 0x300
	v_sub_u32_e32 v9, v8, v4
	s_mul_hi_i32 s28, s27, 0x300
	s_add_u32 s29, s29, s10
	v_lshlrev_b32_e32 v4, 3, v9
	s_addc_u32 s11, s28, s11
	v_mov_b64_e32 v[0:1], s[12:13]
	v_ashrrev_i32_e32 v5, 31, v4
	s_mulk_i32 s11, 0x1200
	s_mul_hi_u32 s28, s29, 0x1200
	v_mad_i64_i32 v[2:3], s[30:31], v54, s18, v[0:1]
	v_mad_i64_i32 v[0:1], s[30:31], v55, s18, v[0:1]
	v_lshlrev_b64 v[50:51], 1, v[4:5]
	s_add_i32 s11, s28, s11
	s_mulk_i32 s29, 0x1200
	v_lshl_add_u64 v[2:3], v[2:3], 0, v[48:49]
	v_lshl_add_u64 v[0:1], v[0:1], 0, v[50:51]
	s_add_u32 s28, s4, s29
	global_load_dwordx4 v[32:35], v[2:3], off offset:1536
	global_load_dwordx4 v[36:39], v[0:1], off offset:1536
	v_lshlrev_b32_e32 v0, 4, v6
	s_addc_u32 s29, s5, s11
	v_and_b32_e32 v52, 0x70, v0
	v_mov_b32_e32 v53, v113
	v_lshl_add_u64 v[0:1], s[28:29], 0, v[52:53]
	v_ashrrev_i32_e32 v53, 3, v6
	v_ashrrev_i32_e32 v56, 3, v8
	v_mad_i64_i32 v[2:3], s[28:29], v53, s16, v[0:1]
	v_mad_i64_i32 v[0:1], s[28:29], v56, s16, v[0:1]
	global_load_dwordx4 v[40:43], v[2:3], off
	global_load_dwordx4 v[44:47], v[0:1], off
	v_and_b32_e32 v57, 15, v6
	v_bfe_u32 v157, v6, 4, 2
	v_ashrrev_i32_e32 v0, 1, v6
	v_and_or_b32 v116, v0, s17, v57
	v_lshlrev_b32_e32 v112, 4, v157
	v_or_b32_e32 v114, 16, v116
	v_lshl_add_u64 v[0:1], s[12:13], 0, v[112:113]
	v_lshlrev_b32_e32 v166, 4, v9
	v_mad_i64_i32 v[2:3], s[12:13], v116, s18, v[0:1]
	v_mad_i64_i32 v[8:9], s[12:13], v114, s18, v[0:1]
	v_lshlrev_b32_e32 v164, 4, v7
	global_load_dwordx4 v[20:23], v[2:3], off
	global_load_dwordx4 v[16:19], v[2:3], off offset:64
	global_load_dwordx4 v[4:7], v[2:3], off offset:128
	s_nop 0
	global_load_dwordx4 v[0:3], v[2:3], off offset:192
	s_nop 0
	global_load_dwordx4 v[28:31], v[8:9], off
	global_load_dwordx4 v[24:27], v[8:9], off offset:64
	global_load_dwordx4 v[12:15], v[8:9], off offset:128
	s_nop 0
	global_load_dwordx4 v[8:11], v[8:9], off offset:192
	v_mul_lo_u32 v163, v54, s19
	v_mul_lo_u32 v160, v53, s20
	v_add_u32_e32 v161, 0, v52
	v_mul_lo_u32 v162, v56, s20
	v_mul_lo_u32 v165, v55, s19
	v_add3_u32 v59, 0, v163, v164
	v_add_u32_e32 v58, v161, v160
	v_add3_u32 v60, 0, v165, v166
	v_cmp_lt_i32_e32 vcc, v152, v153
	s_mul_i32 s12, s27, 0x360000
	s_mul_hi_i32 s11, s27, 0x360000
	s_add_u32 s12, s12, 0x17fa0080
	s_addc_u32 s13, s11, 0
	v_ashrrev_i32_e32 v117, 31, v116
	v_ashrrev_i32_e32 v115, 31, v114
	v_lshl_add_u32 v158, v157, 3, 0
	v_mul_u32_u24_e32 v167, 0x110, v57
	v_mad_u32_u24 v168, v57, s19, v143
	v_mul_u32_u24_e32 v159, 0x90, v57
	s_waitcnt vmcnt(11)
	ds_write_b128 v59, v[32:35]
	s_waitcnt vmcnt(10)
	ds_write_b128 v60, v[36:39]
	s_waitcnt vmcnt(9)
	ds_write_b128 v58, v[40:43] offset:34816
	v_add_u32_e32 v32, v161, v162
	v_mad_u32_u24 v169, v57, s19, v148
	s_waitcnt vmcnt(8)
	ds_write_b128 v32, v[44:47] offset:34816
	v_cndmask_b32_e32 v32, v151, v152, vcc
	v_cmp_lt_i32_e32 vcc, v154, v153
	v_lshlrev_b32_e32 v156, 2, v32
	v_mad_u32_u24 v170, v57, s19, v149
	v_cndmask_b32_e32 v32, v151, v154, vcc
	v_lshlrev_b32_e32 v155, 2, v32
	v_mov_b64_e32 v[32:33], s[12:13]
	v_mad_i64_i32 v[34:35], s[12:13], v53, s16, v[32:33]
	v_mad_i64_i32 v[32:33], s[12:13], v56, s16, v[32:33]
	v_mad_i64_i32 v[120:121], s[12:13], s10, v150, v[34:35]
	v_mad_i64_i32 v[122:123], s[10:11], s10, v150, v[32:33]
	s_add_u32 s10, s35, 0x11460600
	s_addc_u32 s11, s34, 0
	v_mov_b64_e32 v[32:33], s[10:11]
	v_mad_i64_i32 v[32:33], s[12:13], v55, s18, v[32:33]
	s_add_u32 s10, s8, s10
	v_lshl_add_u64 v[32:33], v[32:33], 0, v[50:51]
	s_addc_u32 s11, s9, s11
	v_lshl_add_u64 v[124:125], v[32:33], 0, s[8:9]
	v_mov_b64_e32 v[32:33], s[10:11]
	v_mad_i64_i32 v[32:33], s[10:11], v54, s18, v[32:33]
	v_or_b32_e32 v120, v120, v52
	v_or_b32_e32 v122, v122, v52
	v_lshl_add_u64 v[126:127], v[32:33], 0, v[48:49]
	v_mov_b32_e32 v134, 0xf149f2ca
	v_mov_b32_e32 v128, 0xf149f2ca
	s_mov_b32 s10, 0
	v_mov_b32_e32 v32, 0
	v_mov_b32_e32 v33, v113
	v_mov_b32_e32 v34, v113
	v_mov_b32_e32 v35, v113
	v_mov_b32_e32 v36, 0
	v_mov_b32_e32 v37, v113
	v_mov_b32_e32 v38, v113
	v_mov_b32_e32 v39, v113
	v_mov_b32_e32 v56, 0
	v_mov_b32_e32 v57, v113
	v_mov_b32_e32 v58, v113
	v_mov_b32_e32 v59, v113
	v_mov_b32_e32 v60, 0
	v_mov_b32_e32 v61, v113
	v_mov_b32_e32 v62, v113
	v_mov_b32_e32 v63, v113
	v_mov_b32_e32 v64, 0
	v_mov_b32_e32 v65, v113
	v_mov_b32_e32 v66, v113
	v_mov_b32_e32 v67, v113
	v_mov_b32_e32 v68, 0
	v_mov_b32_e32 v69, v113
	v_mov_b32_e32 v70, v113
	v_mov_b32_e32 v71, v113
	v_mov_b32_e32 v72, 0
	v_mov_b32_e32 v73, v113
	v_mov_b32_e32 v74, v113
	v_mov_b32_e32 v75, v113
	v_mov_b32_e32 v76, 0
	v_mov_b32_e32 v77, v113
	v_mov_b32_e32 v78, v113
	v_mov_b32_e32 v79, v113
	v_mov_b32_e32 v80, 0
	v_mov_b32_e32 v81, v113
	v_mov_b32_e32 v82, v113
	v_mov_b32_e32 v83, v113
	v_mov_b32_e32 v84, 0
	v_mov_b32_e32 v85, v113
	v_mov_b32_e32 v86, v113
	v_mov_b32_e32 v87, v113
	v_mov_b32_e32 v88, 0
	v_mov_b32_e32 v89, v113
	v_mov_b32_e32 v90, v113
	v_mov_b32_e32 v91, v113
	v_mov_b32_e32 v92, 0
	v_mov_b32_e32 v93, v113
	v_mov_b32_e32 v94, v113
	v_mov_b32_e32 v95, v113
	v_mov_b32_e32 v96, 0
	v_mov_b32_e32 v97, v113
	v_mov_b32_e32 v98, v113
	v_mov_b32_e32 v99, v113
	v_mov_b32_e32 v100, 0
	v_mov_b32_e32 v101, v113
	v_mov_b32_e32 v102, v113
	v_mov_b32_e32 v103, v113
	v_mov_b32_e32 v104, 0
	v_mov_b32_e32 v105, v113
	v_mov_b32_e32 v106, v113
	v_mov_b32_e32 v107, v113
	v_mov_b32_e32 v108, 0
	v_mov_b32_e32 v109, v113
	v_mov_b32_e32 v110, v113
	v_mov_b32_e32 v111, v113
	v_mov_b32_e32 v118, 0
	v_mov_b32_e32 v119, v113
	s_waitcnt lgkmcnt(0)
	s_barrier
